# gate-column epilogue (in-proj): packed f32 adds/multiplies/fmas for the log-sigmoid math, same operation order
# baseline (speedup 1.0000x reference)
;   __device__ __forceinline__ void operator()(f32x4 (&acc)[2][2][4][2], int brow, int bcol, int wr, int wc, int fr, int fq) const {
;     ...
;       __syncthreads();
;       typedef short s16x4 __attribute__((ext_vector_type(4)));
;       const u16* wgt = (const u16*)(p.ws + OFF_WGT);
; #pragma unroll
;       for (int dir = 0; dir < 2; ++dir) {
;         s16x4 bfr[2][2];
; #pragma unroll
;         for (int bj = 0; bj < 2; ++bj)
; #pragma unroll
;           for (int n = 0; n < 2; ++n)
;             bfr[bj][n] = *(const s16x4*)(wgt + ((size_t)(dir * 256 + bj * 128 + wc * 32 + n * 16 + fr)) * 16 + fq * 4);
;         u16* dst = (u16*)(p.ws + (dir == 0 ? OFF_LAF : OFF_LAB));
;         const float* bias = dir == 0 ? p.bgf : p.bgb;
; #pragma unroll
;         for (int ai = 0; ai < 2; ++ai)
; #pragma unroll
;           for (int m = 0; m < 4; ++m) {
;             int rl = ai * 128 + wr * 64 + m * 16;
;             s16x4 af = *(const s16x4*)(glr + (rl + fr) * 32 + dir * 16 + fq * 4);
;             int row0 = brow + rl + fq * 4;
; #pragma unroll
;             for (int bj = 0; bj < 2; ++bj)
; #pragma unroll
;               for (int n = 0; n < 2; ++n) {
;                 f32x4 z4 = {0.f, 0.f, 0.f, 0.f};
;                 z4 = __builtin_amdgcn_mfma_f32_16x16x16bf16_1k(af, bfr[bj][n], z4, 0, 0, 0);
;                 int c = bj * 128 + wc * 32 + n * 16 + fr;
;                 float bb = bias[c];
;                 float ls[4];
; #pragma unroll
;                 for (int j = 0; j < 4; ++j) {
;                   float z = z4[j] + bb;
;                   ls[j] = (fminf(z, 0.f) - __logf(1.f + __expf(-fabsf(z)))) * (1.f / 16.f);
;                 }
;                 store_rm4(dst, 256, row0, c, ls[0], ls[1], ls[2], ls[3], fr & 1);
.LBB0_155:
	s_or_b64 exec, exec, s[0:1]
	s_waitcnt vmcnt(0) lgkmcnt(0)
	s_barrier
	s_mov_b32 s94, 0x3377d1cf
	s_mov_b32 s96, 0x3d800000
	v_lshlrev_b32_e32 v225, 1, v232
	v_add_u32_e32 v160, v166, v230
	v_lshl_add_u32 v160, v160, 6, v225
	v_add_u32_e32 v160, 16, v160
	v_lshl_add_u32 v228, v233, 5, v230
	v_lshl_add_u32 v161, v228, 5, v225
	v_add_u32_e32 v224, 0x1000, v161
	v_lshlrev_b32_e32 v162, 2, v228
	v_and_b32_e32 v225, 1, v229
	v_cmp_eq_u32_e32 vcc, 1, v225
	v_add3_u32 v225, v166, v232, v225
	v_and_b32_e32 v163, 14, v230
	v_lshl_add_u32 v163, v233, 5, v163
	v_lshlrev_b32_e32 v163, 1, v163
	v_lshl_add_u32 v163, v225, 9, v163
	v_mov_b32_e32 v164, 0x05040100
	v_mov_b32_e32 v228, 0x03020706
	s_lshl_b32 s0, s60, 9
	v_cndmask_b32_e32 v164, v164, v228, vcc
	s_add_u32 s4, s40, 0x0
	s_addc_u32 s5, s41, 0
	s_add_u32 s8, s12, s0
	s_addc_u32 s9, s13, 0
	global_load_dwordx2 v[168:169], v161, s[4:5]
	global_load_dwordx2 v[170:171], v161, s[4:5] offset:512
	global_load_dwordx2 v[172:173], v224, s[4:5]
	global_load_dwordx2 v[174:175], v224, s[4:5] offset:512
	global_load_dword v176, v162, s[62:63]
	global_load_dword v177, v162, s[62:63] offset:64
	global_load_dword v178, v162, s[62:63] offset:512
	global_load_dword v179, v162, s[62:63] offset:576
	ds_read_b64 v[180:181], v160 offset:49152
	v_mov_b32_e32 v167, v163
	s_waitcnt vmcnt(0) lgkmcnt(0)
	v_mfma_f32_16x16x16_bf16 v[184:187], v[180:181], v[168:169], 0
	v_mfma_f32_16x16x16_bf16 v[188:191], v[180:181], v[170:171], 0
	v_mfma_f32_16x16x16_bf16 v[192:195], v[180:181], v[172:173], 0
	v_mfma_f32_16x16x16_bf16 v[196:199], v[180:181], v[174:175], 0
	s_nop 7
	s_nop 1
	v_pk_add_f32 v[184:185], v[184:185], v[176:177] op_sel_hi:[1,0]
	v_pk_add_f32 v[186:187], v[186:187], v[176:177] op_sel_hi:[1,0]
	v_pk_add_f32 v[188:189], v[188:189], v[176:177] op_sel:[0,1] op_sel_hi:[1,1]
	v_pk_add_f32 v[190:191], v[190:191], v[176:177] op_sel:[0,1] op_sel_hi:[1,1]
	v_min_f32_e32 v200, 0, v184
	v_min_f32_e32 v201, 0, v185
	v_min_f32_e32 v202, 0, v186
	v_min_f32_e32 v203, 0, v187
	v_min_f32_e32 v204, 0, v188
	v_min_f32_e32 v205, 0, v189
	v_min_f32_e32 v206, 0, v190
	v_min_f32_e32 v207, 0, v191
	v_mul_f32_e64 v208, |v184|, s93
	v_mul_f32_e64 v209, |v185|, s93
	v_mul_f32_e64 v210, |v186|, s93
	v_mul_f32_e64 v211, |v187|, s93
	v_mul_f32_e64 v212, |v188|, s93
	v_mul_f32_e64 v213, |v189|, s93
	v_mul_f32_e64 v214, |v190|, s93
	v_mul_f32_e64 v215, |v191|, s93
	v_exp_f32_e32 v208, v208
	v_exp_f32_e32 v209, v209
	v_exp_f32_e32 v210, v210
	v_exp_f32_e32 v211, v211
	v_exp_f32_e32 v212, v212
	v_exp_f32_e32 v213, v213
	v_exp_f32_e32 v214, v214
	v_exp_f32_e32 v215, v215
	v_pk_add_f32 v[208:209], v[208:209], 1.0 op_sel_hi:[1,0]
	v_pk_add_f32 v[210:211], v[210:211], 1.0 op_sel_hi:[1,0]
	v_pk_add_f32 v[212:213], v[212:213], 1.0 op_sel_hi:[1,0]
	v_pk_add_f32 v[214:215], v[214:215], 1.0 op_sel_hi:[1,0]
	v_log_f32_e32 v208, v208
	v_log_f32_e32 v209, v209
	v_log_f32_e32 v210, v210
	v_log_f32_e32 v211, v211
	v_log_f32_e32 v212, v212
	v_log_f32_e32 v213, v213
	v_log_f32_e32 v214, v214
	v_log_f32_e32 v215, v215
	v_pk_mul_f32 v[216:217], v[208:209], s[94:95] op_sel:[0,1] op_sel_hi:[1,1]
	v_pk_mul_f32 v[218:219], v[210:211], s[94:95] op_sel:[0,1] op_sel_hi:[1,1]
	v_pk_mul_f32 v[220:221], v[212:213], s[94:95] op_sel:[0,1] op_sel_hi:[1,1]
	v_pk_mul_f32 v[222:223], v[214:215], s[94:95] op_sel:[0,1] op_sel_hi:[1,1]
	v_pk_fma_f32 v[216:217], v[208:209], s[94:95], v[216:217] op_sel:[0,1,0] op_sel_hi:[1,1,1] neg_lo:[0,0,1] neg_hi:[0,0,1]
	v_pk_fma_f32 v[218:219], v[210:211], s[94:95], v[218:219] op_sel:[0,1,0] op_sel_hi:[1,1,1] neg_lo:[0,0,1] neg_hi:[0,0,1]
	v_pk_fma_f32 v[220:221], v[212:213], s[94:95], v[220:221] op_sel:[0,1,0] op_sel_hi:[1,1,1] neg_lo:[0,0,1] neg_hi:[0,0,1]
	v_pk_fma_f32 v[222:223], v[214:215], s[94:95], v[222:223] op_sel:[0,1,0] op_sel_hi:[1,1,1] neg_lo:[0,0,1] neg_hi:[0,0,1]
	v_pk_fma_f32 v[216:217], v[208:209], s[94:95], v[216:217] op_sel_hi:[1,0,1]
	v_pk_fma_f32 v[218:219], v[210:211], s[94:95], v[218:219] op_sel_hi:[1,0,1]
	v_pk_fma_f32 v[220:221], v[212:213], s[94:95], v[220:221] op_sel_hi:[1,0,1]
	v_pk_fma_f32 v[222:223], v[214:215], s[94:95], v[222:223] op_sel_hi:[1,0,1]
	v_pk_fma_f32 v[216:217], v[208:209], s[94:95], v[216:217] op_sel:[0,1,0] op_sel_hi:[1,1,1]
	v_pk_fma_f32 v[218:219], v[210:211], s[94:95], v[218:219] op_sel:[0,1,0] op_sel_hi:[1,1,1]
	v_pk_fma_f32 v[220:221], v[212:213], s[94:95], v[220:221] op_sel:[0,1,0] op_sel_hi:[1,1,1]
	v_pk_fma_f32 v[222:223], v[214:215], s[94:95], v[222:223] op_sel:[0,1,0] op_sel_hi:[1,1,1]
	v_pk_add_f32 v[200:201], v[200:201], v[216:217] neg_lo:[0,1] neg_hi:[0,1]
	v_pk_add_f32 v[202:203], v[202:203], v[218:219] neg_lo:[0,1] neg_hi:[0,1]
	v_pk_add_f32 v[204:205], v[204:205], v[220:221] neg_lo:[0,1] neg_hi:[0,1]
	v_pk_add_f32 v[206:207], v[206:207], v[222:223] neg_lo:[0,1] neg_hi:[0,1]
	v_pk_mul_f32 v[184:185], v[200:201], s[96:97] op_sel_hi:[1,0]
	v_pk_mul_f32 v[186:187], v[202:203], s[96:97] op_sel_hi:[1,0]
	v_pk_mul_f32 v[188:189], v[204:205], s[96:97] op_sel_hi:[1,0]
	v_pk_mul_f32 v[190:191], v[206:207], s[96:97] op_sel_hi:[1,0]
	v_pk_add_f32 v[192:193], v[192:193], v[178:179] op_sel_hi:[1,0]
	v_pk_add_f32 v[194:195], v[194:195], v[178:179] op_sel_hi:[1,0]
	v_pk_add_f32 v[196:197], v[196:197], v[178:179] op_sel:[0,1] op_sel_hi:[1,1]
	v_pk_add_f32 v[198:199], v[198:199], v[178:179] op_sel:[0,1] op_sel_hi:[1,1]
	v_min_f32_e32 v200, 0, v192
	v_min_f32_e32 v201, 0, v193
	v_min_f32_e32 v202, 0, v194
	v_min_f32_e32 v203, 0, v195
	v_min_f32_e32 v204, 0, v196
	v_min_f32_e32 v205, 0, v197
	v_min_f32_e32 v206, 0, v198
	v_min_f32_e32 v207, 0, v199
	v_mul_f32_e64 v208, |v192|, s93
; __device__ __forceinline__ void store_rm4(u16* dst, size_t ld, int row0, int c, float v0, float v1, float v2, float v3, bool odd) {
;   {
;     float s = odd ? v0 : v1, r = dpp_swap1(s);
;     float lo = odd ? r : v0, hi = odd ? v1 : r;
;     *(unsigned*)(dst + (size_t)(row0 + (odd ? 1 : 0)) * ld + (c - (odd ? 1 : 0))) = pack2(lo, hi);
;   }
;   {
;     float s = odd ? v2 : v3, r = dpp_swap1(s);
;     float lo = odd ? r : v2, hi = odd ? v3 : r;
;     *(unsigned*)(dst + (size_t)(row0 + 2 + (odd ? 1 : 0)) * ld + (c - (odd ? 1 : 0))) = pack2(lo, hi);
;   }
;   __device__ __forceinline__ void operator()(f32x4 (&acc)[2][2][4][2], int brow, int bcol, int wr, int wc, int fr, int fq) const {
;     ...
;                 f32x4 z4 = {0.f, 0.f, 0.f, 0.f};
;                 z4 = __builtin_amdgcn_mfma_f32_16x16x16bf16_1k(af, bfr[bj][n], z4, 0, 0, 0);
;                 int c = bj * 128 + wc * 32 + n * 16 + fr;
;                 float bb = bias[c];
;                 float ls[4];
; #pragma unroll
;                 for (int j = 0; j < 4; ++j) {
;                   float z = z4[j] + bb;
;                   ls[j] = (fminf(z, 0.f) - __logf(1.f + __expf(-fabsf(z)))) * (1.f / 16.f);
;                 }
;                 store_rm4(dst, 256, row0, c, ls[0], ls[1], ls[2], ls[3], fr & 1);
	v_mul_f32_e64 v209, |v193|, s93
	v_mul_f32_e64 v210, |v194|, s93
	v_mul_f32_e64 v211, |v195|, s93
	v_mul_f32_e64 v212, |v196|, s93
	v_mul_f32_e64 v213, |v197|, s93
	v_mul_f32_e64 v214, |v198|, s93
	v_mul_f32_e64 v215, |v199|, s93
	v_exp_f32_e32 v208, v208
	v_exp_f32_e32 v209, v209
	v_exp_f32_e32 v210, v210
	v_exp_f32_e32 v211, v211
	v_exp_f32_e32 v212, v212
	v_exp_f32_e32 v213, v213
	v_exp_f32_e32 v214, v214
	v_exp_f32_e32 v215, v215
	v_pk_add_f32 v[208:209], v[208:209], 1.0 op_sel_hi:[1,0]
	v_pk_add_f32 v[210:211], v[210:211], 1.0 op_sel_hi:[1,0]
	v_pk_add_f32 v[212:213], v[212:213], 1.0 op_sel_hi:[1,0]
	v_pk_add_f32 v[214:215], v[214:215], 1.0 op_sel_hi:[1,0]
	v_log_f32_e32 v208, v208
	v_log_f32_e32 v209, v209
	v_log_f32_e32 v210, v210
	v_log_f32_e32 v211, v211
	v_log_f32_e32 v212, v212
	v_log_f32_e32 v213, v213
	v_log_f32_e32 v214, v214
	v_log_f32_e32 v215, v215
	v_pk_mul_f32 v[216:217], v[208:209], s[94:95] op_sel:[0,1] op_sel_hi:[1,1]
	v_pk_mul_f32 v[218:219], v[210:211], s[94:95] op_sel:[0,1] op_sel_hi:[1,1]
	v_pk_mul_f32 v[220:221], v[212:213], s[94:95] op_sel:[0,1] op_sel_hi:[1,1]
	v_pk_mul_f32 v[222:223], v[214:215], s[94:95] op_sel:[0,1] op_sel_hi:[1,1]
	v_pk_fma_f32 v[216:217], v[208:209], s[94:95], v[216:217] op_sel:[0,1,0] op_sel_hi:[1,1,1] neg_lo:[0,0,1] neg_hi:[0,0,1]
	v_pk_fma_f32 v[218:219], v[210:211], s[94:95], v[218:219] op_sel:[0,1,0] op_sel_hi:[1,1,1] neg_lo:[0,0,1] neg_hi:[0,0,1]
	v_pk_fma_f32 v[220:221], v[212:213], s[94:95], v[220:221] op_sel:[0,1,0] op_sel_hi:[1,1,1] neg_lo:[0,0,1] neg_hi:[0,0,1]
	v_pk_fma_f32 v[222:223], v[214:215], s[94:95], v[222:223] op_sel:[0,1,0] op_sel_hi:[1,1,1] neg_lo:[0,0,1] neg_hi:[0,0,1]
	v_pk_fma_f32 v[216:217], v[208:209], s[94:95], v[216:217] op_sel_hi:[1,0,1]
	v_pk_fma_f32 v[218:219], v[210:211], s[94:95], v[218:219] op_sel_hi:[1,0,1]
	v_pk_fma_f32 v[220:221], v[212:213], s[94:95], v[220:221] op_sel_hi:[1,0,1]
	v_pk_fma_f32 v[222:223], v[214:215], s[94:95], v[222:223] op_sel_hi:[1,0,1]
	v_pk_fma_f32 v[216:217], v[208:209], s[94:95], v[216:217] op_sel:[0,1,0] op_sel_hi:[1,1,1]
	v_pk_fma_f32 v[218:219], v[210:211], s[94:95], v[218:219] op_sel:[0,1,0] op_sel_hi:[1,1,1]
	v_pk_fma_f32 v[220:221], v[212:213], s[94:95], v[220:221] op_sel:[0,1,0] op_sel_hi:[1,1,1]
	v_pk_fma_f32 v[222:223], v[214:215], s[94:95], v[222:223] op_sel:[0,1,0] op_sel_hi:[1,1,1]
	v_pk_add_f32 v[200:201], v[200:201], v[216:217] neg_lo:[0,1] neg_hi:[0,1]
	v_pk_add_f32 v[202:203], v[202:203], v[218:219] neg_lo:[0,1] neg_hi:[0,1]
	v_pk_add_f32 v[204:205], v[204:205], v[220:221] neg_lo:[0,1] neg_hi:[0,1]
	v_pk_add_f32 v[206:207], v[206:207], v[222:223] neg_lo:[0,1] neg_hi:[0,1]
	v_pk_mul_f32 v[192:193], v[200:201], s[96:97] op_sel_hi:[1,0]
	v_pk_mul_f32 v[194:195], v[202:203], s[96:97] op_sel_hi:[1,0]
	v_pk_mul_f32 v[196:197], v[204:205], s[96:97] op_sel_hi:[1,0]
	v_pk_mul_f32 v[198:199], v[206:207], s[96:97] op_sel_hi:[1,0]
	v_cvt_pk_bf16_f32 v208, v184, v185
	v_cvt_pk_bf16_f32 v209, v186, v187
	v_cvt_pk_bf16_f32 v210, v188, v189
	v_cvt_pk_bf16_f32 v211, v190, v191
	v_cvt_pk_bf16_f32 v212, v192, v193
	v_cvt_pk_bf16_f32 v213, v194, v195
	v_cvt_pk_bf16_f32 v214, v196, v197
	v_cvt_pk_bf16_f32 v215, v198, v199
	v_mov_b32_dpp v216, v208 quad_perm:[1,0,3,2] row_mask:0xf bank_mask:0xf bound_ctrl:1
	v_mov_b32_dpp v217, v209 quad_perm:[1,0,3,2] row_mask:0xf bank_mask:0xf bound_ctrl:1
	v_mov_b32_dpp v218, v210 quad_perm:[1,0,3,2] row_mask:0xf bank_mask:0xf bound_ctrl:1
	v_mov_b32_dpp v219, v211 quad_perm:[1,0,3,2] row_mask:0xf bank_mask:0xf bound_ctrl:1
	v_mov_b32_dpp v220, v212 quad_perm:[1,0,3,2] row_mask:0xf bank_mask:0xf bound_ctrl:1
	v_mov_b32_dpp v221, v213 quad_perm:[1,0,3,2] row_mask:0xf bank_mask:0xf bound_ctrl:1
	v_mov_b32_dpp v222, v214 quad_perm:[1,0,3,2] row_mask:0xf bank_mask:0xf bound_ctrl:1
	v_mov_b32_dpp v223, v215 quad_perm:[1,0,3,2] row_mask:0xf bank_mask:0xf bound_ctrl:1
	v_perm_b32 v208, v216, v208, v164
	v_perm_b32 v209, v217, v209, v164
	v_perm_b32 v210, v218, v210, v164
	v_perm_b32 v211, v219, v211, v164
	v_perm_b32 v212, v220, v212, v164
	v_perm_b32 v213, v221, v213, v164
	v_perm_b32 v214, v222, v214, v164
	v_perm_b32 v215, v223, v215, v164
	global_store_dword v167, v208, s[8:9]
	global_store_dword v167, v209, s[8:9] offset:1024
	global_store_dword v167, v210, s[8:9] offset:32
	global_store_dword v167, v211, s[8:9] offset:1056
	global_store_dword v167, v212, s[8:9] offset:256
	global_store_dword v167, v213, s[8:9] offset:1280
	global_store_dword v167, v214, s[8:9] offset:288
	global_store_dword v167, v215, s[8:9] offset:1312
	ds_read_b64 v[180:181], v160 offset:50176
	v_add_u32_e32 v167, 0x2000, v163
	s_waitcnt lgkmcnt(0)
;   __device__ __forceinline__ void operator()(f32x4 (&acc)[2][2][4][2], int brow, int bcol, int wr, int wc, int fr, int fq) const {
;     ...
;                 f32x4 z4 = {0.f, 0.f, 0.f, 0.f};
;                 z4 = __builtin_amdgcn_mfma_f32_16x16x16bf16_1k(af, bfr[bj][n], z4, 0, 0, 0);
;                 int c = bj * 128 + wc * 32 + n * 16 + fr;
;                 float bb = bias[c];
;                 float ls[4];
; #pragma unroll
;                 for (int j = 0; j < 4; ++j) {
;                   float z = z4[j] + bb;
;                   ls[j] = (fminf(z, 0.f) - __logf(1.f + __expf(-fabsf(z)))) * (1.f / 16.f);
;                 }
	v_mfma_f32_16x16x16_bf16 v[184:187], v[180:181], v[168:169], 0
	v_mfma_f32_16x16x16_bf16 v[188:191], v[180:181], v[170:171], 0
	v_mfma_f32_16x16x16_bf16 v[192:195], v[180:181], v[172:173], 0
	v_mfma_f32_16x16x16_bf16 v[196:199], v[180:181], v[174:175], 0
	s_nop 7
	s_nop 1
	v_pk_add_f32 v[184:185], v[184:185], v[176:177] op_sel_hi:[1,0]
	v_pk_add_f32 v[186:187], v[186:187], v[176:177] op_sel_hi:[1,0]
	v_pk_add_f32 v[188:189], v[188:189], v[176:177] op_sel:[0,1] op_sel_hi:[1,1]
	v_pk_add_f32 v[190:191], v[190:191], v[176:177] op_sel:[0,1] op_sel_hi:[1,1]
	v_min_f32_e32 v200, 0, v184
	v_min_f32_e32 v201, 0, v185
	v_min_f32_e32 v202, 0, v186
	v_min_f32_e32 v203, 0, v187
	v_min_f32_e32 v204, 0, v188
	v_min_f32_e32 v205, 0, v189
	v_min_f32_e32 v206, 0, v190
	v_min_f32_e32 v207, 0, v191
	v_mul_f32_e64 v208, |v184|, s93
	v_mul_f32_e64 v209, |v185|, s93
	v_mul_f32_e64 v210, |v186|, s93
	v_mul_f32_e64 v211, |v187|, s93
	v_mul_f32_e64 v212, |v188|, s93
	v_mul_f32_e64 v213, |v189|, s93
	v_mul_f32_e64 v214, |v190|, s93
	v_mul_f32_e64 v215, |v191|, s93
	v_exp_f32_e32 v208, v208
	v_exp_f32_e32 v209, v209
	v_exp_f32_e32 v210, v210
	v_exp_f32_e32 v211, v211
	v_exp_f32_e32 v212, v212
	v_exp_f32_e32 v213, v213
	v_exp_f32_e32 v214, v214
	v_exp_f32_e32 v215, v215
	v_pk_add_f32 v[208:209], v[208:209], 1.0 op_sel_hi:[1,0]
	v_pk_add_f32 v[210:211], v[210:211], 1.0 op_sel_hi:[1,0]
	v_pk_add_f32 v[212:213], v[212:213], 1.0 op_sel_hi:[1,0]
	v_pk_add_f32 v[214:215], v[214:215], 1.0 op_sel_hi:[1,0]
	v_log_f32_e32 v208, v208
	v_log_f32_e32 v209, v209
	v_log_f32_e32 v210, v210
	v_log_f32_e32 v211, v211
	v_log_f32_e32 v212, v212
	v_log_f32_e32 v213, v213
	v_log_f32_e32 v214, v214
	v_log_f32_e32 v215, v215
	v_pk_mul_f32 v[216:217], v[208:209], s[94:95] op_sel:[0,1] op_sel_hi:[1,1]
	v_pk_mul_f32 v[218:219], v[210:211], s[94:95] op_sel:[0,1] op_sel_hi:[1,1]
	v_pk_mul_f32 v[220:221], v[212:213], s[94:95] op_sel:[0,1] op_sel_hi:[1,1]
	v_pk_mul_f32 v[222:223], v[214:215], s[94:95] op_sel:[0,1] op_sel_hi:[1,1]
	v_pk_fma_f32 v[216:217], v[208:209], s[94:95], v[216:217] op_sel:[0,1,0] op_sel_hi:[1,1,1] neg_lo:[0,0,1] neg_hi:[0,0,1]
	v_pk_fma_f32 v[218:219], v[210:211], s[94:95], v[218:219] op_sel:[0,1,0] op_sel_hi:[1,1,1] neg_lo:[0,0,1] neg_hi:[0,0,1]
	v_pk_fma_f32 v[220:221], v[212:213], s[94:95], v[220:221] op_sel:[0,1,0] op_sel_hi:[1,1,1] neg_lo:[0,0,1] neg_hi:[0,0,1]
	v_pk_fma_f32 v[222:223], v[214:215], s[94:95], v[222:223] op_sel:[0,1,0] op_sel_hi:[1,1,1] neg_lo:[0,0,1] neg_hi:[0,0,1]
	v_pk_fma_f32 v[216:217], v[208:209], s[94:95], v[216:217] op_sel_hi:[1,0,1]
	v_pk_fma_f32 v[218:219], v[210:211], s[94:95], v[218:219] op_sel_hi:[1,0,1]
	v_pk_fma_f32 v[220:221], v[212:213], s[94:95], v[220:221] op_sel_hi:[1,0,1]
	v_pk_fma_f32 v[222:223], v[214:215], s[94:95], v[222:223] op_sel_hi:[1,0,1]
	v_pk_fma_f32 v[216:217], v[208:209], s[94:95], v[216:217] op_sel:[0,1,0] op_sel_hi:[1,1,1]
	v_pk_fma_f32 v[218:219], v[210:211], s[94:95], v[218:219] op_sel:[0,1,0] op_sel_hi:[1,1,1]
	v_pk_fma_f32 v[220:221], v[212:213], s[94:95], v[220:221] op_sel:[0,1,0] op_sel_hi:[1,1,1]
	v_pk_fma_f32 v[222:223], v[214:215], s[94:95], v[222:223] op_sel:[0,1,0] op_sel_hi:[1,1,1]
	v_pk_add_f32 v[200:201], v[200:201], v[216:217] neg_lo:[0,1] neg_hi:[0,1]
	v_pk_add_f32 v[202:203], v[202:203], v[218:219] neg_lo:[0,1] neg_hi:[0,1]
	v_pk_add_f32 v[204:205], v[204:205], v[220:221] neg_lo:[0,1] neg_hi:[0,1]
	v_pk_add_f32 v[206:207], v[206:207], v[222:223] neg_lo:[0,1] neg_hi:[0,1]
	v_pk_mul_f32 v[184:185], v[200:201], s[96:97] op_sel_hi:[1,0]
	v_pk_mul_f32 v[186:187], v[202:203], s[96:97] op_sel_hi:[1,0]
	v_pk_mul_f32 v[188:189], v[204:205], s[96:97] op_sel_hi:[1,0]
	v_pk_mul_f32 v[190:191], v[206:207], s[96:97] op_sel_hi:[1,0]
	v_pk_add_f32 v[192:193], v[192:193], v[178:179] op_sel_hi:[1,0]
	v_pk_add_f32 v[194:195], v[194:195], v[178:179] op_sel_hi:[1,0]
	v_pk_add_f32 v[196:197], v[196:197], v[178:179] op_sel:[0,1] op_sel_hi:[1,1]
	v_pk_add_f32 v[198:199], v[198:199], v[178:179] op_sel:[0,1] op_sel_hi:[1,1]
	v_min_f32_e32 v200, 0, v192
	v_min_f32_e32 v201, 0, v193
	v_min_f32_e32 v202, 0, v194
	v_min_f32_e32 v203, 0, v195
	v_min_f32_e32 v204, 0, v196
	v_min_f32_e32 v205, 0, v197
	v_min_f32_e32 v206, 0, v198
	v_min_f32_e32 v207, 0, v199
	v_mul_f32_e64 v208, |v192|, s93
	v_mul_f32_e64 v209, |v193|, s93
	v_mul_f32_e64 v210, |v194|, s93
	v_mul_f32_e64 v211, |v195|, s93
	v_mul_f32_e64 v212, |v196|, s93
	v_mul_f32_e64 v213, |v197|, s93
	v_mul_f32_e64 v214, |v198|, s93
	v_mul_f32_e64 v215, |v199|, s93
	v_exp_f32_e32 v208, v208
	v_exp_f32_e32 v209, v209
	v_exp_f32_e32 v210, v210
	v_exp_f32_e32 v211, v211
	v_exp_f32_e32 v212, v212
	v_exp_f32_e32 v213, v213
	v_exp_f32_e32 v214, v214
	v_exp_f32_e32 v215, v215
	v_pk_add_f32 v[208:209], v[208:209], 1.0 op_sel_hi:[1,0]
	v_pk_add_f32 v[210:211], v[210:211], 1.0 op_sel_hi:[1,0]
	v_pk_add_f32 v[212:213], v[212:213], 1.0 op_sel_hi:[1,0]
	v_pk_add_f32 v[214:215], v[214:215], 1.0 op_sel_hi:[1,0]
	v_log_f32_e32 v208, v208
	v_log_f32_e32 v209, v209
	v_log_f32_e32 v210, v210
	v_log_f32_e32 v211, v211
	v_log_f32_e32 v212, v212
	v_log_f32_e32 v213, v213
	v_log_f32_e32 v214, v214
	v_log_f32_e32 v215, v215
	v_pk_mul_f32 v[216:217], v[208:209], s[94:95] op_sel:[0,1] op_sel_hi:[1,1]
	v_pk_mul_f32 v[218:219], v[210:211], s[94:95] op_sel:[0,1] op_sel_hi:[1,1]
	v_pk_mul_f32 v[220:221], v[212:213], s[94:95] op_sel:[0,1] op_sel_hi:[1,1]
	v_pk_mul_f32 v[222:223], v[214:215], s[94:95] op_sel:[0,1] op_sel_hi:[1,1]
	v_pk_fma_f32 v[216:217], v[208:209], s[94:95], v[216:217] op_sel:[0,1,0] op_sel_hi:[1,1,1] neg_lo:[0,0,1] neg_hi:[0,0,1]
; __device__ __forceinline__ void store_rm4(u16* dst, size_t ld, int row0, int c, float v0, float v1, float v2, float v3, bool odd) {
;   {
;     float s = odd ? v0 : v1, r = dpp_swap1(s);
;     float lo = odd ? r : v0, hi = odd ? v1 : r;
;     *(unsigned*)(dst + (size_t)(row0 + (odd ? 1 : 0)) * ld + (c - (odd ? 1 : 0))) = pack2(lo, hi);
;   }
;   {
;     float s = odd ? v2 : v3, r = dpp_swap1(s);
;     float lo = odd ? r : v2, hi = odd ? v3 : r;
;     *(unsigned*)(dst + (size_t)(row0 + 2 + (odd ? 1 : 0)) * ld + (c - (odd ? 1 : 0))) = pack2(lo, hi);
;   }
;   __device__ __forceinline__ void operator()(f32x4 (&acc)[2][2][4][2], int brow, int bcol, int wr, int wc, int fr, int fq) const {
;     ...
;                 f32x4 z4 = {0.f, 0.f, 0.f, 0.f};
;                 z4 = __builtin_amdgcn_mfma_f32_16x16x16bf16_1k(af, bfr[bj][n], z4, 0, 0, 0);
;                 int c = bj * 128 + wc * 32 + n * 16 + fr;
;                 float bb = bias[c];
;                 float ls[4];
; #pragma unroll
;                 for (int j = 0; j < 4; ++j) {
;                   float z = z4[j] + bb;
;                   ls[j] = (fminf(z, 0.f) - __logf(1.f + __expf(-fabsf(z)))) * (1.f / 16.f);
;                 }
;                 store_rm4(dst, 256, row0, c, ls[0], ls[1], ls[2], ls[3], fr & 1);
	v_pk_fma_f32 v[218:219], v[210:211], s[94:95], v[218:219] op_sel:[0,1,0] op_sel_hi:[1,1,1] neg_lo:[0,0,1] neg_hi:[0,0,1]
	v_pk_fma_f32 v[220:221], v[212:213], s[94:95], v[220:221] op_sel:[0,1,0] op_sel_hi:[1,1,1] neg_lo:[0,0,1] neg_hi:[0,0,1]
	v_pk_fma_f32 v[222:223], v[214:215], s[94:95], v[222:223] op_sel:[0,1,0] op_sel_hi:[1,1,1] neg_lo:[0,0,1] neg_hi:[0,0,1]
	v_pk_fma_f32 v[216:217], v[208:209], s[94:95], v[216:217] op_sel_hi:[1,0,1]
	v_pk_fma_f32 v[218:219], v[210:211], s[94:95], v[218:219] op_sel_hi:[1,0,1]
	v_pk_fma_f32 v[220:221], v[212:213], s[94:95], v[220:221] op_sel_hi:[1,0,1]
	v_pk_fma_f32 v[222:223], v[214:215], s[94:95], v[222:223] op_sel_hi:[1,0,1]
	v_pk_fma_f32 v[216:217], v[208:209], s[94:95], v[216:217] op_sel:[0,1,0] op_sel_hi:[1,1,1]
	v_pk_fma_f32 v[218:219], v[210:211], s[94:95], v[218:219] op_sel:[0,1,0] op_sel_hi:[1,1,1]
	v_pk_fma_f32 v[220:221], v[212:213], s[94:95], v[220:221] op_sel:[0,1,0] op_sel_hi:[1,1,1]
	v_pk_fma_f32 v[222:223], v[214:215], s[94:95], v[222:223] op_sel:[0,1,0] op_sel_hi:[1,1,1]
	v_pk_add_f32 v[200:201], v[200:201], v[216:217] neg_lo:[0,1] neg_hi:[0,1]
	v_pk_add_f32 v[202:203], v[202:203], v[218:219] neg_lo:[0,1] neg_hi:[0,1]
	v_pk_add_f32 v[204:205], v[204:205], v[220:221] neg_lo:[0,1] neg_hi:[0,1]
	v_pk_add_f32 v[206:207], v[206:207], v[222:223] neg_lo:[0,1] neg_hi:[0,1]
	v_pk_mul_f32 v[192:193], v[200:201], s[96:97] op_sel_hi:[1,0]
	v_pk_mul_f32 v[194:195], v[202:203], s[96:97] op_sel_hi:[1,0]
	v_pk_mul_f32 v[196:197], v[204:205], s[96:97] op_sel_hi:[1,0]
	v_pk_mul_f32 v[198:199], v[206:207], s[96:97] op_sel_hi:[1,0]
	v_cvt_pk_bf16_f32 v208, v184, v185
	v_cvt_pk_bf16_f32 v209, v186, v187
	v_cvt_pk_bf16_f32 v210, v188, v189
	v_cvt_pk_bf16_f32 v211, v190, v191
	v_cvt_pk_bf16_f32 v212, v192, v193
	v_cvt_pk_bf16_f32 v213, v194, v195
	v_cvt_pk_bf16_f32 v214, v196, v197
	v_cvt_pk_bf16_f32 v215, v198, v199
	v_mov_b32_dpp v216, v208 quad_perm:[1,0,3,2] row_mask:0xf bank_mask:0xf bound_ctrl:1
	v_mov_b32_dpp v217, v209 quad_perm:[1,0,3,2] row_mask:0xf bank_mask:0xf bound_ctrl:1
	v_mov_b32_dpp v218, v210 quad_perm:[1,0,3,2] row_mask:0xf bank_mask:0xf bound_ctrl:1
	v_mov_b32_dpp v219, v211 quad_perm:[1,0,3,2] row_mask:0xf bank_mask:0xf bound_ctrl:1
	v_mov_b32_dpp v220, v212 quad_perm:[1,0,3,2] row_mask:0xf bank_mask:0xf bound_ctrl:1
	v_mov_b32_dpp v221, v213 quad_perm:[1,0,3,2] row_mask:0xf bank_mask:0xf bound_ctrl:1
	v_mov_b32_dpp v222, v214 quad_perm:[1,0,3,2] row_mask:0xf bank_mask:0xf bound_ctrl:1
	v_mov_b32_dpp v223, v215 quad_perm:[1,0,3,2] row_mask:0xf bank_mask:0xf bound_ctrl:1
	v_perm_b32 v208, v216, v208, v164
	v_perm_b32 v209, v217, v209, v164
	v_perm_b32 v210, v218, v210, v164
	v_perm_b32 v211, v219, v211, v164
	v_perm_b32 v212, v220, v212, v164
	v_perm_b32 v213, v221, v213, v164
	v_perm_b32 v214, v222, v214, v164
	v_perm_b32 v215, v223, v215, v164
	global_store_dword v167, v208, s[8:9]
	global_store_dword v167, v209, s[8:9] offset:1024
	global_store_dword v167, v210, s[8:9] offset:32
	global_store_dword v167, v211, s[8:9] offset:1056
	global_store_dword v167, v212, s[8:9] offset:256
	global_store_dword v167, v213, s[8:9] offset:1280
	global_store_dword v167, v214, s[8:9] offset:288
	global_store_dword v167, v215, s[8:9] offset:1312
	ds_read_b64 v[180:181], v160 offset:51200
	v_add_u32_e32 v167, 0x4000, v163
	s_waitcnt lgkmcnt(0)
	v_mfma_f32_16x16x16_bf16 v[184:187], v[180:181], v[168:169], 0
	v_mfma_f32_16x16x16_bf16 v[188:191], v[180:181], v[170:171], 0
	v_mfma_f32_16x16x16_bf16 v[192:195], v[180:181], v[172:173], 0
	v_mfma_f32_16x16x16_bf16 v[196:199], v[180:181], v[174:175], 0
	s_nop 7
	s_nop 1
	v_pk_add_f32 v[184:185], v[184:185], v[176:177] op_sel_hi:[1,0]
	v_pk_add_f32 v[186:187], v[186:187], v[176:177] op_sel_hi:[1,0]
	v_pk_add_f32 v[188:189], v[188:189], v[176:177] op_sel:[0,1] op_sel_hi:[1,1]
	v_pk_add_f32 v[190:191], v[190:191], v[176:177] op_sel:[0,1] op_sel_hi:[1,1]
	v_min_f32_e32 v200, 0, v184
	v_min_f32_e32 v201, 0, v185
	v_min_f32_e32 v202, 0, v186
	v_min_f32_e32 v203, 0, v187
	v_min_f32_e32 v204, 0, v188
	v_min_f32_e32 v205, 0, v189
	v_min_f32_e32 v206, 0, v190
	v_min_f32_e32 v207, 0, v191
	v_mul_f32_e64 v208, |v184|, s93
	v_mul_f32_e64 v209, |v185|, s93
	v_mul_f32_e64 v210, |v186|, s93
	v_mul_f32_e64 v211, |v187|, s93
	v_mul_f32_e64 v212, |v188|, s93
	v_mul_f32_e64 v213, |v189|, s93
	v_mul_f32_e64 v214, |v190|, s93
	v_mul_f32_e64 v215, |v191|, s93
	v_exp_f32_e32 v208, v208
	v_exp_f32_e32 v209, v209
	v_exp_f32_e32 v210, v210
	v_exp_f32_e32 v211, v211
	v_exp_f32_e32 v212, v212
	v_exp_f32_e32 v213, v213
	v_exp_f32_e32 v214, v214
	v_exp_f32_e32 v215, v215
	v_pk_add_f32 v[208:209], v[208:209], 1.0 op_sel_hi:[1,0]
	v_pk_add_f32 v[210:211], v[210:211], 1.0 op_sel_hi:[1,0]
	v_pk_add_f32 v[212:213], v[212:213], 1.0 op_sel_hi:[1,0]
	v_pk_add_f32 v[214:215], v[214:215], 1.0 op_sel_hi:[1,0]
	v_log_f32_e32 v208, v208
	v_log_f32_e32 v209, v209
	v_log_f32_e32 v210, v210
	v_log_f32_e32 v211, v211
	v_log_f32_e32 v212, v212
	v_log_f32_e32 v213, v213
	v_log_f32_e32 v214, v214
	v_log_f32_e32 v215, v215
	v_pk_mul_f32 v[216:217], v[208:209], s[94:95] op_sel:[0,1] op_sel_hi:[1,1]
	v_pk_mul_f32 v[218:219], v[210:211], s[94:95] op_sel:[0,1] op_sel_hi:[1,1]
	v_pk_mul_f32 v[220:221], v[212:213], s[94:95] op_sel:[0,1] op_sel_hi:[1,1]
	v_pk_mul_f32 v[222:223], v[214:215], s[94:95] op_sel:[0,1] op_sel_hi:[1,1]
	v_pk_fma_f32 v[216:217], v[208:209], s[94:95], v[216:217] op_sel:[0,1,0] op_sel_hi:[1,1,1] neg_lo:[0,0,1] neg_hi:[0,0,1]
	v_pk_fma_f32 v[218:219], v[210:211], s[94:95], v[218:219] op_sel:[0,1,0] op_sel_hi:[1,1,1] neg_lo:[0,0,1] neg_hi:[0,0,1]
; __device__ __forceinline__ void store_rm4(u16* dst, size_t ld, int row0, int c, float v0, float v1, float v2, float v3, bool odd) {
;   {
;     float s = odd ? v0 : v1, r = dpp_swap1(s);
;     float lo = odd ? r : v0, hi = odd ? v1 : r;
;     *(unsigned*)(dst + (size_t)(row0 + (odd ? 1 : 0)) * ld + (c - (odd ? 1 : 0))) = pack2(lo, hi);
;   }
;   {
;     float s = odd ? v2 : v3, r = dpp_swap1(s);
;     float lo = odd ? r : v2, hi = odd ? v3 : r;
;     *(unsigned*)(dst + (size_t)(row0 + 2 + (odd ? 1 : 0)) * ld + (c - (odd ? 1 : 0))) = pack2(lo, hi);
;   }
;   __device__ __forceinline__ void operator()(f32x4 (&acc)[2][2][4][2], int brow, int bcol, int wr, int wc, int fr, int fq) const {
;     ...
;                 f32x4 z4 = {0.f, 0.f, 0.f, 0.f};
;                 z4 = __builtin_amdgcn_mfma_f32_16x16x16bf16_1k(af, bfr[bj][n], z4, 0, 0, 0);
;                 int c = bj * 128 + wc * 32 + n * 16 + fr;
;                 float bb = bias[c];
;                 float ls[4];
; #pragma unroll
;                 for (int j = 0; j < 4; ++j) {
;                   float z = z4[j] + bb;
;                   ls[j] = (fminf(z, 0.f) - __logf(1.f + __expf(-fabsf(z)))) * (1.f / 16.f);
;                 }
;                 store_rm4(dst, 256, row0, c, ls[0], ls[1], ls[2], ls[3], fr & 1);
	v_pk_fma_f32 v[220:221], v[212:213], s[94:95], v[220:221] op_sel:[0,1,0] op_sel_hi:[1,1,1] neg_lo:[0,0,1] neg_hi:[0,0,1]
	v_pk_fma_f32 v[222:223], v[214:215], s[94:95], v[222:223] op_sel:[0,1,0] op_sel_hi:[1,1,1] neg_lo:[0,0,1] neg_hi:[0,0,1]
	v_pk_fma_f32 v[216:217], v[208:209], s[94:95], v[216:217] op_sel_hi:[1,0,1]
	v_pk_fma_f32 v[218:219], v[210:211], s[94:95], v[218:219] op_sel_hi:[1,0,1]
	v_pk_fma_f32 v[220:221], v[212:213], s[94:95], v[220:221] op_sel_hi:[1,0,1]
	v_pk_fma_f32 v[222:223], v[214:215], s[94:95], v[222:223] op_sel_hi:[1,0,1]
	v_pk_fma_f32 v[216:217], v[208:209], s[94:95], v[216:217] op_sel:[0,1,0] op_sel_hi:[1,1,1]
	v_pk_fma_f32 v[218:219], v[210:211], s[94:95], v[218:219] op_sel:[0,1,0] op_sel_hi:[1,1,1]
	v_pk_fma_f32 v[220:221], v[212:213], s[94:95], v[220:221] op_sel:[0,1,0] op_sel_hi:[1,1,1]
	v_pk_fma_f32 v[222:223], v[214:215], s[94:95], v[222:223] op_sel:[0,1,0] op_sel_hi:[1,1,1]
	v_pk_add_f32 v[200:201], v[200:201], v[216:217] neg_lo:[0,1] neg_hi:[0,1]
	v_pk_add_f32 v[202:203], v[202:203], v[218:219] neg_lo:[0,1] neg_hi:[0,1]
	v_pk_add_f32 v[204:205], v[204:205], v[220:221] neg_lo:[0,1] neg_hi:[0,1]
	v_pk_add_f32 v[206:207], v[206:207], v[222:223] neg_lo:[0,1] neg_hi:[0,1]
	v_pk_mul_f32 v[184:185], v[200:201], s[96:97] op_sel_hi:[1,0]
	v_pk_mul_f32 v[186:187], v[202:203], s[96:97] op_sel_hi:[1,0]
	v_pk_mul_f32 v[188:189], v[204:205], s[96:97] op_sel_hi:[1,0]
	v_pk_mul_f32 v[190:191], v[206:207], s[96:97] op_sel_hi:[1,0]
	v_pk_add_f32 v[192:193], v[192:193], v[178:179] op_sel_hi:[1,0]
	v_pk_add_f32 v[194:195], v[194:195], v[178:179] op_sel_hi:[1,0]
	v_pk_add_f32 v[196:197], v[196:197], v[178:179] op_sel:[0,1] op_sel_hi:[1,1]
	v_pk_add_f32 v[198:199], v[198:199], v[178:179] op_sel:[0,1] op_sel_hi:[1,1]
	v_min_f32_e32 v200, 0, v192
	v_min_f32_e32 v201, 0, v193
	v_min_f32_e32 v202, 0, v194
	v_min_f32_e32 v203, 0, v195
	v_min_f32_e32 v204, 0, v196
	v_min_f32_e32 v205, 0, v197
	v_min_f32_e32 v206, 0, v198
	v_min_f32_e32 v207, 0, v199
	v_mul_f32_e64 v208, |v192|, s93
	v_mul_f32_e64 v209, |v193|, s93
	v_mul_f32_e64 v210, |v194|, s93
	v_mul_f32_e64 v211, |v195|, s93
	v_mul_f32_e64 v212, |v196|, s93
	v_mul_f32_e64 v213, |v197|, s93
	v_mul_f32_e64 v214, |v198|, s93
	v_mul_f32_e64 v215, |v199|, s93
	v_exp_f32_e32 v208, v208
	v_exp_f32_e32 v209, v209
	v_exp_f32_e32 v210, v210
	v_exp_f32_e32 v211, v211
	v_exp_f32_e32 v212, v212
	v_exp_f32_e32 v213, v213
	v_exp_f32_e32 v214, v214
	v_exp_f32_e32 v215, v215
	v_pk_add_f32 v[208:209], v[208:209], 1.0 op_sel_hi:[1,0]
	v_pk_add_f32 v[210:211], v[210:211], 1.0 op_sel_hi:[1,0]
	v_pk_add_f32 v[212:213], v[212:213], 1.0 op_sel_hi:[1,0]
	v_pk_add_f32 v[214:215], v[214:215], 1.0 op_sel_hi:[1,0]
	v_log_f32_e32 v208, v208
	v_log_f32_e32 v209, v209
	v_log_f32_e32 v210, v210
	v_log_f32_e32 v211, v211
	v_log_f32_e32 v212, v212
	v_log_f32_e32 v213, v213
	v_log_f32_e32 v214, v214
	v_log_f32_e32 v215, v215
	v_pk_mul_f32 v[216:217], v[208:209], s[94:95] op_sel:[0,1] op_sel_hi:[1,1]
	v_pk_mul_f32 v[218:219], v[210:211], s[94:95] op_sel:[0,1] op_sel_hi:[1,1]
	v_pk_mul_f32 v[220:221], v[212:213], s[94:95] op_sel:[0,1] op_sel_hi:[1,1]
	v_pk_mul_f32 v[222:223], v[214:215], s[94:95] op_sel:[0,1] op_sel_hi:[1,1]
	v_pk_fma_f32 v[216:217], v[208:209], s[94:95], v[216:217] op_sel:[0,1,0] op_sel_hi:[1,1,1] neg_lo:[0,0,1] neg_hi:[0,0,1]
	v_pk_fma_f32 v[218:219], v[210:211], s[94:95], v[218:219] op_sel:[0,1,0] op_sel_hi:[1,1,1] neg_lo:[0,0,1] neg_hi:[0,0,1]
	v_pk_fma_f32 v[220:221], v[212:213], s[94:95], v[220:221] op_sel:[0,1,0] op_sel_hi:[1,1,1] neg_lo:[0,0,1] neg_hi:[0,0,1]
	v_pk_fma_f32 v[222:223], v[214:215], s[94:95], v[222:223] op_sel:[0,1,0] op_sel_hi:[1,1,1] neg_lo:[0,0,1] neg_hi:[0,0,1]
	v_pk_fma_f32 v[216:217], v[208:209], s[94:95], v[216:217] op_sel_hi:[1,0,1]
	v_pk_fma_f32 v[218:219], v[210:211], s[94:95], v[218:219] op_sel_hi:[1,0,1]
	v_pk_fma_f32 v[220:221], v[212:213], s[94:95], v[220:221] op_sel_hi:[1,0,1]
	v_pk_fma_f32 v[222:223], v[214:215], s[94:95], v[222:223] op_sel_hi:[1,0,1]
	v_pk_fma_f32 v[216:217], v[208:209], s[94:95], v[216:217] op_sel:[0,1,0] op_sel_hi:[1,1,1]
	v_pk_fma_f32 v[218:219], v[210:211], s[94:95], v[218:219] op_sel:[0,1,0] op_sel_hi:[1,1,1]
	v_pk_fma_f32 v[220:221], v[212:213], s[94:95], v[220:221] op_sel:[0,1,0] op_sel_hi:[1,1,1]
	v_pk_fma_f32 v[222:223], v[214:215], s[94:95], v[222:223] op_sel:[0,1,0] op_sel_hi:[1,1,1]
	v_pk_add_f32 v[200:201], v[200:201], v[216:217] neg_lo:[0,1] neg_hi:[0,1]
	v_pk_add_f32 v[202:203], v[202:203], v[218:219] neg_lo:[0,1] neg_hi:[0,1]
	v_pk_add_f32 v[204:205], v[204:205], v[220:221] neg_lo:[0,1] neg_hi:[0,1]
	v_pk_add_f32 v[206:207], v[206:207], v[222:223] neg_lo:[0,1] neg_hi:[0,1]
	v_pk_mul_f32 v[192:193], v[200:201], s[96:97] op_sel_hi:[1,0]
	v_pk_mul_f32 v[194:195], v[202:203], s[96:97] op_sel_hi:[1,0]
	v_pk_mul_f32 v[196:197], v[204:205], s[96:97] op_sel_hi:[1,0]
	v_pk_mul_f32 v[198:199], v[206:207], s[96:97] op_sel_hi:[1,0]
	v_cvt_pk_bf16_f32 v208, v184, v185
	v_cvt_pk_bf16_f32 v209, v186, v187
	v_cvt_pk_bf16_f32 v210, v188, v189
	v_cvt_pk_bf16_f32 v211, v190, v191
	v_cvt_pk_bf16_f32 v212, v192, v193
	v_cvt_pk_bf16_f32 v213, v194, v195
	v_cvt_pk_bf16_f32 v214, v196, v197
	v_cvt_pk_bf16_f32 v215, v198, v199
	v_mov_b32_dpp v216, v208 quad_perm:[1,0,3,2] row_mask:0xf bank_mask:0xf bound_ctrl:1
	v_mov_b32_dpp v217, v209 quad_perm:[1,0,3,2] row_mask:0xf bank_mask:0xf bound_ctrl:1
	v_mov_b32_dpp v218, v210 quad_perm:[1,0,3,2] row_mask:0xf bank_mask:0xf bound_ctrl:1
	v_mov_b32_dpp v219, v211 quad_perm:[1,0,3,2] row_mask:0xf bank_mask:0xf bound_ctrl:1
	v_mov_b32_dpp v220, v212 quad_perm:[1,0,3,2] row_mask:0xf bank_mask:0xf bound_ctrl:1
	v_mov_b32_dpp v221, v213 quad_perm:[1,0,3,2] row_mask:0xf bank_mask:0xf bound_ctrl:1
	v_mov_b32_dpp v222, v214 quad_perm:[1,0,3,2] row_mask:0xf bank_mask:0xf bound_ctrl:1
	v_mov_b32_dpp v223, v215 quad_perm:[1,0,3,2] row_mask:0xf bank_mask:0xf bound_ctrl:1
	v_perm_b32 v208, v216, v208, v164
	v_perm_b32 v209, v217, v209, v164
	v_perm_b32 v210, v218, v210, v164
	v_perm_b32 v211, v219, v211, v164
	v_perm_b32 v212, v220, v212, v164
	v_perm_b32 v213, v221, v213, v164
	v_perm_b32 v214, v222, v214, v164
	v_perm_b32 v215, v223, v215, v164
	global_store_dword v167, v208, s[8:9]
	global_store_dword v167, v209, s[8:9] offset:1024
	global_store_dword v167, v210, s[8:9] offset:32
	global_store_dword v167, v211, s[8:9] offset:1056
	global_store_dword v167, v212, s[8:9] offset:256
	global_store_dword v167, v213, s[8:9] offset:1280
	global_store_dword v167, v214, s[8:9] offset:288
	global_store_dword v167, v215, s[8:9] offset:1312
	ds_read_b64 v[180:181], v160 offset:52224
	v_add_u32_e32 v167, 0x6000, v163
	s_waitcnt lgkmcnt(0)
;   __device__ __forceinline__ void operator()(f32x4 (&acc)[2][2][4][2], int brow, int bcol, int wr, int wc, int fr, int fq) const {
;     ...
;                 f32x4 z4 = {0.f, 0.f, 0.f, 0.f};
;                 z4 = __builtin_amdgcn_mfma_f32_16x16x16bf16_1k(af, bfr[bj][n], z4, 0, 0, 0);
;                 int c = bj * 128 + wc * 32 + n * 16 + fr;
;                 float bb = bias[c];
;                 float ls[4];
; #pragma unroll
;                 for (int j = 0; j < 4; ++j) {
;                   float z = z4[j] + bb;
;                   ls[j] = (fminf(z, 0.f) - __logf(1.f + __expf(-fabsf(z)))) * (1.f / 16.f);
;                 }
	v_mfma_f32_16x16x16_bf16 v[184:187], v[180:181], v[168:169], 0
	v_mfma_f32_16x16x16_bf16 v[188:191], v[180:181], v[170:171], 0
	v_mfma_f32_16x16x16_bf16 v[192:195], v[180:181], v[172:173], 0
	v_mfma_f32_16x16x16_bf16 v[196:199], v[180:181], v[174:175], 0
	s_nop 7
	s_nop 1
	v_pk_add_f32 v[184:185], v[184:185], v[176:177] op_sel_hi:[1,0]
	v_pk_add_f32 v[186:187], v[186:187], v[176:177] op_sel_hi:[1,0]
	v_pk_add_f32 v[188:189], v[188:189], v[176:177] op_sel:[0,1] op_sel_hi:[1,1]
	v_pk_add_f32 v[190:191], v[190:191], v[176:177] op_sel:[0,1] op_sel_hi:[1,1]
	v_min_f32_e32 v200, 0, v184
	v_min_f32_e32 v201, 0, v185
	v_min_f32_e32 v202, 0, v186
	v_min_f32_e32 v203, 0, v187
	v_min_f32_e32 v204, 0, v188
	v_min_f32_e32 v205, 0, v189
	v_min_f32_e32 v206, 0, v190
	v_min_f32_e32 v207, 0, v191
	v_mul_f32_e64 v208, |v184|, s93
	v_mul_f32_e64 v209, |v185|, s93
	v_mul_f32_e64 v210, |v186|, s93
	v_mul_f32_e64 v211, |v187|, s93
	v_mul_f32_e64 v212, |v188|, s93
	v_mul_f32_e64 v213, |v189|, s93
	v_mul_f32_e64 v214, |v190|, s93
	v_mul_f32_e64 v215, |v191|, s93
	v_exp_f32_e32 v208, v208
	v_exp_f32_e32 v209, v209
	v_exp_f32_e32 v210, v210
	v_exp_f32_e32 v211, v211
	v_exp_f32_e32 v212, v212
	v_exp_f32_e32 v213, v213
	v_exp_f32_e32 v214, v214
	v_exp_f32_e32 v215, v215
	v_pk_add_f32 v[208:209], v[208:209], 1.0 op_sel_hi:[1,0]
	v_pk_add_f32 v[210:211], v[210:211], 1.0 op_sel_hi:[1,0]
	v_pk_add_f32 v[212:213], v[212:213], 1.0 op_sel_hi:[1,0]
	v_pk_add_f32 v[214:215], v[214:215], 1.0 op_sel_hi:[1,0]
	v_log_f32_e32 v208, v208
	v_log_f32_e32 v209, v209
	v_log_f32_e32 v210, v210
	v_log_f32_e32 v211, v211
	v_log_f32_e32 v212, v212
	v_log_f32_e32 v213, v213
	v_log_f32_e32 v214, v214
	v_log_f32_e32 v215, v215
	v_pk_mul_f32 v[216:217], v[208:209], s[94:95] op_sel:[0,1] op_sel_hi:[1,1]
	v_pk_mul_f32 v[218:219], v[210:211], s[94:95] op_sel:[0,1] op_sel_hi:[1,1]
	v_pk_mul_f32 v[220:221], v[212:213], s[94:95] op_sel:[0,1] op_sel_hi:[1,1]
	v_pk_mul_f32 v[222:223], v[214:215], s[94:95] op_sel:[0,1] op_sel_hi:[1,1]
	v_pk_fma_f32 v[216:217], v[208:209], s[94:95], v[216:217] op_sel:[0,1,0] op_sel_hi:[1,1,1] neg_lo:[0,0,1] neg_hi:[0,0,1]
	v_pk_fma_f32 v[218:219], v[210:211], s[94:95], v[218:219] op_sel:[0,1,0] op_sel_hi:[1,1,1] neg_lo:[0,0,1] neg_hi:[0,0,1]
	v_pk_fma_f32 v[220:221], v[212:213], s[94:95], v[220:221] op_sel:[0,1,0] op_sel_hi:[1,1,1] neg_lo:[0,0,1] neg_hi:[0,0,1]
	v_pk_fma_f32 v[222:223], v[214:215], s[94:95], v[222:223] op_sel:[0,1,0] op_sel_hi:[1,1,1] neg_lo:[0,0,1] neg_hi:[0,0,1]
	v_pk_fma_f32 v[216:217], v[208:209], s[94:95], v[216:217] op_sel_hi:[1,0,1]
	v_pk_fma_f32 v[218:219], v[210:211], s[94:95], v[218:219] op_sel_hi:[1,0,1]
	v_pk_fma_f32 v[220:221], v[212:213], s[94:95], v[220:221] op_sel_hi:[1,0,1]
	v_pk_fma_f32 v[222:223], v[214:215], s[94:95], v[222:223] op_sel_hi:[1,0,1]
	v_pk_fma_f32 v[216:217], v[208:209], s[94:95], v[216:217] op_sel:[0,1,0] op_sel_hi:[1,1,1]
	v_pk_fma_f32 v[218:219], v[210:211], s[94:95], v[218:219] op_sel:[0,1,0] op_sel_hi:[1,1,1]
	v_pk_fma_f32 v[220:221], v[212:213], s[94:95], v[220:221] op_sel:[0,1,0] op_sel_hi:[1,1,1]
	v_pk_fma_f32 v[222:223], v[214:215], s[94:95], v[222:223] op_sel:[0,1,0] op_sel_hi:[1,1,1]
	v_pk_add_f32 v[200:201], v[200:201], v[216:217] neg_lo:[0,1] neg_hi:[0,1]
	v_pk_add_f32 v[202:203], v[202:203], v[218:219] neg_lo:[0,1] neg_hi:[0,1]
	v_pk_add_f32 v[204:205], v[204:205], v[220:221] neg_lo:[0,1] neg_hi:[0,1]
	v_pk_add_f32 v[206:207], v[206:207], v[222:223] neg_lo:[0,1] neg_hi:[0,1]
	v_pk_mul_f32 v[184:185], v[200:201], s[96:97] op_sel_hi:[1,0]
	v_pk_mul_f32 v[186:187], v[202:203], s[96:97] op_sel_hi:[1,0]
	v_pk_mul_f32 v[188:189], v[204:205], s[96:97] op_sel_hi:[1,0]
	v_pk_mul_f32 v[190:191], v[206:207], s[96:97] op_sel_hi:[1,0]
	v_pk_add_f32 v[192:193], v[192:193], v[178:179] op_sel_hi:[1,0]
	v_pk_add_f32 v[194:195], v[194:195], v[178:179] op_sel_hi:[1,0]
	v_pk_add_f32 v[196:197], v[196:197], v[178:179] op_sel:[0,1] op_sel_hi:[1,1]
	v_pk_add_f32 v[198:199], v[198:199], v[178:179] op_sel:[0,1] op_sel_hi:[1,1]
	v_min_f32_e32 v200, 0, v192
	v_min_f32_e32 v201, 0, v193
	v_min_f32_e32 v202, 0, v194
	v_min_f32_e32 v203, 0, v195
	v_min_f32_e32 v204, 0, v196
	v_min_f32_e32 v205, 0, v197
	v_min_f32_e32 v206, 0, v198
	v_min_f32_e32 v207, 0, v199
	v_mul_f32_e64 v208, |v192|, s93
	v_mul_f32_e64 v209, |v193|, s93
	v_mul_f32_e64 v210, |v194|, s93
	v_mul_f32_e64 v211, |v195|, s93
	v_mul_f32_e64 v212, |v196|, s93
	v_mul_f32_e64 v213, |v197|, s93
	v_mul_f32_e64 v214, |v198|, s93
	v_mul_f32_e64 v215, |v199|, s93
	v_exp_f32_e32 v208, v208
	v_exp_f32_e32 v209, v209
	v_exp_f32_e32 v210, v210
	v_exp_f32_e32 v211, v211
	v_exp_f32_e32 v212, v212
	v_exp_f32_e32 v213, v213
	v_exp_f32_e32 v214, v214
	v_exp_f32_e32 v215, v215
	v_pk_add_f32 v[208:209], v[208:209], 1.0 op_sel_hi:[1,0]
	v_pk_add_f32 v[210:211], v[210:211], 1.0 op_sel_hi:[1,0]
	v_pk_add_f32 v[212:213], v[212:213], 1.0 op_sel_hi:[1,0]
	v_pk_add_f32 v[214:215], v[214:215], 1.0 op_sel_hi:[1,0]
	v_log_f32_e32 v208, v208
	v_log_f32_e32 v209, v209
	v_log_f32_e32 v210, v210
	v_log_f32_e32 v211, v211
	v_log_f32_e32 v212, v212
	v_log_f32_e32 v213, v213
	v_log_f32_e32 v214, v214
	v_log_f32_e32 v215, v215
	v_pk_mul_f32 v[216:217], v[208:209], s[94:95] op_sel:[0,1] op_sel_hi:[1,1]
	v_pk_mul_f32 v[218:219], v[210:211], s[94:95] op_sel:[0,1] op_sel_hi:[1,1]
	v_pk_mul_f32 v[220:221], v[212:213], s[94:95] op_sel:[0,1] op_sel_hi:[1,1]
	v_pk_mul_f32 v[222:223], v[214:215], s[94:95] op_sel:[0,1] op_sel_hi:[1,1]
	v_pk_fma_f32 v[216:217], v[208:209], s[94:95], v[216:217] op_sel:[0,1,0] op_sel_hi:[1,1,1] neg_lo:[0,0,1] neg_hi:[0,0,1]
; __device__ __forceinline__ void store_rm4(u16* dst, size_t ld, int row0, int c, float v0, float v1, float v2, float v3, bool odd) {
;   {
;     float s = odd ? v0 : v1, r = dpp_swap1(s);
;     float lo = odd ? r : v0, hi = odd ? v1 : r;
;     *(unsigned*)(dst + (size_t)(row0 + (odd ? 1 : 0)) * ld + (c - (odd ? 1 : 0))) = pack2(lo, hi);
;   }
;   {
;     float s = odd ? v2 : v3, r = dpp_swap1(s);
;     float lo = odd ? r : v2, hi = odd ? v3 : r;
;     *(unsigned*)(dst + (size_t)(row0 + 2 + (odd ? 1 : 0)) * ld + (c - (odd ? 1 : 0))) = pack2(lo, hi);
;   }
;   __device__ __forceinline__ void operator()(f32x4 (&acc)[2][2][4][2], int brow, int bcol, int wr, int wc, int fr, int fq) const {
;     ...
;             for (int bj = 0; bj < 2; ++bj)
; #pragma unroll
;               for (int n = 0; n < 2; ++n) {
;                 f32x4 z4 = {0.f, 0.f, 0.f, 0.f};
;                 z4 = __builtin_amdgcn_mfma_f32_16x16x16bf16_1k(af, bfr[bj][n], z4, 0, 0, 0);
;                 int c = bj * 128 + wc * 32 + n * 16 + fr;
;                 float bb = bias[c];
;                 float ls[4];
; #pragma unroll
;                 for (int j = 0; j < 4; ++j) {
;                   float z = z4[j] + bb;
;                   ls[j] = (fminf(z, 0.f) - __logf(1.f + __expf(-fabsf(z)))) * (1.f / 16.f);
;                 }
;                 store_rm4(dst, 256, row0, c, ls[0], ls[1], ls[2], ls[3], fr & 1);
;               }
	v_pk_fma_f32 v[218:219], v[210:211], s[94:95], v[218:219] op_sel:[0,1,0] op_sel_hi:[1,1,1] neg_lo:[0,0,1] neg_hi:[0,0,1]
	v_pk_fma_f32 v[220:221], v[212:213], s[94:95], v[220:221] op_sel:[0,1,0] op_sel_hi:[1,1,1] neg_lo:[0,0,1] neg_hi:[0,0,1]
	v_pk_fma_f32 v[222:223], v[214:215], s[94:95], v[222:223] op_sel:[0,1,0] op_sel_hi:[1,1,1] neg_lo:[0,0,1] neg_hi:[0,0,1]
	v_pk_fma_f32 v[216:217], v[208:209], s[94:95], v[216:217] op_sel_hi:[1,0,1]
	v_pk_fma_f32 v[218:219], v[210:211], s[94:95], v[218:219] op_sel_hi:[1,0,1]
	v_pk_fma_f32 v[220:221], v[212:213], s[94:95], v[220:221] op_sel_hi:[1,0,1]
	v_pk_fma_f32 v[222:223], v[214:215], s[94:95], v[222:223] op_sel_hi:[1,0,1]
	v_pk_fma_f32 v[216:217], v[208:209], s[94:95], v[216:217] op_sel:[0,1,0] op_sel_hi:[1,1,1]
	v_pk_fma_f32 v[218:219], v[210:211], s[94:95], v[218:219] op_sel:[0,1,0] op_sel_hi:[1,1,1]
	v_pk_fma_f32 v[220:221], v[212:213], s[94:95], v[220:221] op_sel:[0,1,0] op_sel_hi:[1,1,1]
	v_pk_fma_f32 v[222:223], v[214:215], s[94:95], v[222:223] op_sel:[0,1,0] op_sel_hi:[1,1,1]
	v_pk_add_f32 v[200:201], v[200:201], v[216:217] neg_lo:[0,1] neg_hi:[0,1]
	v_pk_add_f32 v[202:203], v[202:203], v[218:219] neg_lo:[0,1] neg_hi:[0,1]
	v_pk_add_f32 v[204:205], v[204:205], v[220:221] neg_lo:[0,1] neg_hi:[0,1]
	v_pk_add_f32 v[206:207], v[206:207], v[222:223] neg_lo:[0,1] neg_hi:[0,1]
	v_pk_mul_f32 v[192:193], v[200:201], s[96:97] op_sel_hi:[1,0]
	v_pk_mul_f32 v[194:195], v[202:203], s[96:97] op_sel_hi:[1,0]
	v_pk_mul_f32 v[196:197], v[204:205], s[96:97] op_sel_hi:[1,0]
	v_pk_mul_f32 v[198:199], v[206:207], s[96:97] op_sel_hi:[1,0]
	v_cvt_pk_bf16_f32 v208, v184, v185
	v_cvt_pk_bf16_f32 v209, v186, v187
	v_cvt_pk_bf16_f32 v210, v188, v189
	v_cvt_pk_bf16_f32 v211, v190, v191
	v_cvt_pk_bf16_f32 v212, v192, v193
	v_cvt_pk_bf16_f32 v213, v194, v195
	v_cvt_pk_bf16_f32 v214, v196, v197
	v_cvt_pk_bf16_f32 v215, v198, v199
	v_mov_b32_dpp v216, v208 quad_perm:[1,0,3,2] row_mask:0xf bank_mask:0xf bound_ctrl:1
	v_mov_b32_dpp v217, v209 quad_perm:[1,0,3,2] row_mask:0xf bank_mask:0xf bound_ctrl:1
	v_mov_b32_dpp v218, v210 quad_perm:[1,0,3,2] row_mask:0xf bank_mask:0xf bound_ctrl:1
	v_mov_b32_dpp v219, v211 quad_perm:[1,0,3,2] row_mask:0xf bank_mask:0xf bound_ctrl:1
	v_mov_b32_dpp v220, v212 quad_perm:[1,0,3,2] row_mask:0xf bank_mask:0xf bound_ctrl:1
	v_mov_b32_dpp v221, v213 quad_perm:[1,0,3,2] row_mask:0xf bank_mask:0xf bound_ctrl:1
	v_mov_b32_dpp v222, v214 quad_perm:[1,0,3,2] row_mask:0xf bank_mask:0xf bound_ctrl:1
	v_mov_b32_dpp v223, v215 quad_perm:[1,0,3,2] row_mask:0xf bank_mask:0xf bound_ctrl:1
	v_perm_b32 v208, v216, v208, v164
	v_perm_b32 v209, v217, v209, v164
	v_perm_b32 v210, v218, v210, v164
	v_perm_b32 v211, v219, v211, v164
	v_perm_b32 v212, v220, v212, v164
	v_perm_b32 v213, v221, v213, v164
	v_perm_b32 v214, v222, v214, v164
	v_perm_b32 v215, v223, v215, v164
	global_store_dword v167, v208, s[8:9]
	global_store_dword v167, v209, s[8:9] offset:1024
	global_store_dword v167, v210, s[8:9] offset:32
	global_store_dword v167, v211, s[8:9] offset:1056
	global_store_dword v167, v212, s[8:9] offset:256
	global_store_dword v167, v213, s[8:9] offset:1280
	global_store_dword v167, v214, s[8:9] offset:288
	global_store_dword v167, v215, s[8:9] offset:1312
	ds_read_b64 v[180:181], v160 offset:57344
	v_add_u32_e32 v167, 0x10000, v163
	s_waitcnt lgkmcnt(0)
	v_mfma_f32_16x16x16_bf16 v[184:187], v[180:181], v[168:169], 0
	v_mfma_f32_16x16x16_bf16 v[188:191], v[180:181], v[170:171], 0
	v_mfma_f32_16x16x16_bf16 v[192:195], v[180:181], v[172:173], 0
	v_mfma_f32_16x16x16_bf16 v[196:199], v[180:181], v[174:175], 0
	s_nop 7
	s_nop 1
	v_pk_add_f32 v[184:185], v[184:185], v[176:177] op_sel_hi:[1,0]
	v_pk_add_f32 v[186:187], v[186:187], v[176:177] op_sel_hi:[1,0]
	v_pk_add_f32 v[188:189], v[188:189], v[176:177] op_sel:[0,1] op_sel_hi:[1,1]
	v_pk_add_f32 v[190:191], v[190:191], v[176:177] op_sel:[0,1] op_sel_hi:[1,1]
	v_min_f32_e32 v200, 0, v184
	v_min_f32_e32 v201, 0, v185
	v_min_f32_e32 v202, 0, v186
	v_min_f32_e32 v203, 0, v187
	v_min_f32_e32 v204, 0, v188
	v_min_f32_e32 v205, 0, v189
	v_min_f32_e32 v206, 0, v190
	v_min_f32_e32 v207, 0, v191
	v_mul_f32_e64 v208, |v184|, s93
	v_mul_f32_e64 v209, |v185|, s93
	v_mul_f32_e64 v210, |v186|, s93
	v_mul_f32_e64 v211, |v187|, s93
	v_mul_f32_e64 v212, |v188|, s93
	v_mul_f32_e64 v213, |v189|, s93
	v_mul_f32_e64 v214, |v190|, s93
	v_mul_f32_e64 v215, |v191|, s93
	v_exp_f32_e32 v208, v208
	v_exp_f32_e32 v209, v209
	v_exp_f32_e32 v210, v210
	v_exp_f32_e32 v211, v211
	v_exp_f32_e32 v212, v212
	v_exp_f32_e32 v213, v213
	v_exp_f32_e32 v214, v214
	v_exp_f32_e32 v215, v215
	v_pk_add_f32 v[208:209], v[208:209], 1.0 op_sel_hi:[1,0]
	v_pk_add_f32 v[210:211], v[210:211], 1.0 op_sel_hi:[1,0]
	v_pk_add_f32 v[212:213], v[212:213], 1.0 op_sel_hi:[1,0]
	v_pk_add_f32 v[214:215], v[214:215], 1.0 op_sel_hi:[1,0]
	v_log_f32_e32 v208, v208
	v_log_f32_e32 v209, v209
	v_log_f32_e32 v210, v210
	v_log_f32_e32 v211, v211
	v_log_f32_e32 v212, v212
	v_log_f32_e32 v213, v213
	v_log_f32_e32 v214, v214
	v_log_f32_e32 v215, v215
	v_pk_mul_f32 v[216:217], v[208:209], s[94:95] op_sel:[0,1] op_sel_hi:[1,1]
	v_pk_mul_f32 v[218:219], v[210:211], s[94:95] op_sel:[0,1] op_sel_hi:[1,1]
	v_pk_mul_f32 v[220:221], v[212:213], s[94:95] op_sel:[0,1] op_sel_hi:[1,1]
	v_pk_mul_f32 v[222:223], v[214:215], s[94:95] op_sel:[0,1] op_sel_hi:[1,1]
	v_pk_fma_f32 v[216:217], v[208:209], s[94:95], v[216:217] op_sel:[0,1,0] op_sel_hi:[1,1,1] neg_lo:[0,0,1] neg_hi:[0,0,1]
	v_pk_fma_f32 v[218:219], v[210:211], s[94:95], v[218:219] op_sel:[0,1,0] op_sel_hi:[1,1,1] neg_lo:[0,0,1] neg_hi:[0,0,1]
; __device__ __forceinline__ void store_rm4(u16* dst, size_t ld, int row0, int c, float v0, float v1, float v2, float v3, bool odd) {
;   {
;     float s = odd ? v0 : v1, r = dpp_swap1(s);
;     float lo = odd ? r : v0, hi = odd ? v1 : r;
;     *(unsigned*)(dst + (size_t)(row0 + (odd ? 1 : 0)) * ld + (c - (odd ? 1 : 0))) = pack2(lo, hi);
;   }
;   {
;     float s = odd ? v2 : v3, r = dpp_swap1(s);
;     float lo = odd ? r : v2, hi = odd ? v3 : r;
;     *(unsigned*)(dst + (size_t)(row0 + 2 + (odd ? 1 : 0)) * ld + (c - (odd ? 1 : 0))) = pack2(lo, hi);
;   }
;   __device__ __forceinline__ void operator()(f32x4 (&acc)[2][2][4][2], int brow, int bcol, int wr, int wc, int fr, int fq) const {
;     ...
;             for (int bj = 0; bj < 2; ++bj)
; #pragma unroll
;               for (int n = 0; n < 2; ++n) {
;                 f32x4 z4 = {0.f, 0.f, 0.f, 0.f};
;                 z4 = __builtin_amdgcn_mfma_f32_16x16x16bf16_1k(af, bfr[bj][n], z4, 0, 0, 0);
;                 int c = bj * 128 + wc * 32 + n * 16 + fr;
;                 float bb = bias[c];
;                 float ls[4];
; #pragma unroll
;                 for (int j = 0; j < 4; ++j) {
;                   float z = z4[j] + bb;
;                   ls[j] = (fminf(z, 0.f) - __logf(1.f + __expf(-fabsf(z)))) * (1.f / 16.f);
;                 }
;                 store_rm4(dst, 256, row0, c, ls[0], ls[1], ls[2], ls[3], fr & 1);
;               }
	v_pk_fma_f32 v[220:221], v[212:213], s[94:95], v[220:221] op_sel:[0,1,0] op_sel_hi:[1,1,1] neg_lo:[0,0,1] neg_hi:[0,0,1]
	v_pk_fma_f32 v[222:223], v[214:215], s[94:95], v[222:223] op_sel:[0,1,0] op_sel_hi:[1,1,1] neg_lo:[0,0,1] neg_hi:[0,0,1]
	v_pk_fma_f32 v[216:217], v[208:209], s[94:95], v[216:217] op_sel_hi:[1,0,1]
	v_pk_fma_f32 v[218:219], v[210:211], s[94:95], v[218:219] op_sel_hi:[1,0,1]
	v_pk_fma_f32 v[220:221], v[212:213], s[94:95], v[220:221] op_sel_hi:[1,0,1]
	v_pk_fma_f32 v[222:223], v[214:215], s[94:95], v[222:223] op_sel_hi:[1,0,1]
	v_pk_fma_f32 v[216:217], v[208:209], s[94:95], v[216:217] op_sel:[0,1,0] op_sel_hi:[1,1,1]
	v_pk_fma_f32 v[218:219], v[210:211], s[94:95], v[218:219] op_sel:[0,1,0] op_sel_hi:[1,1,1]
	v_pk_fma_f32 v[220:221], v[212:213], s[94:95], v[220:221] op_sel:[0,1,0] op_sel_hi:[1,1,1]
	v_pk_fma_f32 v[222:223], v[214:215], s[94:95], v[222:223] op_sel:[0,1,0] op_sel_hi:[1,1,1]
	v_pk_add_f32 v[200:201], v[200:201], v[216:217] neg_lo:[0,1] neg_hi:[0,1]
	v_pk_add_f32 v[202:203], v[202:203], v[218:219] neg_lo:[0,1] neg_hi:[0,1]
	v_pk_add_f32 v[204:205], v[204:205], v[220:221] neg_lo:[0,1] neg_hi:[0,1]
	v_pk_add_f32 v[206:207], v[206:207], v[222:223] neg_lo:[0,1] neg_hi:[0,1]
	v_pk_mul_f32 v[184:185], v[200:201], s[96:97] op_sel_hi:[1,0]
	v_pk_mul_f32 v[186:187], v[202:203], s[96:97] op_sel_hi:[1,0]
	v_pk_mul_f32 v[188:189], v[204:205], s[96:97] op_sel_hi:[1,0]
	v_pk_mul_f32 v[190:191], v[206:207], s[96:97] op_sel_hi:[1,0]
	v_pk_add_f32 v[192:193], v[192:193], v[178:179] op_sel_hi:[1,0]
	v_pk_add_f32 v[194:195], v[194:195], v[178:179] op_sel_hi:[1,0]
	v_pk_add_f32 v[196:197], v[196:197], v[178:179] op_sel:[0,1] op_sel_hi:[1,1]
	v_pk_add_f32 v[198:199], v[198:199], v[178:179] op_sel:[0,1] op_sel_hi:[1,1]
	v_min_f32_e32 v200, 0, v192
	v_min_f32_e32 v201, 0, v193
	v_min_f32_e32 v202, 0, v194
	v_min_f32_e32 v203, 0, v195
	v_min_f32_e32 v204, 0, v196
	v_min_f32_e32 v205, 0, v197
	v_min_f32_e32 v206, 0, v198
	v_min_f32_e32 v207, 0, v199
	v_mul_f32_e64 v208, |v192|, s93
	v_mul_f32_e64 v209, |v193|, s93
	v_mul_f32_e64 v210, |v194|, s93
	v_mul_f32_e64 v211, |v195|, s93
	v_mul_f32_e64 v212, |v196|, s93
	v_mul_f32_e64 v213, |v197|, s93
	v_mul_f32_e64 v214, |v198|, s93
	v_mul_f32_e64 v215, |v199|, s93
	v_exp_f32_e32 v208, v208
	v_exp_f32_e32 v209, v209
	v_exp_f32_e32 v210, v210
	v_exp_f32_e32 v211, v211
	v_exp_f32_e32 v212, v212
	v_exp_f32_e32 v213, v213
	v_exp_f32_e32 v214, v214
	v_exp_f32_e32 v215, v215
	v_pk_add_f32 v[208:209], v[208:209], 1.0 op_sel_hi:[1,0]
	v_pk_add_f32 v[210:211], v[210:211], 1.0 op_sel_hi:[1,0]
	v_pk_add_f32 v[212:213], v[212:213], 1.0 op_sel_hi:[1,0]
	v_pk_add_f32 v[214:215], v[214:215], 1.0 op_sel_hi:[1,0]
	v_log_f32_e32 v208, v208
	v_log_f32_e32 v209, v209
	v_log_f32_e32 v210, v210
	v_log_f32_e32 v211, v211
	v_log_f32_e32 v212, v212
	v_log_f32_e32 v213, v213
	v_log_f32_e32 v214, v214
	v_log_f32_e32 v215, v215
	v_pk_mul_f32 v[216:217], v[208:209], s[94:95] op_sel:[0,1] op_sel_hi:[1,1]
	v_pk_mul_f32 v[218:219], v[210:211], s[94:95] op_sel:[0,1] op_sel_hi:[1,1]
	v_pk_mul_f32 v[220:221], v[212:213], s[94:95] op_sel:[0,1] op_sel_hi:[1,1]
	v_pk_mul_f32 v[222:223], v[214:215], s[94:95] op_sel:[0,1] op_sel_hi:[1,1]
	v_pk_fma_f32 v[216:217], v[208:209], s[94:95], v[216:217] op_sel:[0,1,0] op_sel_hi:[1,1,1] neg_lo:[0,0,1] neg_hi:[0,0,1]
	v_pk_fma_f32 v[218:219], v[210:211], s[94:95], v[218:219] op_sel:[0,1,0] op_sel_hi:[1,1,1] neg_lo:[0,0,1] neg_hi:[0,0,1]
	v_pk_fma_f32 v[220:221], v[212:213], s[94:95], v[220:221] op_sel:[0,1,0] op_sel_hi:[1,1,1] neg_lo:[0,0,1] neg_hi:[0,0,1]
	v_pk_fma_f32 v[222:223], v[214:215], s[94:95], v[222:223] op_sel:[0,1,0] op_sel_hi:[1,1,1] neg_lo:[0,0,1] neg_hi:[0,0,1]
	v_pk_fma_f32 v[216:217], v[208:209], s[94:95], v[216:217] op_sel_hi:[1,0,1]
	v_pk_fma_f32 v[218:219], v[210:211], s[94:95], v[218:219] op_sel_hi:[1,0,1]
	v_pk_fma_f32 v[220:221], v[212:213], s[94:95], v[220:221] op_sel_hi:[1,0,1]
	v_pk_fma_f32 v[222:223], v[214:215], s[94:95], v[222:223] op_sel_hi:[1,0,1]
	v_pk_fma_f32 v[216:217], v[208:209], s[94:95], v[216:217] op_sel:[0,1,0] op_sel_hi:[1,1,1]
	v_pk_fma_f32 v[218:219], v[210:211], s[94:95], v[218:219] op_sel:[0,1,0] op_sel_hi:[1,1,1]
	v_pk_fma_f32 v[220:221], v[212:213], s[94:95], v[220:221] op_sel:[0,1,0] op_sel_hi:[1,1,1]
	v_pk_fma_f32 v[222:223], v[214:215], s[94:95], v[222:223] op_sel:[0,1,0] op_sel_hi:[1,1,1]
	v_pk_add_f32 v[200:201], v[200:201], v[216:217] neg_lo:[0,1] neg_hi:[0,1]
	v_pk_add_f32 v[202:203], v[202:203], v[218:219] neg_lo:[0,1] neg_hi:[0,1]
	v_pk_add_f32 v[204:205], v[204:205], v[220:221] neg_lo:[0,1] neg_hi:[0,1]
	v_pk_add_f32 v[206:207], v[206:207], v[222:223] neg_lo:[0,1] neg_hi:[0,1]
	v_pk_mul_f32 v[192:193], v[200:201], s[96:97] op_sel_hi:[1,0]
	v_pk_mul_f32 v[194:195], v[202:203], s[96:97] op_sel_hi:[1,0]
	v_pk_mul_f32 v[196:197], v[204:205], s[96:97] op_sel_hi:[1,0]
	v_pk_mul_f32 v[198:199], v[206:207], s[96:97] op_sel_hi:[1,0]
	v_cvt_pk_bf16_f32 v208, v184, v185
	v_cvt_pk_bf16_f32 v209, v186, v187
	v_cvt_pk_bf16_f32 v210, v188, v189
	v_cvt_pk_bf16_f32 v211, v190, v191
	v_cvt_pk_bf16_f32 v212, v192, v193
	v_cvt_pk_bf16_f32 v213, v194, v195
	v_cvt_pk_bf16_f32 v214, v196, v197
	v_cvt_pk_bf16_f32 v215, v198, v199
	v_mov_b32_dpp v216, v208 quad_perm:[1,0,3,2] row_mask:0xf bank_mask:0xf bound_ctrl:1
	v_mov_b32_dpp v217, v209 quad_perm:[1,0,3,2] row_mask:0xf bank_mask:0xf bound_ctrl:1
	v_mov_b32_dpp v218, v210 quad_perm:[1,0,3,2] row_mask:0xf bank_mask:0xf bound_ctrl:1
	v_mov_b32_dpp v219, v211 quad_perm:[1,0,3,2] row_mask:0xf bank_mask:0xf bound_ctrl:1
	v_mov_b32_dpp v220, v212 quad_perm:[1,0,3,2] row_mask:0xf bank_mask:0xf bound_ctrl:1
	v_mov_b32_dpp v221, v213 quad_perm:[1,0,3,2] row_mask:0xf bank_mask:0xf bound_ctrl:1
	v_mov_b32_dpp v222, v214 quad_perm:[1,0,3,2] row_mask:0xf bank_mask:0xf bound_ctrl:1
	v_mov_b32_dpp v223, v215 quad_perm:[1,0,3,2] row_mask:0xf bank_mask:0xf bound_ctrl:1
	v_perm_b32 v208, v216, v208, v164
	v_perm_b32 v209, v217, v209, v164
	v_perm_b32 v210, v218, v210, v164
	v_perm_b32 v211, v219, v211, v164
	v_perm_b32 v212, v220, v212, v164
	v_perm_b32 v213, v221, v213, v164
	v_perm_b32 v214, v222, v214, v164
	v_perm_b32 v215, v223, v215, v164
	global_store_dword v167, v208, s[8:9]
	global_store_dword v167, v209, s[8:9] offset:1024
	global_store_dword v167, v210, s[8:9] offset:32
	global_store_dword v167, v211, s[8:9] offset:1056
	global_store_dword v167, v212, s[8:9] offset:256
	global_store_dword v167, v213, s[8:9] offset:1280
	global_store_dword v167, v214, s[8:9] offset:288
	global_store_dword v167, v215, s[8:9] offset:1312
	ds_read_b64 v[180:181], v160 offset:58368
	v_add_u32_e32 v167, 0x12000, v163
	s_waitcnt lgkmcnt(0)
;   __device__ __forceinline__ void operator()(f32x4 (&acc)[2][2][4][2], int brow, int bcol, int wr, int wc, int fr, int fq) const {
;     ...
;             for (int bj = 0; bj < 2; ++bj)
; #pragma unroll
;               for (int n = 0; n < 2; ++n) {
;                 f32x4 z4 = {0.f, 0.f, 0.f, 0.f};
;                 z4 = __builtin_amdgcn_mfma_f32_16x16x16bf16_1k(af, bfr[bj][n], z4, 0, 0, 0);
;                 int c = bj * 128 + wc * 32 + n * 16 + fr;
;                 float bb = bias[c];
;                 float ls[4];
; #pragma unroll
;                 for (int j = 0; j < 4; ++j) {
;                   float z = z4[j] + bb;
;                   ls[j] = (fminf(z, 0.f) - __logf(1.f + __expf(-fabsf(z)))) * (1.f / 16.f);
;                 }
;                 store_rm4(dst, 256, row0, c, ls[0], ls[1], ls[2], ls[3], fr & 1);
;               }
	v_mfma_f32_16x16x16_bf16 v[184:187], v[180:181], v[168:169], 0
	v_mfma_f32_16x16x16_bf16 v[188:191], v[180:181], v[170:171], 0
	v_mfma_f32_16x16x16_bf16 v[192:195], v[180:181], v[172:173], 0
	v_mfma_f32_16x16x16_bf16 v[196:199], v[180:181], v[174:175], 0
	s_nop 7
	s_nop 1
	v_pk_add_f32 v[184:185], v[184:185], v[176:177] op_sel_hi:[1,0]
	v_pk_add_f32 v[186:187], v[186:187], v[176:177] op_sel_hi:[1,0]
	v_pk_add_f32 v[188:189], v[188:189], v[176:177] op_sel:[0,1] op_sel_hi:[1,1]
	v_pk_add_f32 v[190:191], v[190:191], v[176:177] op_sel:[0,1] op_sel_hi:[1,1]
	v_min_f32_e32 v200, 0, v184
	v_min_f32_e32 v201, 0, v185
	v_min_f32_e32 v202, 0, v186
	v_min_f32_e32 v203, 0, v187
	v_min_f32_e32 v204, 0, v188
	v_min_f32_e32 v205, 0, v189
	v_min_f32_e32 v206, 0, v190
	v_min_f32_e32 v207, 0, v191
	v_mul_f32_e64 v208, |v184|, s93
	v_mul_f32_e64 v209, |v185|, s93
	v_mul_f32_e64 v210, |v186|, s93
	v_mul_f32_e64 v211, |v187|, s93
	v_mul_f32_e64 v212, |v188|, s93
	v_mul_f32_e64 v213, |v189|, s93
	v_mul_f32_e64 v214, |v190|, s93
	v_mul_f32_e64 v215, |v191|, s93
	v_exp_f32_e32 v208, v208
	v_exp_f32_e32 v209, v209
	v_exp_f32_e32 v210, v210
	v_exp_f32_e32 v211, v211
	v_exp_f32_e32 v212, v212
	v_exp_f32_e32 v213, v213
	v_exp_f32_e32 v214, v214
	v_exp_f32_e32 v215, v215
	v_pk_add_f32 v[208:209], v[208:209], 1.0 op_sel_hi:[1,0]
	v_pk_add_f32 v[210:211], v[210:211], 1.0 op_sel_hi:[1,0]
	v_pk_add_f32 v[212:213], v[212:213], 1.0 op_sel_hi:[1,0]
	v_pk_add_f32 v[214:215], v[214:215], 1.0 op_sel_hi:[1,0]
	v_log_f32_e32 v208, v208
	v_log_f32_e32 v209, v209
	v_log_f32_e32 v210, v210
	v_log_f32_e32 v211, v211
	v_log_f32_e32 v212, v212
	v_log_f32_e32 v213, v213
	v_log_f32_e32 v214, v214
	v_log_f32_e32 v215, v215
	v_pk_mul_f32 v[216:217], v[208:209], s[94:95] op_sel:[0,1] op_sel_hi:[1,1]
	v_pk_mul_f32 v[218:219], v[210:211], s[94:95] op_sel:[0,1] op_sel_hi:[1,1]
	v_pk_mul_f32 v[220:221], v[212:213], s[94:95] op_sel:[0,1] op_sel_hi:[1,1]
	v_pk_mul_f32 v[222:223], v[214:215], s[94:95] op_sel:[0,1] op_sel_hi:[1,1]
	v_pk_fma_f32 v[216:217], v[208:209], s[94:95], v[216:217] op_sel:[0,1,0] op_sel_hi:[1,1,1] neg_lo:[0,0,1] neg_hi:[0,0,1]
	v_pk_fma_f32 v[218:219], v[210:211], s[94:95], v[218:219] op_sel:[0,1,0] op_sel_hi:[1,1,1] neg_lo:[0,0,1] neg_hi:[0,0,1]
	v_pk_fma_f32 v[220:221], v[212:213], s[94:95], v[220:221] op_sel:[0,1,0] op_sel_hi:[1,1,1] neg_lo:[0,0,1] neg_hi:[0,0,1]
	v_pk_fma_f32 v[222:223], v[214:215], s[94:95], v[222:223] op_sel:[0,1,0] op_sel_hi:[1,1,1] neg_lo:[0,0,1] neg_hi:[0,0,1]
	v_pk_fma_f32 v[216:217], v[208:209], s[94:95], v[216:217] op_sel_hi:[1,0,1]
	v_pk_fma_f32 v[218:219], v[210:211], s[94:95], v[218:219] op_sel_hi:[1,0,1]
	v_pk_fma_f32 v[220:221], v[212:213], s[94:95], v[220:221] op_sel_hi:[1,0,1]
	v_pk_fma_f32 v[222:223], v[214:215], s[94:95], v[222:223] op_sel_hi:[1,0,1]
	v_pk_fma_f32 v[216:217], v[208:209], s[94:95], v[216:217] op_sel:[0,1,0] op_sel_hi:[1,1,1]
	v_pk_fma_f32 v[218:219], v[210:211], s[94:95], v[218:219] op_sel:[0,1,0] op_sel_hi:[1,1,1]
	v_pk_fma_f32 v[220:221], v[212:213], s[94:95], v[220:221] op_sel:[0,1,0] op_sel_hi:[1,1,1]
	v_pk_fma_f32 v[222:223], v[214:215], s[94:95], v[222:223] op_sel:[0,1,0] op_sel_hi:[1,1,1]
	v_pk_add_f32 v[200:201], v[200:201], v[216:217] neg_lo:[0,1] neg_hi:[0,1]
	v_pk_add_f32 v[202:203], v[202:203], v[218:219] neg_lo:[0,1] neg_hi:[0,1]
	v_pk_add_f32 v[204:205], v[204:205], v[220:221] neg_lo:[0,1] neg_hi:[0,1]
	v_pk_add_f32 v[206:207], v[206:207], v[222:223] neg_lo:[0,1] neg_hi:[0,1]
	v_pk_mul_f32 v[184:185], v[200:201], s[96:97] op_sel_hi:[1,0]
	v_pk_mul_f32 v[186:187], v[202:203], s[96:97] op_sel_hi:[1,0]
	v_pk_mul_f32 v[188:189], v[204:205], s[96:97] op_sel_hi:[1,0]
	v_pk_mul_f32 v[190:191], v[206:207], s[96:97] op_sel_hi:[1,0]
	v_pk_add_f32 v[192:193], v[192:193], v[178:179] op_sel_hi:[1,0]
	v_pk_add_f32 v[194:195], v[194:195], v[178:179] op_sel_hi:[1,0]
	v_pk_add_f32 v[196:197], v[196:197], v[178:179] op_sel:[0,1] op_sel_hi:[1,1]
	v_pk_add_f32 v[198:199], v[198:199], v[178:179] op_sel:[0,1] op_sel_hi:[1,1]
	v_min_f32_e32 v200, 0, v192
	v_min_f32_e32 v201, 0, v193
	v_min_f32_e32 v202, 0, v194
	v_min_f32_e32 v203, 0, v195
	v_min_f32_e32 v204, 0, v196
	v_min_f32_e32 v205, 0, v197
	v_min_f32_e32 v206, 0, v198
	v_min_f32_e32 v207, 0, v199
	v_mul_f32_e64 v208, |v192|, s93
	v_mul_f32_e64 v209, |v193|, s93
	v_mul_f32_e64 v210, |v194|, s93
	v_mul_f32_e64 v211, |v195|, s93
	v_mul_f32_e64 v212, |v196|, s93
	v_mul_f32_e64 v213, |v197|, s93
	v_mul_f32_e64 v214, |v198|, s93
	v_mul_f32_e64 v215, |v199|, s93
	v_exp_f32_e32 v208, v208
	v_exp_f32_e32 v209, v209
	v_exp_f32_e32 v210, v210
	v_exp_f32_e32 v211, v211
	v_exp_f32_e32 v212, v212
	v_exp_f32_e32 v213, v213
	v_exp_f32_e32 v214, v214
	v_exp_f32_e32 v215, v215
	v_pk_add_f32 v[208:209], v[208:209], 1.0 op_sel_hi:[1,0]
	v_pk_add_f32 v[210:211], v[210:211], 1.0 op_sel_hi:[1,0]
	v_pk_add_f32 v[212:213], v[212:213], 1.0 op_sel_hi:[1,0]
	v_pk_add_f32 v[214:215], v[214:215], 1.0 op_sel_hi:[1,0]
	v_log_f32_e32 v208, v208
	v_log_f32_e32 v209, v209
	v_log_f32_e32 v210, v210
	v_log_f32_e32 v211, v211
	v_log_f32_e32 v212, v212
	v_log_f32_e32 v213, v213
	v_log_f32_e32 v214, v214
	v_log_f32_e32 v215, v215
	v_pk_mul_f32 v[216:217], v[208:209], s[94:95] op_sel:[0,1] op_sel_hi:[1,1]
	v_pk_mul_f32 v[218:219], v[210:211], s[94:95] op_sel:[0,1] op_sel_hi:[1,1]
	v_pk_mul_f32 v[220:221], v[212:213], s[94:95] op_sel:[0,1] op_sel_hi:[1,1]
	v_pk_mul_f32 v[222:223], v[214:215], s[94:95] op_sel:[0,1] op_sel_hi:[1,1]
	v_pk_fma_f32 v[216:217], v[208:209], s[94:95], v[216:217] op_sel:[0,1,0] op_sel_hi:[1,1,1] neg_lo:[0,0,1] neg_hi:[0,0,1]
; __device__ __forceinline__ void store_rm4(u16* dst, size_t ld, int row0, int c, float v0, float v1, float v2, float v3, bool odd) {
;   {
;     float s = odd ? v0 : v1, r = dpp_swap1(s);
;     float lo = odd ? r : v0, hi = odd ? v1 : r;
;     *(unsigned*)(dst + (size_t)(row0 + (odd ? 1 : 0)) * ld + (c - (odd ? 1 : 0))) = pack2(lo, hi);
;   }
;   {
;     float s = odd ? v2 : v3, r = dpp_swap1(s);
;     float lo = odd ? r : v2, hi = odd ? v3 : r;
;     *(unsigned*)(dst + (size_t)(row0 + 2 + (odd ? 1 : 0)) * ld + (c - (odd ? 1 : 0))) = pack2(lo, hi);
;   }
;   __device__ __forceinline__ void operator()(f32x4 (&acc)[2][2][4][2], int brow, int bcol, int wr, int wc, int fr, int fq) const {
;     ...
;             for (int bj = 0; bj < 2; ++bj)
; #pragma unroll
;               for (int n = 0; n < 2; ++n) {
;                 f32x4 z4 = {0.f, 0.f, 0.f, 0.f};
;                 z4 = __builtin_amdgcn_mfma_f32_16x16x16bf16_1k(af, bfr[bj][n], z4, 0, 0, 0);
;                 int c = bj * 128 + wc * 32 + n * 16 + fr;
;                 float bb = bias[c];
;                 float ls[4];
; #pragma unroll
;                 for (int j = 0; j < 4; ++j) {
;                   float z = z4[j] + bb;
;                   ls[j] = (fminf(z, 0.f) - __logf(1.f + __expf(-fabsf(z)))) * (1.f / 16.f);
;                 }
;                 store_rm4(dst, 256, row0, c, ls[0], ls[1], ls[2], ls[3], fr & 1);
;               }
	v_pk_fma_f32 v[218:219], v[210:211], s[94:95], v[218:219] op_sel:[0,1,0] op_sel_hi:[1,1,1] neg_lo:[0,0,1] neg_hi:[0,0,1]
	v_pk_fma_f32 v[220:221], v[212:213], s[94:95], v[220:221] op_sel:[0,1,0] op_sel_hi:[1,1,1] neg_lo:[0,0,1] neg_hi:[0,0,1]
	v_pk_fma_f32 v[222:223], v[214:215], s[94:95], v[222:223] op_sel:[0,1,0] op_sel_hi:[1,1,1] neg_lo:[0,0,1] neg_hi:[0,0,1]
	v_pk_fma_f32 v[216:217], v[208:209], s[94:95], v[216:217] op_sel_hi:[1,0,1]
	v_pk_fma_f32 v[218:219], v[210:211], s[94:95], v[218:219] op_sel_hi:[1,0,1]
	v_pk_fma_f32 v[220:221], v[212:213], s[94:95], v[220:221] op_sel_hi:[1,0,1]
	v_pk_fma_f32 v[222:223], v[214:215], s[94:95], v[222:223] op_sel_hi:[1,0,1]
	v_pk_fma_f32 v[216:217], v[208:209], s[94:95], v[216:217] op_sel:[0,1,0] op_sel_hi:[1,1,1]
	v_pk_fma_f32 v[218:219], v[210:211], s[94:95], v[218:219] op_sel:[0,1,0] op_sel_hi:[1,1,1]
	v_pk_fma_f32 v[220:221], v[212:213], s[94:95], v[220:221] op_sel:[0,1,0] op_sel_hi:[1,1,1]
	v_pk_fma_f32 v[222:223], v[214:215], s[94:95], v[222:223] op_sel:[0,1,0] op_sel_hi:[1,1,1]
	v_pk_add_f32 v[200:201], v[200:201], v[216:217] neg_lo:[0,1] neg_hi:[0,1]
	v_pk_add_f32 v[202:203], v[202:203], v[218:219] neg_lo:[0,1] neg_hi:[0,1]
	v_pk_add_f32 v[204:205], v[204:205], v[220:221] neg_lo:[0,1] neg_hi:[0,1]
	v_pk_add_f32 v[206:207], v[206:207], v[222:223] neg_lo:[0,1] neg_hi:[0,1]
	v_pk_mul_f32 v[192:193], v[200:201], s[96:97] op_sel_hi:[1,0]
	v_pk_mul_f32 v[194:195], v[202:203], s[96:97] op_sel_hi:[1,0]
	v_pk_mul_f32 v[196:197], v[204:205], s[96:97] op_sel_hi:[1,0]
	v_pk_mul_f32 v[198:199], v[206:207], s[96:97] op_sel_hi:[1,0]
	v_cvt_pk_bf16_f32 v208, v184, v185
	v_cvt_pk_bf16_f32 v209, v186, v187
	v_cvt_pk_bf16_f32 v210, v188, v189
	v_cvt_pk_bf16_f32 v211, v190, v191
	v_cvt_pk_bf16_f32 v212, v192, v193
	v_cvt_pk_bf16_f32 v213, v194, v195
	v_cvt_pk_bf16_f32 v214, v196, v197
	v_cvt_pk_bf16_f32 v215, v198, v199
	v_mov_b32_dpp v216, v208 quad_perm:[1,0,3,2] row_mask:0xf bank_mask:0xf bound_ctrl:1
	v_mov_b32_dpp v217, v209 quad_perm:[1,0,3,2] row_mask:0xf bank_mask:0xf bound_ctrl:1
	v_mov_b32_dpp v218, v210 quad_perm:[1,0,3,2] row_mask:0xf bank_mask:0xf bound_ctrl:1
	v_mov_b32_dpp v219, v211 quad_perm:[1,0,3,2] row_mask:0xf bank_mask:0xf bound_ctrl:1
	v_mov_b32_dpp v220, v212 quad_perm:[1,0,3,2] row_mask:0xf bank_mask:0xf bound_ctrl:1
	v_mov_b32_dpp v221, v213 quad_perm:[1,0,3,2] row_mask:0xf bank_mask:0xf bound_ctrl:1
	v_mov_b32_dpp v222, v214 quad_perm:[1,0,3,2] row_mask:0xf bank_mask:0xf bound_ctrl:1
	v_mov_b32_dpp v223, v215 quad_perm:[1,0,3,2] row_mask:0xf bank_mask:0xf bound_ctrl:1
	v_perm_b32 v208, v216, v208, v164
	v_perm_b32 v209, v217, v209, v164
	v_perm_b32 v210, v218, v210, v164
	v_perm_b32 v211, v219, v211, v164
	v_perm_b32 v212, v220, v212, v164
	v_perm_b32 v213, v221, v213, v164
	v_perm_b32 v214, v222, v214, v164
	v_perm_b32 v215, v223, v215, v164
	global_store_dword v167, v208, s[8:9]
	global_store_dword v167, v209, s[8:9] offset:1024
	global_store_dword v167, v210, s[8:9] offset:32
	global_store_dword v167, v211, s[8:9] offset:1056
	global_store_dword v167, v212, s[8:9] offset:256
	global_store_dword v167, v213, s[8:9] offset:1280
	global_store_dword v167, v214, s[8:9] offset:288
	global_store_dword v167, v215, s[8:9] offset:1312
	ds_read_b64 v[180:181], v160 offset:59392
	v_add_u32_e32 v167, 0x14000, v163
	s_waitcnt lgkmcnt(0)
	v_mfma_f32_16x16x16_bf16 v[184:187], v[180:181], v[168:169], 0
	v_mfma_f32_16x16x16_bf16 v[188:191], v[180:181], v[170:171], 0
	v_mfma_f32_16x16x16_bf16 v[192:195], v[180:181], v[172:173], 0
	v_mfma_f32_16x16x16_bf16 v[196:199], v[180:181], v[174:175], 0
	s_nop 7
	s_nop 1
	v_pk_add_f32 v[184:185], v[184:185], v[176:177] op_sel_hi:[1,0]
	v_pk_add_f32 v[186:187], v[186:187], v[176:177] op_sel_hi:[1,0]
	v_pk_add_f32 v[188:189], v[188:189], v[176:177] op_sel:[0,1] op_sel_hi:[1,1]
	v_pk_add_f32 v[190:191], v[190:191], v[176:177] op_sel:[0,1] op_sel_hi:[1,1]
	v_min_f32_e32 v200, 0, v184
	v_min_f32_e32 v201, 0, v185
	v_min_f32_e32 v202, 0, v186
	v_min_f32_e32 v203, 0, v187
	v_min_f32_e32 v204, 0, v188
	v_min_f32_e32 v205, 0, v189
	v_min_f32_e32 v206, 0, v190
	v_min_f32_e32 v207, 0, v191
	v_mul_f32_e64 v208, |v184|, s93
	v_mul_f32_e64 v209, |v185|, s93
	v_mul_f32_e64 v210, |v186|, s93
	v_mul_f32_e64 v211, |v187|, s93
	v_mul_f32_e64 v212, |v188|, s93
	v_mul_f32_e64 v213, |v189|, s93
	v_mul_f32_e64 v214, |v190|, s93
	v_mul_f32_e64 v215, |v191|, s93
	v_exp_f32_e32 v208, v208
	v_exp_f32_e32 v209, v209
	v_exp_f32_e32 v210, v210
	v_exp_f32_e32 v211, v211
	v_exp_f32_e32 v212, v212
	v_exp_f32_e32 v213, v213
	v_exp_f32_e32 v214, v214
	v_exp_f32_e32 v215, v215
	v_pk_add_f32 v[208:209], v[208:209], 1.0 op_sel_hi:[1,0]
	v_pk_add_f32 v[210:211], v[210:211], 1.0 op_sel_hi:[1,0]
	v_pk_add_f32 v[212:213], v[212:213], 1.0 op_sel_hi:[1,0]
	v_pk_add_f32 v[214:215], v[214:215], 1.0 op_sel_hi:[1,0]
	v_log_f32_e32 v208, v208
	v_log_f32_e32 v209, v209
	v_log_f32_e32 v210, v210
	v_log_f32_e32 v211, v211
	v_log_f32_e32 v212, v212
	v_log_f32_e32 v213, v213
	v_log_f32_e32 v214, v214
	v_log_f32_e32 v215, v215
	v_pk_mul_f32 v[216:217], v[208:209], s[94:95] op_sel:[0,1] op_sel_hi:[1,1]
	v_pk_mul_f32 v[218:219], v[210:211], s[94:95] op_sel:[0,1] op_sel_hi:[1,1]
	v_pk_mul_f32 v[220:221], v[212:213], s[94:95] op_sel:[0,1] op_sel_hi:[1,1]
	v_pk_mul_f32 v[222:223], v[214:215], s[94:95] op_sel:[0,1] op_sel_hi:[1,1]
	v_pk_fma_f32 v[216:217], v[208:209], s[94:95], v[216:217] op_sel:[0,1,0] op_sel_hi:[1,1,1] neg_lo:[0,0,1] neg_hi:[0,0,1]
	v_pk_fma_f32 v[218:219], v[210:211], s[94:95], v[218:219] op_sel:[0,1,0] op_sel_hi:[1,1,1] neg_lo:[0,0,1] neg_hi:[0,0,1]
; __device__ __forceinline__ void store_rm4(u16* dst, size_t ld, int row0, int c, float v0, float v1, float v2, float v3, bool odd) {
;   {
;     float s = odd ? v0 : v1, r = dpp_swap1(s);
;     float lo = odd ? r : v0, hi = odd ? v1 : r;
;     *(unsigned*)(dst + (size_t)(row0 + (odd ? 1 : 0)) * ld + (c - (odd ? 1 : 0))) = pack2(lo, hi);
;   }
;   {
;     float s = odd ? v2 : v3, r = dpp_swap1(s);
;     float lo = odd ? r : v2, hi = odd ? v3 : r;
;     *(unsigned*)(dst + (size_t)(row0 + 2 + (odd ? 1 : 0)) * ld + (c - (odd ? 1 : 0))) = pack2(lo, hi);
;   }
;   __device__ __forceinline__ void operator()(f32x4 (&acc)[2][2][4][2], int brow, int bcol, int wr, int wc, int fr, int fq) const {
;     ...
;             for (int bj = 0; bj < 2; ++bj)
; #pragma unroll
;               for (int n = 0; n < 2; ++n) {
;                 f32x4 z4 = {0.f, 0.f, 0.f, 0.f};
;                 z4 = __builtin_amdgcn_mfma_f32_16x16x16bf16_1k(af, bfr[bj][n], z4, 0, 0, 0);
;                 int c = bj * 128 + wc * 32 + n * 16 + fr;
;                 float bb = bias[c];
;                 float ls[4];
; #pragma unroll
;                 for (int j = 0; j < 4; ++j) {
;                   float z = z4[j] + bb;
;                   ls[j] = (fminf(z, 0.f) - __logf(1.f + __expf(-fabsf(z)))) * (1.f / 16.f);
;                 }
;                 store_rm4(dst, 256, row0, c, ls[0], ls[1], ls[2], ls[3], fr & 1);
;               }
	v_pk_fma_f32 v[220:221], v[212:213], s[94:95], v[220:221] op_sel:[0,1,0] op_sel_hi:[1,1,1] neg_lo:[0,0,1] neg_hi:[0,0,1]
	v_pk_fma_f32 v[222:223], v[214:215], s[94:95], v[222:223] op_sel:[0,1,0] op_sel_hi:[1,1,1] neg_lo:[0,0,1] neg_hi:[0,0,1]
	v_pk_fma_f32 v[216:217], v[208:209], s[94:95], v[216:217] op_sel_hi:[1,0,1]
	v_pk_fma_f32 v[218:219], v[210:211], s[94:95], v[218:219] op_sel_hi:[1,0,1]
	v_pk_fma_f32 v[220:221], v[212:213], s[94:95], v[220:221] op_sel_hi:[1,0,1]
	v_pk_fma_f32 v[222:223], v[214:215], s[94:95], v[222:223] op_sel_hi:[1,0,1]
	v_pk_fma_f32 v[216:217], v[208:209], s[94:95], v[216:217] op_sel:[0,1,0] op_sel_hi:[1,1,1]
	v_pk_fma_f32 v[218:219], v[210:211], s[94:95], v[218:219] op_sel:[0,1,0] op_sel_hi:[1,1,1]
	v_pk_fma_f32 v[220:221], v[212:213], s[94:95], v[220:221] op_sel:[0,1,0] op_sel_hi:[1,1,1]
	v_pk_fma_f32 v[222:223], v[214:215], s[94:95], v[222:223] op_sel:[0,1,0] op_sel_hi:[1,1,1]
	v_pk_add_f32 v[200:201], v[200:201], v[216:217] neg_lo:[0,1] neg_hi:[0,1]
	v_pk_add_f32 v[202:203], v[202:203], v[218:219] neg_lo:[0,1] neg_hi:[0,1]
	v_pk_add_f32 v[204:205], v[204:205], v[220:221] neg_lo:[0,1] neg_hi:[0,1]
	v_pk_add_f32 v[206:207], v[206:207], v[222:223] neg_lo:[0,1] neg_hi:[0,1]
	v_pk_mul_f32 v[184:185], v[200:201], s[96:97] op_sel_hi:[1,0]
	v_pk_mul_f32 v[186:187], v[202:203], s[96:97] op_sel_hi:[1,0]
	v_pk_mul_f32 v[188:189], v[204:205], s[96:97] op_sel_hi:[1,0]
	v_pk_mul_f32 v[190:191], v[206:207], s[96:97] op_sel_hi:[1,0]
	v_pk_add_f32 v[192:193], v[192:193], v[178:179] op_sel_hi:[1,0]
	v_pk_add_f32 v[194:195], v[194:195], v[178:179] op_sel_hi:[1,0]
	v_pk_add_f32 v[196:197], v[196:197], v[178:179] op_sel:[0,1] op_sel_hi:[1,1]
	v_pk_add_f32 v[198:199], v[198:199], v[178:179] op_sel:[0,1] op_sel_hi:[1,1]
	v_min_f32_e32 v200, 0, v192
	v_min_f32_e32 v201, 0, v193
	v_min_f32_e32 v202, 0, v194
	v_min_f32_e32 v203, 0, v195
	v_min_f32_e32 v204, 0, v196
	v_min_f32_e32 v205, 0, v197
	v_min_f32_e32 v206, 0, v198
	v_min_f32_e32 v207, 0, v199
	v_mul_f32_e64 v208, |v192|, s93
	v_mul_f32_e64 v209, |v193|, s93
	v_mul_f32_e64 v210, |v194|, s93
	v_mul_f32_e64 v211, |v195|, s93
	v_mul_f32_e64 v212, |v196|, s93
	v_mul_f32_e64 v213, |v197|, s93
	v_mul_f32_e64 v214, |v198|, s93
	v_mul_f32_e64 v215, |v199|, s93
	v_exp_f32_e32 v208, v208
	v_exp_f32_e32 v209, v209
	v_exp_f32_e32 v210, v210
	v_exp_f32_e32 v211, v211
	v_exp_f32_e32 v212, v212
	v_exp_f32_e32 v213, v213
	v_exp_f32_e32 v214, v214
	v_exp_f32_e32 v215, v215
	v_pk_add_f32 v[208:209], v[208:209], 1.0 op_sel_hi:[1,0]
	v_pk_add_f32 v[210:211], v[210:211], 1.0 op_sel_hi:[1,0]
	v_pk_add_f32 v[212:213], v[212:213], 1.0 op_sel_hi:[1,0]
	v_pk_add_f32 v[214:215], v[214:215], 1.0 op_sel_hi:[1,0]
	v_log_f32_e32 v208, v208
	v_log_f32_e32 v209, v209
	v_log_f32_e32 v210, v210
	v_log_f32_e32 v211, v211
	v_log_f32_e32 v212, v212
	v_log_f32_e32 v213, v213
	v_log_f32_e32 v214, v214
	v_log_f32_e32 v215, v215
	v_pk_mul_f32 v[216:217], v[208:209], s[94:95] op_sel:[0,1] op_sel_hi:[1,1]
	v_pk_mul_f32 v[218:219], v[210:211], s[94:95] op_sel:[0,1] op_sel_hi:[1,1]
	v_pk_mul_f32 v[220:221], v[212:213], s[94:95] op_sel:[0,1] op_sel_hi:[1,1]
	v_pk_mul_f32 v[222:223], v[214:215], s[94:95] op_sel:[0,1] op_sel_hi:[1,1]
	v_pk_fma_f32 v[216:217], v[208:209], s[94:95], v[216:217] op_sel:[0,1,0] op_sel_hi:[1,1,1] neg_lo:[0,0,1] neg_hi:[0,0,1]
	v_pk_fma_f32 v[218:219], v[210:211], s[94:95], v[218:219] op_sel:[0,1,0] op_sel_hi:[1,1,1] neg_lo:[0,0,1] neg_hi:[0,0,1]
	v_pk_fma_f32 v[220:221], v[212:213], s[94:95], v[220:221] op_sel:[0,1,0] op_sel_hi:[1,1,1] neg_lo:[0,0,1] neg_hi:[0,0,1]
	v_pk_fma_f32 v[222:223], v[214:215], s[94:95], v[222:223] op_sel:[0,1,0] op_sel_hi:[1,1,1] neg_lo:[0,0,1] neg_hi:[0,0,1]
	v_pk_fma_f32 v[216:217], v[208:209], s[94:95], v[216:217] op_sel_hi:[1,0,1]
	v_pk_fma_f32 v[218:219], v[210:211], s[94:95], v[218:219] op_sel_hi:[1,0,1]
	v_pk_fma_f32 v[220:221], v[212:213], s[94:95], v[220:221] op_sel_hi:[1,0,1]
	v_pk_fma_f32 v[222:223], v[214:215], s[94:95], v[222:223] op_sel_hi:[1,0,1]
	v_pk_fma_f32 v[216:217], v[208:209], s[94:95], v[216:217] op_sel:[0,1,0] op_sel_hi:[1,1,1]
	v_pk_fma_f32 v[218:219], v[210:211], s[94:95], v[218:219] op_sel:[0,1,0] op_sel_hi:[1,1,1]
	v_pk_fma_f32 v[220:221], v[212:213], s[94:95], v[220:221] op_sel:[0,1,0] op_sel_hi:[1,1,1]
	v_pk_fma_f32 v[222:223], v[214:215], s[94:95], v[222:223] op_sel:[0,1,0] op_sel_hi:[1,1,1]
	v_pk_add_f32 v[200:201], v[200:201], v[216:217] neg_lo:[0,1] neg_hi:[0,1]
	v_pk_add_f32 v[202:203], v[202:203], v[218:219] neg_lo:[0,1] neg_hi:[0,1]
	v_pk_add_f32 v[204:205], v[204:205], v[220:221] neg_lo:[0,1] neg_hi:[0,1]
	v_pk_add_f32 v[206:207], v[206:207], v[222:223] neg_lo:[0,1] neg_hi:[0,1]
	v_pk_mul_f32 v[192:193], v[200:201], s[96:97] op_sel_hi:[1,0]
	v_pk_mul_f32 v[194:195], v[202:203], s[96:97] op_sel_hi:[1,0]
	v_pk_mul_f32 v[196:197], v[204:205], s[96:97] op_sel_hi:[1,0]
	v_pk_mul_f32 v[198:199], v[206:207], s[96:97] op_sel_hi:[1,0]
	v_cvt_pk_bf16_f32 v208, v184, v185
	v_cvt_pk_bf16_f32 v209, v186, v187
	v_cvt_pk_bf16_f32 v210, v188, v189
	v_cvt_pk_bf16_f32 v211, v190, v191
	v_cvt_pk_bf16_f32 v212, v192, v193
	v_cvt_pk_bf16_f32 v213, v194, v195
	v_cvt_pk_bf16_f32 v214, v196, v197
	v_cvt_pk_bf16_f32 v215, v198, v199
	v_mov_b32_dpp v216, v208 quad_perm:[1,0,3,2] row_mask:0xf bank_mask:0xf bound_ctrl:1
	v_mov_b32_dpp v217, v209 quad_perm:[1,0,3,2] row_mask:0xf bank_mask:0xf bound_ctrl:1
	v_mov_b32_dpp v218, v210 quad_perm:[1,0,3,2] row_mask:0xf bank_mask:0xf bound_ctrl:1
	v_mov_b32_dpp v219, v211 quad_perm:[1,0,3,2] row_mask:0xf bank_mask:0xf bound_ctrl:1
	v_mov_b32_dpp v220, v212 quad_perm:[1,0,3,2] row_mask:0xf bank_mask:0xf bound_ctrl:1
	v_mov_b32_dpp v221, v213 quad_perm:[1,0,3,2] row_mask:0xf bank_mask:0xf bound_ctrl:1
	v_mov_b32_dpp v222, v214 quad_perm:[1,0,3,2] row_mask:0xf bank_mask:0xf bound_ctrl:1
	v_mov_b32_dpp v223, v215 quad_perm:[1,0,3,2] row_mask:0xf bank_mask:0xf bound_ctrl:1
	v_perm_b32 v208, v216, v208, v164
	v_perm_b32 v209, v217, v209, v164
	v_perm_b32 v210, v218, v210, v164
	v_perm_b32 v211, v219, v211, v164
	v_perm_b32 v212, v220, v212, v164
	v_perm_b32 v213, v221, v213, v164
	v_perm_b32 v214, v222, v214, v164
	v_perm_b32 v215, v223, v215, v164
	global_store_dword v167, v208, s[8:9]
	global_store_dword v167, v209, s[8:9] offset:1024
	global_store_dword v167, v210, s[8:9] offset:32
	global_store_dword v167, v211, s[8:9] offset:1056
	global_store_dword v167, v212, s[8:9] offset:256
	global_store_dword v167, v213, s[8:9] offset:1280
	global_store_dword v167, v214, s[8:9] offset:288
	global_store_dword v167, v215, s[8:9] offset:1312
	ds_read_b64 v[180:181], v160 offset:60416
	v_add_u32_e32 v167, 0x16000, v163
	s_waitcnt lgkmcnt(0)
;   __device__ __forceinline__ void operator()(f32x4 (&acc)[2][2][4][2], int brow, int bcol, int wr, int wc, int fr, int fq) const {
;     ...
;             for (int bj = 0; bj < 2; ++bj)
; #pragma unroll
;               for (int n = 0; n < 2; ++n) {
;                 f32x4 z4 = {0.f, 0.f, 0.f, 0.f};
;                 z4 = __builtin_amdgcn_mfma_f32_16x16x16bf16_1k(af, bfr[bj][n], z4, 0, 0, 0);
;                 int c = bj * 128 + wc * 32 + n * 16 + fr;
;                 float bb = bias[c];
;                 float ls[4];
; #pragma unroll
;                 for (int j = 0; j < 4; ++j) {
;                   float z = z4[j] + bb;
;                   ls[j] = (fminf(z, 0.f) - __logf(1.f + __expf(-fabsf(z)))) * (1.f / 16.f);
;                 }
;                 store_rm4(dst, 256, row0, c, ls[0], ls[1], ls[2], ls[3], fr & 1);
;               }
	v_mfma_f32_16x16x16_bf16 v[184:187], v[180:181], v[168:169], 0
	v_mfma_f32_16x16x16_bf16 v[188:191], v[180:181], v[170:171], 0
	v_mfma_f32_16x16x16_bf16 v[192:195], v[180:181], v[172:173], 0
	v_mfma_f32_16x16x16_bf16 v[196:199], v[180:181], v[174:175], 0
	s_nop 7
	s_nop 1
	v_pk_add_f32 v[184:185], v[184:185], v[176:177] op_sel_hi:[1,0]
	v_pk_add_f32 v[186:187], v[186:187], v[176:177] op_sel_hi:[1,0]
	v_pk_add_f32 v[188:189], v[188:189], v[176:177] op_sel:[0,1] op_sel_hi:[1,1]
	v_pk_add_f32 v[190:191], v[190:191], v[176:177] op_sel:[0,1] op_sel_hi:[1,1]
	v_min_f32_e32 v200, 0, v184
	v_min_f32_e32 v201, 0, v185
	v_min_f32_e32 v202, 0, v186
	v_min_f32_e32 v203, 0, v187
	v_min_f32_e32 v204, 0, v188
	v_min_f32_e32 v205, 0, v189
	v_min_f32_e32 v206, 0, v190
	v_min_f32_e32 v207, 0, v191
	v_mul_f32_e64 v208, |v184|, s93
	v_mul_f32_e64 v209, |v185|, s93
	v_mul_f32_e64 v210, |v186|, s93
	v_mul_f32_e64 v211, |v187|, s93
	v_mul_f32_e64 v212, |v188|, s93
	v_mul_f32_e64 v213, |v189|, s93
	v_mul_f32_e64 v214, |v190|, s93
	v_mul_f32_e64 v215, |v191|, s93
	v_exp_f32_e32 v208, v208
	v_exp_f32_e32 v209, v209
	v_exp_f32_e32 v210, v210
	v_exp_f32_e32 v211, v211
	v_exp_f32_e32 v212, v212
	v_exp_f32_e32 v213, v213
	v_exp_f32_e32 v214, v214
	v_exp_f32_e32 v215, v215
	v_pk_add_f32 v[208:209], v[208:209], 1.0 op_sel_hi:[1,0]
	v_pk_add_f32 v[210:211], v[210:211], 1.0 op_sel_hi:[1,0]
	v_pk_add_f32 v[212:213], v[212:213], 1.0 op_sel_hi:[1,0]
	v_pk_add_f32 v[214:215], v[214:215], 1.0 op_sel_hi:[1,0]
	v_log_f32_e32 v208, v208
	v_log_f32_e32 v209, v209
	v_log_f32_e32 v210, v210
	v_log_f32_e32 v211, v211
	v_log_f32_e32 v212, v212
	v_log_f32_e32 v213, v213
	v_log_f32_e32 v214, v214
	v_log_f32_e32 v215, v215
	v_pk_mul_f32 v[216:217], v[208:209], s[94:95] op_sel:[0,1] op_sel_hi:[1,1]
	v_pk_mul_f32 v[218:219], v[210:211], s[94:95] op_sel:[0,1] op_sel_hi:[1,1]
	v_pk_mul_f32 v[220:221], v[212:213], s[94:95] op_sel:[0,1] op_sel_hi:[1,1]
	v_pk_mul_f32 v[222:223], v[214:215], s[94:95] op_sel:[0,1] op_sel_hi:[1,1]
	v_pk_fma_f32 v[216:217], v[208:209], s[94:95], v[216:217] op_sel:[0,1,0] op_sel_hi:[1,1,1] neg_lo:[0,0,1] neg_hi:[0,0,1]
	v_pk_fma_f32 v[218:219], v[210:211], s[94:95], v[218:219] op_sel:[0,1,0] op_sel_hi:[1,1,1] neg_lo:[0,0,1] neg_hi:[0,0,1]
	v_pk_fma_f32 v[220:221], v[212:213], s[94:95], v[220:221] op_sel:[0,1,0] op_sel_hi:[1,1,1] neg_lo:[0,0,1] neg_hi:[0,0,1]
	v_pk_fma_f32 v[222:223], v[214:215], s[94:95], v[222:223] op_sel:[0,1,0] op_sel_hi:[1,1,1] neg_lo:[0,0,1] neg_hi:[0,0,1]
	v_pk_fma_f32 v[216:217], v[208:209], s[94:95], v[216:217] op_sel_hi:[1,0,1]
	v_pk_fma_f32 v[218:219], v[210:211], s[94:95], v[218:219] op_sel_hi:[1,0,1]
	v_pk_fma_f32 v[220:221], v[212:213], s[94:95], v[220:221] op_sel_hi:[1,0,1]
	v_pk_fma_f32 v[222:223], v[214:215], s[94:95], v[222:223] op_sel_hi:[1,0,1]
	v_pk_fma_f32 v[216:217], v[208:209], s[94:95], v[216:217] op_sel:[0,1,0] op_sel_hi:[1,1,1]
	v_pk_fma_f32 v[218:219], v[210:211], s[94:95], v[218:219] op_sel:[0,1,0] op_sel_hi:[1,1,1]
	v_pk_fma_f32 v[220:221], v[212:213], s[94:95], v[220:221] op_sel:[0,1,0] op_sel_hi:[1,1,1]
	v_pk_fma_f32 v[222:223], v[214:215], s[94:95], v[222:223] op_sel:[0,1,0] op_sel_hi:[1,1,1]
	v_pk_add_f32 v[200:201], v[200:201], v[216:217] neg_lo:[0,1] neg_hi:[0,1]
	v_pk_add_f32 v[202:203], v[202:203], v[218:219] neg_lo:[0,1] neg_hi:[0,1]
	v_pk_add_f32 v[204:205], v[204:205], v[220:221] neg_lo:[0,1] neg_hi:[0,1]
	v_pk_add_f32 v[206:207], v[206:207], v[222:223] neg_lo:[0,1] neg_hi:[0,1]
	v_pk_mul_f32 v[184:185], v[200:201], s[96:97] op_sel_hi:[1,0]
	v_pk_mul_f32 v[186:187], v[202:203], s[96:97] op_sel_hi:[1,0]
	v_pk_mul_f32 v[188:189], v[204:205], s[96:97] op_sel_hi:[1,0]
	v_pk_mul_f32 v[190:191], v[206:207], s[96:97] op_sel_hi:[1,0]
	v_pk_add_f32 v[192:193], v[192:193], v[178:179] op_sel_hi:[1,0]
	v_pk_add_f32 v[194:195], v[194:195], v[178:179] op_sel_hi:[1,0]
	v_pk_add_f32 v[196:197], v[196:197], v[178:179] op_sel:[0,1] op_sel_hi:[1,1]
	v_pk_add_f32 v[198:199], v[198:199], v[178:179] op_sel:[0,1] op_sel_hi:[1,1]
	v_min_f32_e32 v200, 0, v192
	v_min_f32_e32 v201, 0, v193
	v_min_f32_e32 v202, 0, v194
	v_min_f32_e32 v203, 0, v195
	v_min_f32_e32 v204, 0, v196
	v_min_f32_e32 v205, 0, v197
	v_min_f32_e32 v206, 0, v198
	v_min_f32_e32 v207, 0, v199
	v_mul_f32_e64 v208, |v192|, s93
	v_mul_f32_e64 v209, |v193|, s93
	v_mul_f32_e64 v210, |v194|, s93
	v_mul_f32_e64 v211, |v195|, s93
	v_mul_f32_e64 v212, |v196|, s93
	v_mul_f32_e64 v213, |v197|, s93
	v_mul_f32_e64 v214, |v198|, s93
	v_mul_f32_e64 v215, |v199|, s93
	v_exp_f32_e32 v208, v208
	v_exp_f32_e32 v209, v209
	v_exp_f32_e32 v210, v210
	v_exp_f32_e32 v211, v211
	v_exp_f32_e32 v212, v212
	v_exp_f32_e32 v213, v213
	v_exp_f32_e32 v214, v214
	v_exp_f32_e32 v215, v215
	v_pk_add_f32 v[208:209], v[208:209], 1.0 op_sel_hi:[1,0]
	v_pk_add_f32 v[210:211], v[210:211], 1.0 op_sel_hi:[1,0]
	v_pk_add_f32 v[212:213], v[212:213], 1.0 op_sel_hi:[1,0]
	v_pk_add_f32 v[214:215], v[214:215], 1.0 op_sel_hi:[1,0]
	v_log_f32_e32 v208, v208
	v_log_f32_e32 v209, v209
	v_log_f32_e32 v210, v210
	v_log_f32_e32 v211, v211
	v_log_f32_e32 v212, v212
	v_log_f32_e32 v213, v213
	v_log_f32_e32 v214, v214
	v_log_f32_e32 v215, v215
	v_pk_mul_f32 v[216:217], v[208:209], s[94:95] op_sel:[0,1] op_sel_hi:[1,1]
	v_pk_mul_f32 v[218:219], v[210:211], s[94:95] op_sel:[0,1] op_sel_hi:[1,1]
	v_pk_mul_f32 v[220:221], v[212:213], s[94:95] op_sel:[0,1] op_sel_hi:[1,1]
	v_pk_mul_f32 v[222:223], v[214:215], s[94:95] op_sel:[0,1] op_sel_hi:[1,1]
	v_pk_fma_f32 v[216:217], v[208:209], s[94:95], v[216:217] op_sel:[0,1,0] op_sel_hi:[1,1,1] neg_lo:[0,0,1] neg_hi:[0,0,1]
;   __device__ __forceinline__ void operator()(f32x4 (&acc)[2][2][4][2], int brow, int bcol, int wr, int wc, int fr, int fq) const {
;     ...
;       for (int dir = 0; dir < 2; ++dir) {
;         s16x4 bfr[2][2];
; #pragma unroll
;         for (int bj = 0; bj < 2; ++bj)
; #pragma unroll
;           for (int n = 0; n < 2; ++n)
;             bfr[bj][n] = *(const s16x4*)(wgt + ((size_t)(dir * 256 + bj * 128 + wc * 32 + n * 16 + fr)) * 16 + fq * 4);
;         u16* dst = (u16*)(p.ws + (dir == 0 ? OFF_LAF : OFF_LAB));
;         const float* bias = dir == 0 ? p.bgf : p.bgb;
; #pragma unroll
;         for (int ai = 0; ai < 2; ++ai)
; #pragma unroll
;           for (int m = 0; m < 4; ++m) {
;             int rl = ai * 128 + wr * 64 + m * 16;
;             s16x4 af = *(const s16x4*)(glr + (rl + fr) * 32 + dir * 16 + fq * 4);
;             int row0 = brow + rl + fq * 4;
; #pragma unroll
;             for (int bj = 0; bj < 2; ++bj)
; #pragma unroll
;               for (int n = 0; n < 2; ++n) {
;                 f32x4 z4 = {0.f, 0.f, 0.f, 0.f};
;                 z4 = __builtin_amdgcn_mfma_f32_16x16x16bf16_1k(af, bfr[bj][n], z4, 0, 0, 0);
;                 int c = bj * 128 + wc * 32 + n * 16 + fr;
;                 float bb = bias[c];
;                 float ls[4];
; #pragma unroll
;                 for (int j = 0; j < 4; ++j) {
;                   float z = z4[j] + bb;
;                   ls[j] = (fminf(z, 0.f) - __logf(1.f + __expf(-fabsf(z)))) * (1.f / 16.f);
;                 }
;                 store_rm4(dst, 256, row0, c, ls[0], ls[1], ls[2], ls[3], fr & 1);
;               }
	v_pk_fma_f32 v[218:219], v[210:211], s[94:95], v[218:219] op_sel:[0,1,0] op_sel_hi:[1,1,1] neg_lo:[0,0,1] neg_hi:[0,0,1]
	v_pk_fma_f32 v[220:221], v[212:213], s[94:95], v[220:221] op_sel:[0,1,0] op_sel_hi:[1,1,1] neg_lo:[0,0,1] neg_hi:[0,0,1]
	v_pk_fma_f32 v[222:223], v[214:215], s[94:95], v[222:223] op_sel:[0,1,0] op_sel_hi:[1,1,1] neg_lo:[0,0,1] neg_hi:[0,0,1]
	v_pk_fma_f32 v[216:217], v[208:209], s[94:95], v[216:217] op_sel_hi:[1,0,1]
	v_pk_fma_f32 v[218:219], v[210:211], s[94:95], v[218:219] op_sel_hi:[1,0,1]
	v_pk_fma_f32 v[220:221], v[212:213], s[94:95], v[220:221] op_sel_hi:[1,0,1]
	v_pk_fma_f32 v[222:223], v[214:215], s[94:95], v[222:223] op_sel_hi:[1,0,1]
	v_pk_fma_f32 v[216:217], v[208:209], s[94:95], v[216:217] op_sel:[0,1,0] op_sel_hi:[1,1,1]
	v_pk_fma_f32 v[218:219], v[210:211], s[94:95], v[218:219] op_sel:[0,1,0] op_sel_hi:[1,1,1]
	v_pk_fma_f32 v[220:221], v[212:213], s[94:95], v[220:221] op_sel:[0,1,0] op_sel_hi:[1,1,1]
	v_pk_fma_f32 v[222:223], v[214:215], s[94:95], v[222:223] op_sel:[0,1,0] op_sel_hi:[1,1,1]
	v_pk_add_f32 v[200:201], v[200:201], v[216:217] neg_lo:[0,1] neg_hi:[0,1]
	v_pk_add_f32 v[202:203], v[202:203], v[218:219] neg_lo:[0,1] neg_hi:[0,1]
	v_pk_add_f32 v[204:205], v[204:205], v[220:221] neg_lo:[0,1] neg_hi:[0,1]
	v_pk_add_f32 v[206:207], v[206:207], v[222:223] neg_lo:[0,1] neg_hi:[0,1]
	v_pk_mul_f32 v[192:193], v[200:201], s[96:97] op_sel_hi:[1,0]
	v_pk_mul_f32 v[194:195], v[202:203], s[96:97] op_sel_hi:[1,0]
	v_pk_mul_f32 v[196:197], v[204:205], s[96:97] op_sel_hi:[1,0]
	v_pk_mul_f32 v[198:199], v[206:207], s[96:97] op_sel_hi:[1,0]
	v_cvt_pk_bf16_f32 v208, v184, v185
	v_cvt_pk_bf16_f32 v209, v186, v187
	v_cvt_pk_bf16_f32 v210, v188, v189
	v_cvt_pk_bf16_f32 v211, v190, v191
	v_cvt_pk_bf16_f32 v212, v192, v193
	v_cvt_pk_bf16_f32 v213, v194, v195
	v_cvt_pk_bf16_f32 v214, v196, v197
	v_cvt_pk_bf16_f32 v215, v198, v199
	v_mov_b32_dpp v216, v208 quad_perm:[1,0,3,2] row_mask:0xf bank_mask:0xf bound_ctrl:1
	v_mov_b32_dpp v217, v209 quad_perm:[1,0,3,2] row_mask:0xf bank_mask:0xf bound_ctrl:1
	v_mov_b32_dpp v218, v210 quad_perm:[1,0,3,2] row_mask:0xf bank_mask:0xf bound_ctrl:1
	v_mov_b32_dpp v219, v211 quad_perm:[1,0,3,2] row_mask:0xf bank_mask:0xf bound_ctrl:1
	v_mov_b32_dpp v220, v212 quad_perm:[1,0,3,2] row_mask:0xf bank_mask:0xf bound_ctrl:1
	v_mov_b32_dpp v221, v213 quad_perm:[1,0,3,2] row_mask:0xf bank_mask:0xf bound_ctrl:1
	v_mov_b32_dpp v222, v214 quad_perm:[1,0,3,2] row_mask:0xf bank_mask:0xf bound_ctrl:1
	v_mov_b32_dpp v223, v215 quad_perm:[1,0,3,2] row_mask:0xf bank_mask:0xf bound_ctrl:1
	v_perm_b32 v208, v216, v208, v164
	v_perm_b32 v209, v217, v209, v164
	v_perm_b32 v210, v218, v210, v164
	v_perm_b32 v211, v219, v211, v164
	v_perm_b32 v212, v220, v212, v164
	v_perm_b32 v213, v221, v213, v164
	v_perm_b32 v214, v222, v214, v164
	v_perm_b32 v215, v223, v215, v164
	global_store_dword v167, v208, s[8:9]
	global_store_dword v167, v209, s[8:9] offset:1024
	global_store_dword v167, v210, s[8:9] offset:32
	global_store_dword v167, v211, s[8:9] offset:1056
	global_store_dword v167, v212, s[8:9] offset:256
	global_store_dword v167, v213, s[8:9] offset:1280
	global_store_dword v167, v214, s[8:9] offset:288
	global_store_dword v167, v215, s[8:9] offset:1312
	s_add_u32 s4, s40, 0x2000
	s_addc_u32 s5, s41, 0
	s_add_u32 s8, s14, s0
	s_addc_u32 s9, s15, 0
	global_load_dwordx2 v[168:169], v161, s[4:5]
	global_load_dwordx2 v[170:171], v161, s[4:5] offset:512
	global_load_dwordx2 v[172:173], v224, s[4:5]
	global_load_dwordx2 v[174:175], v224, s[4:5] offset:512
	global_load_dword v176, v162, s[66:67]
	global_load_dword v177, v162, s[66:67] offset:64
	global_load_dword v178, v162, s[66:67] offset:512
	global_load_dword v179, v162, s[66:67] offset:576
	ds_read_b64 v[180:181], v160 offset:49184
	v_mov_b32_e32 v167, v163
	s_waitcnt vmcnt(0) lgkmcnt(0)
	v_mfma_f32_16x16x16_bf16 v[184:187], v[180:181], v[168:169], 0
	v_mfma_f32_16x16x16_bf16 v[188:191], v[180:181], v[170:171], 0
	v_mfma_f32_16x16x16_bf16 v[192:195], v[180:181], v[172:173], 0
	v_mfma_f32_16x16x16_bf16 v[196:199], v[180:181], v[174:175], 0
	s_nop 7
	s_nop 1
	v_pk_add_f32 v[184:185], v[184:185], v[176:177] op_sel_hi:[1,0]
	v_pk_add_f32 v[186:187], v[186:187], v[176:177] op_sel_hi:[1,0]
	v_pk_add_f32 v[188:189], v[188:189], v[176:177] op_sel:[0,1] op_sel_hi:[1,1]
	v_pk_add_f32 v[190:191], v[190:191], v[176:177] op_sel:[0,1] op_sel_hi:[1,1]
	v_min_f32_e32 v200, 0, v184
	v_min_f32_e32 v201, 0, v185
	v_min_f32_e32 v202, 0, v186
	v_min_f32_e32 v203, 0, v187
	v_min_f32_e32 v204, 0, v188
	v_min_f32_e32 v205, 0, v189
	v_min_f32_e32 v206, 0, v190
	v_min_f32_e32 v207, 0, v191
	v_mul_f32_e64 v208, |v184|, s93
	v_mul_f32_e64 v209, |v185|, s93
	v_mul_f32_e64 v210, |v186|, s93
	v_mul_f32_e64 v211, |v187|, s93
	v_mul_f32_e64 v212, |v188|, s93
	v_mul_f32_e64 v213, |v189|, s93
	v_mul_f32_e64 v214, |v190|, s93
	v_mul_f32_e64 v215, |v191|, s93
	v_exp_f32_e32 v208, v208
	v_exp_f32_e32 v209, v209
	v_exp_f32_e32 v210, v210
	v_exp_f32_e32 v211, v211
	v_exp_f32_e32 v212, v212
	v_exp_f32_e32 v213, v213
	v_exp_f32_e32 v214, v214
	v_exp_f32_e32 v215, v215
	v_pk_add_f32 v[208:209], v[208:209], 1.0 op_sel_hi:[1,0]
	v_pk_add_f32 v[210:211], v[210:211], 1.0 op_sel_hi:[1,0]
	v_pk_add_f32 v[212:213], v[212:213], 1.0 op_sel_hi:[1,0]
	v_pk_add_f32 v[214:215], v[214:215], 1.0 op_sel_hi:[1,0]
	v_log_f32_e32 v208, v208
	v_log_f32_e32 v209, v209
	v_log_f32_e32 v210, v210
	v_log_f32_e32 v211, v211
	v_log_f32_e32 v212, v212
	v_log_f32_e32 v213, v213
	v_log_f32_e32 v214, v214
	v_log_f32_e32 v215, v215
	v_pk_mul_f32 v[216:217], v[208:209], s[94:95] op_sel:[0,1] op_sel_hi:[1,1]
;   __device__ __forceinline__ void operator()(f32x4 (&acc)[2][2][4][2], int brow, int bcol, int wr, int wc, int fr, int fq) const {
;     ...
;             for (int bj = 0; bj < 2; ++bj)
; #pragma unroll
;               for (int n = 0; n < 2; ++n) {
;                 f32x4 z4 = {0.f, 0.f, 0.f, 0.f};
;                 z4 = __builtin_amdgcn_mfma_f32_16x16x16bf16_1k(af, bfr[bj][n], z4, 0, 0, 0);
;                 int c = bj * 128 + wc * 32 + n * 16 + fr;
;                 float bb = bias[c];
;                 float ls[4];
; #pragma unroll
;                 for (int j = 0; j < 4; ++j) {
;                   float z = z4[j] + bb;
;                   ls[j] = (fminf(z, 0.f) - __logf(1.f + __expf(-fabsf(z)))) * (1.f / 16.f);
;                 }
;                 store_rm4(dst, 256, row0, c, ls[0], ls[1], ls[2], ls[3], fr & 1);
;               }
	v_pk_mul_f32 v[218:219], v[210:211], s[94:95] op_sel:[0,1] op_sel_hi:[1,1]
	v_pk_mul_f32 v[220:221], v[212:213], s[94:95] op_sel:[0,1] op_sel_hi:[1,1]
	v_pk_mul_f32 v[222:223], v[214:215], s[94:95] op_sel:[0,1] op_sel_hi:[1,1]
	v_pk_fma_f32 v[216:217], v[208:209], s[94:95], v[216:217] op_sel:[0,1,0] op_sel_hi:[1,1,1] neg_lo:[0,0,1] neg_hi:[0,0,1]
	v_pk_fma_f32 v[218:219], v[210:211], s[94:95], v[218:219] op_sel:[0,1,0] op_sel_hi:[1,1,1] neg_lo:[0,0,1] neg_hi:[0,0,1]
	v_pk_fma_f32 v[220:221], v[212:213], s[94:95], v[220:221] op_sel:[0,1,0] op_sel_hi:[1,1,1] neg_lo:[0,0,1] neg_hi:[0,0,1]
	v_pk_fma_f32 v[222:223], v[214:215], s[94:95], v[222:223] op_sel:[0,1,0] op_sel_hi:[1,1,1] neg_lo:[0,0,1] neg_hi:[0,0,1]
	v_pk_fma_f32 v[216:217], v[208:209], s[94:95], v[216:217] op_sel_hi:[1,0,1]
	v_pk_fma_f32 v[218:219], v[210:211], s[94:95], v[218:219] op_sel_hi:[1,0,1]
	v_pk_fma_f32 v[220:221], v[212:213], s[94:95], v[220:221] op_sel_hi:[1,0,1]
	v_pk_fma_f32 v[222:223], v[214:215], s[94:95], v[222:223] op_sel_hi:[1,0,1]
	v_pk_fma_f32 v[216:217], v[208:209], s[94:95], v[216:217] op_sel:[0,1,0] op_sel_hi:[1,1,1]
	v_pk_fma_f32 v[218:219], v[210:211], s[94:95], v[218:219] op_sel:[0,1,0] op_sel_hi:[1,1,1]
	v_pk_fma_f32 v[220:221], v[212:213], s[94:95], v[220:221] op_sel:[0,1,0] op_sel_hi:[1,1,1]
	v_pk_fma_f32 v[222:223], v[214:215], s[94:95], v[222:223] op_sel:[0,1,0] op_sel_hi:[1,1,1]
	v_pk_add_f32 v[200:201], v[200:201], v[216:217] neg_lo:[0,1] neg_hi:[0,1]
	v_pk_add_f32 v[202:203], v[202:203], v[218:219] neg_lo:[0,1] neg_hi:[0,1]
	v_pk_add_f32 v[204:205], v[204:205], v[220:221] neg_lo:[0,1] neg_hi:[0,1]
	v_pk_add_f32 v[206:207], v[206:207], v[222:223] neg_lo:[0,1] neg_hi:[0,1]
	v_pk_mul_f32 v[184:185], v[200:201], s[96:97] op_sel_hi:[1,0]
	v_pk_mul_f32 v[186:187], v[202:203], s[96:97] op_sel_hi:[1,0]
	v_pk_mul_f32 v[188:189], v[204:205], s[96:97] op_sel_hi:[1,0]
	v_pk_mul_f32 v[190:191], v[206:207], s[96:97] op_sel_hi:[1,0]
	v_pk_add_f32 v[192:193], v[192:193], v[178:179] op_sel_hi:[1,0]
	v_pk_add_f32 v[194:195], v[194:195], v[178:179] op_sel_hi:[1,0]
	v_pk_add_f32 v[196:197], v[196:197], v[178:179] op_sel:[0,1] op_sel_hi:[1,1]
	v_pk_add_f32 v[198:199], v[198:199], v[178:179] op_sel:[0,1] op_sel_hi:[1,1]
	v_min_f32_e32 v200, 0, v192
	v_min_f32_e32 v201, 0, v193
	v_min_f32_e32 v202, 0, v194
	v_min_f32_e32 v203, 0, v195
	v_min_f32_e32 v204, 0, v196
	v_min_f32_e32 v205, 0, v197
	v_min_f32_e32 v206, 0, v198
	v_min_f32_e32 v207, 0, v199
	v_mul_f32_e64 v208, |v192|, s93
	v_mul_f32_e64 v209, |v193|, s93
	v_mul_f32_e64 v210, |v194|, s93
	v_mul_f32_e64 v211, |v195|, s93
	v_mul_f32_e64 v212, |v196|, s93
	v_mul_f32_e64 v213, |v197|, s93
	v_mul_f32_e64 v214, |v198|, s93
	v_mul_f32_e64 v215, |v199|, s93
	v_exp_f32_e32 v208, v208
	v_exp_f32_e32 v209, v209
	v_exp_f32_e32 v210, v210
	v_exp_f32_e32 v211, v211
	v_exp_f32_e32 v212, v212
	v_exp_f32_e32 v213, v213
	v_exp_f32_e32 v214, v214
	v_exp_f32_e32 v215, v215
	v_pk_add_f32 v[208:209], v[208:209], 1.0 op_sel_hi:[1,0]
	v_pk_add_f32 v[210:211], v[210:211], 1.0 op_sel_hi:[1,0]
	v_pk_add_f32 v[212:213], v[212:213], 1.0 op_sel_hi:[1,0]
	v_pk_add_f32 v[214:215], v[214:215], 1.0 op_sel_hi:[1,0]
	v_log_f32_e32 v208, v208
	v_log_f32_e32 v209, v209
	v_log_f32_e32 v210, v210
	v_log_f32_e32 v211, v211
	v_log_f32_e32 v212, v212
	v_log_f32_e32 v213, v213
	v_log_f32_e32 v214, v214
	v_log_f32_e32 v215, v215
	v_pk_mul_f32 v[216:217], v[208:209], s[94:95] op_sel:[0,1] op_sel_hi:[1,1]
	v_pk_mul_f32 v[218:219], v[210:211], s[94:95] op_sel:[0,1] op_sel_hi:[1,1]
	v_pk_mul_f32 v[220:221], v[212:213], s[94:95] op_sel:[0,1] op_sel_hi:[1,1]
	v_pk_mul_f32 v[222:223], v[214:215], s[94:95] op_sel:[0,1] op_sel_hi:[1,1]
	v_pk_fma_f32 v[216:217], v[208:209], s[94:95], v[216:217] op_sel:[0,1,0] op_sel_hi:[1,1,1] neg_lo:[0,0,1] neg_hi:[0,0,1]
	v_pk_fma_f32 v[218:219], v[210:211], s[94:95], v[218:219] op_sel:[0,1,0] op_sel_hi:[1,1,1] neg_lo:[0,0,1] neg_hi:[0,0,1]
	v_pk_fma_f32 v[220:221], v[212:213], s[94:95], v[220:221] op_sel:[0,1,0] op_sel_hi:[1,1,1] neg_lo:[0,0,1] neg_hi:[0,0,1]
	v_pk_fma_f32 v[222:223], v[214:215], s[94:95], v[222:223] op_sel:[0,1,0] op_sel_hi:[1,1,1] neg_lo:[0,0,1] neg_hi:[0,0,1]
	v_pk_fma_f32 v[216:217], v[208:209], s[94:95], v[216:217] op_sel_hi:[1,0,1]
	v_pk_fma_f32 v[218:219], v[210:211], s[94:95], v[218:219] op_sel_hi:[1,0,1]
	v_pk_fma_f32 v[220:221], v[212:213], s[94:95], v[220:221] op_sel_hi:[1,0,1]
	v_pk_fma_f32 v[222:223], v[214:215], s[94:95], v[222:223] op_sel_hi:[1,0,1]
	v_pk_fma_f32 v[216:217], v[208:209], s[94:95], v[216:217] op_sel:[0,1,0] op_sel_hi:[1,1,1]
	v_pk_fma_f32 v[218:219], v[210:211], s[94:95], v[218:219] op_sel:[0,1,0] op_sel_hi:[1,1,1]
	v_pk_fma_f32 v[220:221], v[212:213], s[94:95], v[220:221] op_sel:[0,1,0] op_sel_hi:[1,1,1]
	v_pk_fma_f32 v[222:223], v[214:215], s[94:95], v[222:223] op_sel:[0,1,0] op_sel_hi:[1,1,1]
	v_pk_add_f32 v[200:201], v[200:201], v[216:217] neg_lo:[0,1] neg_hi:[0,1]
	v_pk_add_f32 v[202:203], v[202:203], v[218:219] neg_lo:[0,1] neg_hi:[0,1]
	v_pk_add_f32 v[204:205], v[204:205], v[220:221] neg_lo:[0,1] neg_hi:[0,1]
	v_pk_add_f32 v[206:207], v[206:207], v[222:223] neg_lo:[0,1] neg_hi:[0,1]
	v_pk_mul_f32 v[192:193], v[200:201], s[96:97] op_sel_hi:[1,0]
	v_pk_mul_f32 v[194:195], v[202:203], s[96:97] op_sel_hi:[1,0]
	v_pk_mul_f32 v[196:197], v[204:205], s[96:97] op_sel_hi:[1,0]
	v_pk_mul_f32 v[198:199], v[206:207], s[96:97] op_sel_hi:[1,0]
	v_cvt_pk_bf16_f32 v208, v184, v185
	v_cvt_pk_bf16_f32 v209, v186, v187
	v_cvt_pk_bf16_f32 v210, v188, v189
	v_cvt_pk_bf16_f32 v211, v190, v191
	v_cvt_pk_bf16_f32 v212, v192, v193
	v_cvt_pk_bf16_f32 v213, v194, v195
	v_cvt_pk_bf16_f32 v214, v196, v197
; __device__ __forceinline__ void store_rm4(u16* dst, size_t ld, int row0, int c, float v0, float v1, float v2, float v3, bool odd) {
;   {
;     float s = odd ? v0 : v1, r = dpp_swap1(s);
;     float lo = odd ? r : v0, hi = odd ? v1 : r;
;     *(unsigned*)(dst + (size_t)(row0 + (odd ? 1 : 0)) * ld + (c - (odd ? 1 : 0))) = pack2(lo, hi);
;   }
;   {
;     float s = odd ? v2 : v3, r = dpp_swap1(s);
;     float lo = odd ? r : v2, hi = odd ? v3 : r;
;     *(unsigned*)(dst + (size_t)(row0 + 2 + (odd ? 1 : 0)) * ld + (c - (odd ? 1 : 0))) = pack2(lo, hi);
;   }
;   __device__ __forceinline__ void operator()(f32x4 (&acc)[2][2][4][2], int brow, int bcol, int wr, int wc, int fr, int fq) const {
;     ...
;             for (int bj = 0; bj < 2; ++bj)
; #pragma unroll
;               for (int n = 0; n < 2; ++n) {
;                 f32x4 z4 = {0.f, 0.f, 0.f, 0.f};
;                 z4 = __builtin_amdgcn_mfma_f32_16x16x16bf16_1k(af, bfr[bj][n], z4, 0, 0, 0);
;                 int c = bj * 128 + wc * 32 + n * 16 + fr;
;                 float bb = bias[c];
;                 float ls[4];
; #pragma unroll
;                 for (int j = 0; j < 4; ++j) {
;                   float z = z4[j] + bb;
;                   ls[j] = (fminf(z, 0.f) - __logf(1.f + __expf(-fabsf(z)))) * (1.f / 16.f);
;                 }
;                 store_rm4(dst, 256, row0, c, ls[0], ls[1], ls[2], ls[3], fr & 1);
;               }
	v_cvt_pk_bf16_f32 v215, v198, v199
	v_mov_b32_dpp v216, v208 quad_perm:[1,0,3,2] row_mask:0xf bank_mask:0xf bound_ctrl:1
	v_mov_b32_dpp v217, v209 quad_perm:[1,0,3,2] row_mask:0xf bank_mask:0xf bound_ctrl:1
	v_mov_b32_dpp v218, v210 quad_perm:[1,0,3,2] row_mask:0xf bank_mask:0xf bound_ctrl:1
	v_mov_b32_dpp v219, v211 quad_perm:[1,0,3,2] row_mask:0xf bank_mask:0xf bound_ctrl:1
	v_mov_b32_dpp v220, v212 quad_perm:[1,0,3,2] row_mask:0xf bank_mask:0xf bound_ctrl:1
	v_mov_b32_dpp v221, v213 quad_perm:[1,0,3,2] row_mask:0xf bank_mask:0xf bound_ctrl:1
	v_mov_b32_dpp v222, v214 quad_perm:[1,0,3,2] row_mask:0xf bank_mask:0xf bound_ctrl:1
	v_mov_b32_dpp v223, v215 quad_perm:[1,0,3,2] row_mask:0xf bank_mask:0xf bound_ctrl:1
	v_perm_b32 v208, v216, v208, v164
	v_perm_b32 v209, v217, v209, v164
	v_perm_b32 v210, v218, v210, v164
	v_perm_b32 v211, v219, v211, v164
	v_perm_b32 v212, v220, v212, v164
	v_perm_b32 v213, v221, v213, v164
	v_perm_b32 v214, v222, v214, v164
	v_perm_b32 v215, v223, v215, v164
	global_store_dword v167, v208, s[8:9]
	global_store_dword v167, v209, s[8:9] offset:1024
	global_store_dword v167, v210, s[8:9] offset:32
	global_store_dword v167, v211, s[8:9] offset:1056
	global_store_dword v167, v212, s[8:9] offset:256
	global_store_dword v167, v213, s[8:9] offset:1280
	global_store_dword v167, v214, s[8:9] offset:288
	global_store_dword v167, v215, s[8:9] offset:1312
	ds_read_b64 v[180:181], v160 offset:50208
	v_add_u32_e32 v167, 0x2000, v163
	s_waitcnt lgkmcnt(0)
	v_mfma_f32_16x16x16_bf16 v[184:187], v[180:181], v[168:169], 0
	v_mfma_f32_16x16x16_bf16 v[188:191], v[180:181], v[170:171], 0
	v_mfma_f32_16x16x16_bf16 v[192:195], v[180:181], v[172:173], 0
	v_mfma_f32_16x16x16_bf16 v[196:199], v[180:181], v[174:175], 0
	s_nop 7
	s_nop 1
	v_pk_add_f32 v[184:185], v[184:185], v[176:177] op_sel_hi:[1,0]
	v_pk_add_f32 v[186:187], v[186:187], v[176:177] op_sel_hi:[1,0]
	v_pk_add_f32 v[188:189], v[188:189], v[176:177] op_sel:[0,1] op_sel_hi:[1,1]
	v_pk_add_f32 v[190:191], v[190:191], v[176:177] op_sel:[0,1] op_sel_hi:[1,1]
	v_min_f32_e32 v200, 0, v184
	v_min_f32_e32 v201, 0, v185
	v_min_f32_e32 v202, 0, v186
	v_min_f32_e32 v203, 0, v187
	v_min_f32_e32 v204, 0, v188
	v_min_f32_e32 v205, 0, v189
	v_min_f32_e32 v206, 0, v190
	v_min_f32_e32 v207, 0, v191
	v_mul_f32_e64 v208, |v184|, s93
	v_mul_f32_e64 v209, |v185|, s93
	v_mul_f32_e64 v210, |v186|, s93
	v_mul_f32_e64 v211, |v187|, s93
	v_mul_f32_e64 v212, |v188|, s93
	v_mul_f32_e64 v213, |v189|, s93
	v_mul_f32_e64 v214, |v190|, s93
	v_mul_f32_e64 v215, |v191|, s93
	v_exp_f32_e32 v208, v208
	v_exp_f32_e32 v209, v209
	v_exp_f32_e32 v210, v210
	v_exp_f32_e32 v211, v211
	v_exp_f32_e32 v212, v212
	v_exp_f32_e32 v213, v213
	v_exp_f32_e32 v214, v214
	v_exp_f32_e32 v215, v215
	v_pk_add_f32 v[208:209], v[208:209], 1.0 op_sel_hi:[1,0]
	v_pk_add_f32 v[210:211], v[210:211], 1.0 op_sel_hi:[1,0]
	v_pk_add_f32 v[212:213], v[212:213], 1.0 op_sel_hi:[1,0]
	v_pk_add_f32 v[214:215], v[214:215], 1.0 op_sel_hi:[1,0]
	v_log_f32_e32 v208, v208
	v_log_f32_e32 v209, v209
	v_log_f32_e32 v210, v210
	v_log_f32_e32 v211, v211
	v_log_f32_e32 v212, v212
	v_log_f32_e32 v213, v213
	v_log_f32_e32 v214, v214
	v_log_f32_e32 v215, v215
	v_pk_mul_f32 v[216:217], v[208:209], s[94:95] op_sel:[0,1] op_sel_hi:[1,1]
	v_pk_mul_f32 v[218:219], v[210:211], s[94:95] op_sel:[0,1] op_sel_hi:[1,1]
	v_pk_mul_f32 v[220:221], v[212:213], s[94:95] op_sel:[0,1] op_sel_hi:[1,1]
	v_pk_mul_f32 v[222:223], v[214:215], s[94:95] op_sel:[0,1] op_sel_hi:[1,1]
	v_pk_fma_f32 v[216:217], v[208:209], s[94:95], v[216:217] op_sel:[0,1,0] op_sel_hi:[1,1,1] neg_lo:[0,0,1] neg_hi:[0,0,1]
	v_pk_fma_f32 v[218:219], v[210:211], s[94:95], v[218:219] op_sel:[0,1,0] op_sel_hi:[1,1,1] neg_lo:[0,0,1] neg_hi:[0,0,1]
	v_pk_fma_f32 v[220:221], v[212:213], s[94:95], v[220:221] op_sel:[0,1,0] op_sel_hi:[1,1,1] neg_lo:[0,0,1] neg_hi:[0,0,1]
	v_pk_fma_f32 v[222:223], v[214:215], s[94:95], v[222:223] op_sel:[0,1,0] op_sel_hi:[1,1,1] neg_lo:[0,0,1] neg_hi:[0,0,1]
	v_pk_fma_f32 v[216:217], v[208:209], s[94:95], v[216:217] op_sel_hi:[1,0,1]
	v_pk_fma_f32 v[218:219], v[210:211], s[94:95], v[218:219] op_sel_hi:[1,0,1]
	v_pk_fma_f32 v[220:221], v[212:213], s[94:95], v[220:221] op_sel_hi:[1,0,1]
	v_pk_fma_f32 v[222:223], v[214:215], s[94:95], v[222:223] op_sel_hi:[1,0,1]
	v_pk_fma_f32 v[216:217], v[208:209], s[94:95], v[216:217] op_sel:[0,1,0] op_sel_hi:[1,1,1]
	v_pk_fma_f32 v[218:219], v[210:211], s[94:95], v[218:219] op_sel:[0,1,0] op_sel_hi:[1,1,1]
	v_pk_fma_f32 v[220:221], v[212:213], s[94:95], v[220:221] op_sel:[0,1,0] op_sel_hi:[1,1,1]
	v_pk_fma_f32 v[222:223], v[214:215], s[94:95], v[222:223] op_sel:[0,1,0] op_sel_hi:[1,1,1]
	v_pk_add_f32 v[200:201], v[200:201], v[216:217] neg_lo:[0,1] neg_hi:[0,1]
	v_pk_add_f32 v[202:203], v[202:203], v[218:219] neg_lo:[0,1] neg_hi:[0,1]
	v_pk_add_f32 v[204:205], v[204:205], v[220:221] neg_lo:[0,1] neg_hi:[0,1]
	v_pk_add_f32 v[206:207], v[206:207], v[222:223] neg_lo:[0,1] neg_hi:[0,1]
	v_pk_mul_f32 v[184:185], v[200:201], s[96:97] op_sel_hi:[1,0]
	v_pk_mul_f32 v[186:187], v[202:203], s[96:97] op_sel_hi:[1,0]
	v_pk_mul_f32 v[188:189], v[204:205], s[96:97] op_sel_hi:[1,0]
	v_pk_mul_f32 v[190:191], v[206:207], s[96:97] op_sel_hi:[1,0]
	v_pk_add_f32 v[192:193], v[192:193], v[178:179] op_sel_hi:[1,0]
	v_pk_add_f32 v[194:195], v[194:195], v[178:179] op_sel_hi:[1,0]
	v_pk_add_f32 v[196:197], v[196:197], v[178:179] op_sel:[0,1] op_sel_hi:[1,1]
	v_pk_add_f32 v[198:199], v[198:199], v[178:179] op_sel:[0,1] op_sel_hi:[1,1]
	v_min_f32_e32 v200, 0, v192
	v_min_f32_e32 v201, 0, v193
	v_min_f32_e32 v202, 0, v194
	v_min_f32_e32 v203, 0, v195
	v_min_f32_e32 v204, 0, v196
; __device__ __forceinline__ void store_rm4(u16* dst, size_t ld, int row0, int c, float v0, float v1, float v2, float v3, bool odd) {
;   {
;     float s = odd ? v0 : v1, r = dpp_swap1(s);
;     float lo = odd ? r : v0, hi = odd ? v1 : r;
;     *(unsigned*)(dst + (size_t)(row0 + (odd ? 1 : 0)) * ld + (c - (odd ? 1 : 0))) = pack2(lo, hi);
;   }
;   {
;     float s = odd ? v2 : v3, r = dpp_swap1(s);
;     float lo = odd ? r : v2, hi = odd ? v3 : r;
;     *(unsigned*)(dst + (size_t)(row0 + 2 + (odd ? 1 : 0)) * ld + (c - (odd ? 1 : 0))) = pack2(lo, hi);
;   }
;   __device__ __forceinline__ void operator()(f32x4 (&acc)[2][2][4][2], int brow, int bcol, int wr, int wc, int fr, int fq) const {
;     ...
;             for (int bj = 0; bj < 2; ++bj)
; #pragma unroll
;               for (int n = 0; n < 2; ++n) {
;                 f32x4 z4 = {0.f, 0.f, 0.f, 0.f};
;                 z4 = __builtin_amdgcn_mfma_f32_16x16x16bf16_1k(af, bfr[bj][n], z4, 0, 0, 0);
;                 int c = bj * 128 + wc * 32 + n * 16 + fr;
;                 float bb = bias[c];
;                 float ls[4];
; #pragma unroll
;                 for (int j = 0; j < 4; ++j) {
;                   float z = z4[j] + bb;
;                   ls[j] = (fminf(z, 0.f) - __logf(1.f + __expf(-fabsf(z)))) * (1.f / 16.f);
;                 }
;                 store_rm4(dst, 256, row0, c, ls[0], ls[1], ls[2], ls[3], fr & 1);
;               }
	v_min_f32_e32 v205, 0, v197
	v_min_f32_e32 v206, 0, v198
	v_min_f32_e32 v207, 0, v199
	v_mul_f32_e64 v208, |v192|, s93
	v_mul_f32_e64 v209, |v193|, s93
	v_mul_f32_e64 v210, |v194|, s93
	v_mul_f32_e64 v211, |v195|, s93
	v_mul_f32_e64 v212, |v196|, s93
	v_mul_f32_e64 v213, |v197|, s93
	v_mul_f32_e64 v214, |v198|, s93
	v_mul_f32_e64 v215, |v199|, s93
	v_exp_f32_e32 v208, v208
	v_exp_f32_e32 v209, v209
	v_exp_f32_e32 v210, v210
	v_exp_f32_e32 v211, v211
	v_exp_f32_e32 v212, v212
	v_exp_f32_e32 v213, v213
	v_exp_f32_e32 v214, v214
	v_exp_f32_e32 v215, v215
	v_pk_add_f32 v[208:209], v[208:209], 1.0 op_sel_hi:[1,0]
	v_pk_add_f32 v[210:211], v[210:211], 1.0 op_sel_hi:[1,0]
	v_pk_add_f32 v[212:213], v[212:213], 1.0 op_sel_hi:[1,0]
	v_pk_add_f32 v[214:215], v[214:215], 1.0 op_sel_hi:[1,0]
	v_log_f32_e32 v208, v208
	v_log_f32_e32 v209, v209
	v_log_f32_e32 v210, v210
	v_log_f32_e32 v211, v211
	v_log_f32_e32 v212, v212
	v_log_f32_e32 v213, v213
	v_log_f32_e32 v214, v214
	v_log_f32_e32 v215, v215
	v_pk_mul_f32 v[216:217], v[208:209], s[94:95] op_sel:[0,1] op_sel_hi:[1,1]
	v_pk_mul_f32 v[218:219], v[210:211], s[94:95] op_sel:[0,1] op_sel_hi:[1,1]
	v_pk_mul_f32 v[220:221], v[212:213], s[94:95] op_sel:[0,1] op_sel_hi:[1,1]
	v_pk_mul_f32 v[222:223], v[214:215], s[94:95] op_sel:[0,1] op_sel_hi:[1,1]
	v_pk_fma_f32 v[216:217], v[208:209], s[94:95], v[216:217] op_sel:[0,1,0] op_sel_hi:[1,1,1] neg_lo:[0,0,1] neg_hi:[0,0,1]
	v_pk_fma_f32 v[218:219], v[210:211], s[94:95], v[218:219] op_sel:[0,1,0] op_sel_hi:[1,1,1] neg_lo:[0,0,1] neg_hi:[0,0,1]
	v_pk_fma_f32 v[220:221], v[212:213], s[94:95], v[220:221] op_sel:[0,1,0] op_sel_hi:[1,1,1] neg_lo:[0,0,1] neg_hi:[0,0,1]
	v_pk_fma_f32 v[222:223], v[214:215], s[94:95], v[222:223] op_sel:[0,1,0] op_sel_hi:[1,1,1] neg_lo:[0,0,1] neg_hi:[0,0,1]
	v_pk_fma_f32 v[216:217], v[208:209], s[94:95], v[216:217] op_sel_hi:[1,0,1]
	v_pk_fma_f32 v[218:219], v[210:211], s[94:95], v[218:219] op_sel_hi:[1,0,1]
	v_pk_fma_f32 v[220:221], v[212:213], s[94:95], v[220:221] op_sel_hi:[1,0,1]
	v_pk_fma_f32 v[222:223], v[214:215], s[94:95], v[222:223] op_sel_hi:[1,0,1]
	v_pk_fma_f32 v[216:217], v[208:209], s[94:95], v[216:217] op_sel:[0,1,0] op_sel_hi:[1,1,1]
	v_pk_fma_f32 v[218:219], v[210:211], s[94:95], v[218:219] op_sel:[0,1,0] op_sel_hi:[1,1,1]
	v_pk_fma_f32 v[220:221], v[212:213], s[94:95], v[220:221] op_sel:[0,1,0] op_sel_hi:[1,1,1]
	v_pk_fma_f32 v[222:223], v[214:215], s[94:95], v[222:223] op_sel:[0,1,0] op_sel_hi:[1,1,1]
	v_pk_add_f32 v[200:201], v[200:201], v[216:217] neg_lo:[0,1] neg_hi:[0,1]
	v_pk_add_f32 v[202:203], v[202:203], v[218:219] neg_lo:[0,1] neg_hi:[0,1]
	v_pk_add_f32 v[204:205], v[204:205], v[220:221] neg_lo:[0,1] neg_hi:[0,1]
	v_pk_add_f32 v[206:207], v[206:207], v[222:223] neg_lo:[0,1] neg_hi:[0,1]
	v_pk_mul_f32 v[192:193], v[200:201], s[96:97] op_sel_hi:[1,0]
	v_pk_mul_f32 v[194:195], v[202:203], s[96:97] op_sel_hi:[1,0]
	v_pk_mul_f32 v[196:197], v[204:205], s[96:97] op_sel_hi:[1,0]
	v_pk_mul_f32 v[198:199], v[206:207], s[96:97] op_sel_hi:[1,0]
	v_cvt_pk_bf16_f32 v208, v184, v185
	v_cvt_pk_bf16_f32 v209, v186, v187
	v_cvt_pk_bf16_f32 v210, v188, v189
	v_cvt_pk_bf16_f32 v211, v190, v191
	v_cvt_pk_bf16_f32 v212, v192, v193
	v_cvt_pk_bf16_f32 v213, v194, v195
	v_cvt_pk_bf16_f32 v214, v196, v197
	v_cvt_pk_bf16_f32 v215, v198, v199
	v_mov_b32_dpp v216, v208 quad_perm:[1,0,3,2] row_mask:0xf bank_mask:0xf bound_ctrl:1
	v_mov_b32_dpp v217, v209 quad_perm:[1,0,3,2] row_mask:0xf bank_mask:0xf bound_ctrl:1
	v_mov_b32_dpp v218, v210 quad_perm:[1,0,3,2] row_mask:0xf bank_mask:0xf bound_ctrl:1
	v_mov_b32_dpp v219, v211 quad_perm:[1,0,3,2] row_mask:0xf bank_mask:0xf bound_ctrl:1
	v_mov_b32_dpp v220, v212 quad_perm:[1,0,3,2] row_mask:0xf bank_mask:0xf bound_ctrl:1
	v_mov_b32_dpp v221, v213 quad_perm:[1,0,3,2] row_mask:0xf bank_mask:0xf bound_ctrl:1
	v_mov_b32_dpp v222, v214 quad_perm:[1,0,3,2] row_mask:0xf bank_mask:0xf bound_ctrl:1
	v_mov_b32_dpp v223, v215 quad_perm:[1,0,3,2] row_mask:0xf bank_mask:0xf bound_ctrl:1
	v_perm_b32 v208, v216, v208, v164
	v_perm_b32 v209, v217, v209, v164
	v_perm_b32 v210, v218, v210, v164
	v_perm_b32 v211, v219, v211, v164
	v_perm_b32 v212, v220, v212, v164
	v_perm_b32 v213, v221, v213, v164
	v_perm_b32 v214, v222, v214, v164
	v_perm_b32 v215, v223, v215, v164
	global_store_dword v167, v208, s[8:9]
	global_store_dword v167, v209, s[8:9] offset:1024
	global_store_dword v167, v210, s[8:9] offset:32
	global_store_dword v167, v211, s[8:9] offset:1056
	global_store_dword v167, v212, s[8:9] offset:256
	global_store_dword v167, v213, s[8:9] offset:1280
	global_store_dword v167, v214, s[8:9] offset:288
	global_store_dword v167, v215, s[8:9] offset:1312
	ds_read_b64 v[180:181], v160 offset:51232
	v_add_u32_e32 v167, 0x4000, v163
	s_waitcnt lgkmcnt(0)
;   __device__ __forceinline__ void operator()(f32x4 (&acc)[2][2][4][2], int brow, int bcol, int wr, int wc, int fr, int fq) const {
;     ...
;             for (int bj = 0; bj < 2; ++bj)
; #pragma unroll
;               for (int n = 0; n < 2; ++n) {
;                 f32x4 z4 = {0.f, 0.f, 0.f, 0.f};
;                 z4 = __builtin_amdgcn_mfma_f32_16x16x16bf16_1k(af, bfr[bj][n], z4, 0, 0, 0);
;                 int c = bj * 128 + wc * 32 + n * 16 + fr;
;                 float bb = bias[c];
;                 float ls[4];
; #pragma unroll
;                 for (int j = 0; j < 4; ++j) {
;                   float z = z4[j] + bb;
;                   ls[j] = (fminf(z, 0.f) - __logf(1.f + __expf(-fabsf(z)))) * (1.f / 16.f);
;                 }
;                 store_rm4(dst, 256, row0, c, ls[0], ls[1], ls[2], ls[3], fr & 1);
;               }
	v_mfma_f32_16x16x16_bf16 v[184:187], v[180:181], v[168:169], 0
	v_mfma_f32_16x16x16_bf16 v[188:191], v[180:181], v[170:171], 0
	v_mfma_f32_16x16x16_bf16 v[192:195], v[180:181], v[172:173], 0
	v_mfma_f32_16x16x16_bf16 v[196:199], v[180:181], v[174:175], 0
	s_nop 7
	s_nop 1
	v_pk_add_f32 v[184:185], v[184:185], v[176:177] op_sel_hi:[1,0]
	v_pk_add_f32 v[186:187], v[186:187], v[176:177] op_sel_hi:[1,0]
	v_pk_add_f32 v[188:189], v[188:189], v[176:177] op_sel:[0,1] op_sel_hi:[1,1]
	v_pk_add_f32 v[190:191], v[190:191], v[176:177] op_sel:[0,1] op_sel_hi:[1,1]
	v_min_f32_e32 v200, 0, v184
	v_min_f32_e32 v201, 0, v185
	v_min_f32_e32 v202, 0, v186
	v_min_f32_e32 v203, 0, v187
	v_min_f32_e32 v204, 0, v188
	v_min_f32_e32 v205, 0, v189
	v_min_f32_e32 v206, 0, v190
	v_min_f32_e32 v207, 0, v191
	v_mul_f32_e64 v208, |v184|, s93
	v_mul_f32_e64 v209, |v185|, s93
	v_mul_f32_e64 v210, |v186|, s93
	v_mul_f32_e64 v211, |v187|, s93
	v_mul_f32_e64 v212, |v188|, s93
	v_mul_f32_e64 v213, |v189|, s93
	v_mul_f32_e64 v214, |v190|, s93
	v_mul_f32_e64 v215, |v191|, s93
	v_exp_f32_e32 v208, v208
	v_exp_f32_e32 v209, v209
	v_exp_f32_e32 v210, v210
	v_exp_f32_e32 v211, v211
	v_exp_f32_e32 v212, v212
	v_exp_f32_e32 v213, v213
	v_exp_f32_e32 v214, v214
	v_exp_f32_e32 v215, v215
	v_pk_add_f32 v[208:209], v[208:209], 1.0 op_sel_hi:[1,0]
	v_pk_add_f32 v[210:211], v[210:211], 1.0 op_sel_hi:[1,0]
	v_pk_add_f32 v[212:213], v[212:213], 1.0 op_sel_hi:[1,0]
	v_pk_add_f32 v[214:215], v[214:215], 1.0 op_sel_hi:[1,0]
	v_log_f32_e32 v208, v208
	v_log_f32_e32 v209, v209
	v_log_f32_e32 v210, v210
	v_log_f32_e32 v211, v211
	v_log_f32_e32 v212, v212
	v_log_f32_e32 v213, v213
	v_log_f32_e32 v214, v214
	v_log_f32_e32 v215, v215
	v_pk_mul_f32 v[216:217], v[208:209], s[94:95] op_sel:[0,1] op_sel_hi:[1,1]
	v_pk_mul_f32 v[218:219], v[210:211], s[94:95] op_sel:[0,1] op_sel_hi:[1,1]
	v_pk_mul_f32 v[220:221], v[212:213], s[94:95] op_sel:[0,1] op_sel_hi:[1,1]
	v_pk_mul_f32 v[222:223], v[214:215], s[94:95] op_sel:[0,1] op_sel_hi:[1,1]
	v_pk_fma_f32 v[216:217], v[208:209], s[94:95], v[216:217] op_sel:[0,1,0] op_sel_hi:[1,1,1] neg_lo:[0,0,1] neg_hi:[0,0,1]
	v_pk_fma_f32 v[218:219], v[210:211], s[94:95], v[218:219] op_sel:[0,1,0] op_sel_hi:[1,1,1] neg_lo:[0,0,1] neg_hi:[0,0,1]
	v_pk_fma_f32 v[220:221], v[212:213], s[94:95], v[220:221] op_sel:[0,1,0] op_sel_hi:[1,1,1] neg_lo:[0,0,1] neg_hi:[0,0,1]
	v_pk_fma_f32 v[222:223], v[214:215], s[94:95], v[222:223] op_sel:[0,1,0] op_sel_hi:[1,1,1] neg_lo:[0,0,1] neg_hi:[0,0,1]
	v_pk_fma_f32 v[216:217], v[208:209], s[94:95], v[216:217] op_sel_hi:[1,0,1]
	v_pk_fma_f32 v[218:219], v[210:211], s[94:95], v[218:219] op_sel_hi:[1,0,1]
	v_pk_fma_f32 v[220:221], v[212:213], s[94:95], v[220:221] op_sel_hi:[1,0,1]
	v_pk_fma_f32 v[222:223], v[214:215], s[94:95], v[222:223] op_sel_hi:[1,0,1]
	v_pk_fma_f32 v[216:217], v[208:209], s[94:95], v[216:217] op_sel:[0,1,0] op_sel_hi:[1,1,1]
	v_pk_fma_f32 v[218:219], v[210:211], s[94:95], v[218:219] op_sel:[0,1,0] op_sel_hi:[1,1,1]
	v_pk_fma_f32 v[220:221], v[212:213], s[94:95], v[220:221] op_sel:[0,1,0] op_sel_hi:[1,1,1]
	v_pk_fma_f32 v[222:223], v[214:215], s[94:95], v[222:223] op_sel:[0,1,0] op_sel_hi:[1,1,1]
	v_pk_add_f32 v[200:201], v[200:201], v[216:217] neg_lo:[0,1] neg_hi:[0,1]
	v_pk_add_f32 v[202:203], v[202:203], v[218:219] neg_lo:[0,1] neg_hi:[0,1]
	v_pk_add_f32 v[204:205], v[204:205], v[220:221] neg_lo:[0,1] neg_hi:[0,1]
	v_pk_add_f32 v[206:207], v[206:207], v[222:223] neg_lo:[0,1] neg_hi:[0,1]
	v_pk_mul_f32 v[184:185], v[200:201], s[96:97] op_sel_hi:[1,0]
	v_pk_mul_f32 v[186:187], v[202:203], s[96:97] op_sel_hi:[1,0]
	v_pk_mul_f32 v[188:189], v[204:205], s[96:97] op_sel_hi:[1,0]
	v_pk_mul_f32 v[190:191], v[206:207], s[96:97] op_sel_hi:[1,0]
	v_pk_add_f32 v[192:193], v[192:193], v[178:179] op_sel_hi:[1,0]
	v_pk_add_f32 v[194:195], v[194:195], v[178:179] op_sel_hi:[1,0]
	v_pk_add_f32 v[196:197], v[196:197], v[178:179] op_sel:[0,1] op_sel_hi:[1,1]
	v_pk_add_f32 v[198:199], v[198:199], v[178:179] op_sel:[0,1] op_sel_hi:[1,1]
	v_min_f32_e32 v200, 0, v192
	v_min_f32_e32 v201, 0, v193
	v_min_f32_e32 v202, 0, v194
	v_min_f32_e32 v203, 0, v195
	v_min_f32_e32 v204, 0, v196
	v_min_f32_e32 v205, 0, v197
	v_min_f32_e32 v206, 0, v198
	v_min_f32_e32 v207, 0, v199
	v_mul_f32_e64 v208, |v192|, s93
	v_mul_f32_e64 v209, |v193|, s93
	v_mul_f32_e64 v210, |v194|, s93
	v_mul_f32_e64 v211, |v195|, s93
	v_mul_f32_e64 v212, |v196|, s93
	v_mul_f32_e64 v213, |v197|, s93
	v_mul_f32_e64 v214, |v198|, s93
	v_mul_f32_e64 v215, |v199|, s93
	v_exp_f32_e32 v208, v208
	v_exp_f32_e32 v209, v209
	v_exp_f32_e32 v210, v210
	v_exp_f32_e32 v211, v211
	v_exp_f32_e32 v212, v212
	v_exp_f32_e32 v213, v213
	v_exp_f32_e32 v214, v214
	v_exp_f32_e32 v215, v215
	v_pk_add_f32 v[208:209], v[208:209], 1.0 op_sel_hi:[1,0]
	v_pk_add_f32 v[210:211], v[210:211], 1.0 op_sel_hi:[1,0]
	v_pk_add_f32 v[212:213], v[212:213], 1.0 op_sel_hi:[1,0]
	v_pk_add_f32 v[214:215], v[214:215], 1.0 op_sel_hi:[1,0]
	v_log_f32_e32 v208, v208
	v_log_f32_e32 v209, v209
	v_log_f32_e32 v210, v210
	v_log_f32_e32 v211, v211
	v_log_f32_e32 v212, v212
	v_log_f32_e32 v213, v213
	v_log_f32_e32 v214, v214
	v_log_f32_e32 v215, v215
	v_pk_mul_f32 v[216:217], v[208:209], s[94:95] op_sel:[0,1] op_sel_hi:[1,1]
	v_pk_mul_f32 v[218:219], v[210:211], s[94:95] op_sel:[0,1] op_sel_hi:[1,1]
	v_pk_mul_f32 v[220:221], v[212:213], s[94:95] op_sel:[0,1] op_sel_hi:[1,1]
	v_pk_mul_f32 v[222:223], v[214:215], s[94:95] op_sel:[0,1] op_sel_hi:[1,1]
	v_pk_fma_f32 v[216:217], v[208:209], s[94:95], v[216:217] op_sel:[0,1,0] op_sel_hi:[1,1,1] neg_lo:[0,0,1] neg_hi:[0,0,1]
; __device__ __forceinline__ void store_rm4(u16* dst, size_t ld, int row0, int c, float v0, float v1, float v2, float v3, bool odd) {
;   {
;     float s = odd ? v0 : v1, r = dpp_swap1(s);
;     float lo = odd ? r : v0, hi = odd ? v1 : r;
;     *(unsigned*)(dst + (size_t)(row0 + (odd ? 1 : 0)) * ld + (c - (odd ? 1 : 0))) = pack2(lo, hi);
;   }
;   {
;     float s = odd ? v2 : v3, r = dpp_swap1(s);
;     float lo = odd ? r : v2, hi = odd ? v3 : r;
;     *(unsigned*)(dst + (size_t)(row0 + 2 + (odd ? 1 : 0)) * ld + (c - (odd ? 1 : 0))) = pack2(lo, hi);
;   }
;   __device__ __forceinline__ void operator()(f32x4 (&acc)[2][2][4][2], int brow, int bcol, int wr, int wc, int fr, int fq) const {
;     ...
;             for (int bj = 0; bj < 2; ++bj)
; #pragma unroll
;               for (int n = 0; n < 2; ++n) {
;                 f32x4 z4 = {0.f, 0.f, 0.f, 0.f};
;                 z4 = __builtin_amdgcn_mfma_f32_16x16x16bf16_1k(af, bfr[bj][n], z4, 0, 0, 0);
;                 int c = bj * 128 + wc * 32 + n * 16 + fr;
;                 float bb = bias[c];
;                 float ls[4];
; #pragma unroll
;                 for (int j = 0; j < 4; ++j) {
;                   float z = z4[j] + bb;
;                   ls[j] = (fminf(z, 0.f) - __logf(1.f + __expf(-fabsf(z)))) * (1.f / 16.f);
;                 }
;                 store_rm4(dst, 256, row0, c, ls[0], ls[1], ls[2], ls[3], fr & 1);
;               }
	v_pk_fma_f32 v[218:219], v[210:211], s[94:95], v[218:219] op_sel:[0,1,0] op_sel_hi:[1,1,1] neg_lo:[0,0,1] neg_hi:[0,0,1]
	v_pk_fma_f32 v[220:221], v[212:213], s[94:95], v[220:221] op_sel:[0,1,0] op_sel_hi:[1,1,1] neg_lo:[0,0,1] neg_hi:[0,0,1]
	v_pk_fma_f32 v[222:223], v[214:215], s[94:95], v[222:223] op_sel:[0,1,0] op_sel_hi:[1,1,1] neg_lo:[0,0,1] neg_hi:[0,0,1]
	v_pk_fma_f32 v[216:217], v[208:209], s[94:95], v[216:217] op_sel_hi:[1,0,1]
	v_pk_fma_f32 v[218:219], v[210:211], s[94:95], v[218:219] op_sel_hi:[1,0,1]
	v_pk_fma_f32 v[220:221], v[212:213], s[94:95], v[220:221] op_sel_hi:[1,0,1]
	v_pk_fma_f32 v[222:223], v[214:215], s[94:95], v[222:223] op_sel_hi:[1,0,1]
	v_pk_fma_f32 v[216:217], v[208:209], s[94:95], v[216:217] op_sel:[0,1,0] op_sel_hi:[1,1,1]
	v_pk_fma_f32 v[218:219], v[210:211], s[94:95], v[218:219] op_sel:[0,1,0] op_sel_hi:[1,1,1]
	v_pk_fma_f32 v[220:221], v[212:213], s[94:95], v[220:221] op_sel:[0,1,0] op_sel_hi:[1,1,1]
	v_pk_fma_f32 v[222:223], v[214:215], s[94:95], v[222:223] op_sel:[0,1,0] op_sel_hi:[1,1,1]
	v_pk_add_f32 v[200:201], v[200:201], v[216:217] neg_lo:[0,1] neg_hi:[0,1]
	v_pk_add_f32 v[202:203], v[202:203], v[218:219] neg_lo:[0,1] neg_hi:[0,1]
	v_pk_add_f32 v[204:205], v[204:205], v[220:221] neg_lo:[0,1] neg_hi:[0,1]
	v_pk_add_f32 v[206:207], v[206:207], v[222:223] neg_lo:[0,1] neg_hi:[0,1]
	v_pk_mul_f32 v[192:193], v[200:201], s[96:97] op_sel_hi:[1,0]
	v_pk_mul_f32 v[194:195], v[202:203], s[96:97] op_sel_hi:[1,0]
	v_pk_mul_f32 v[196:197], v[204:205], s[96:97] op_sel_hi:[1,0]
	v_pk_mul_f32 v[198:199], v[206:207], s[96:97] op_sel_hi:[1,0]
	v_cvt_pk_bf16_f32 v208, v184, v185
	v_cvt_pk_bf16_f32 v209, v186, v187
	v_cvt_pk_bf16_f32 v210, v188, v189
	v_cvt_pk_bf16_f32 v211, v190, v191
	v_cvt_pk_bf16_f32 v212, v192, v193
	v_cvt_pk_bf16_f32 v213, v194, v195
	v_cvt_pk_bf16_f32 v214, v196, v197
	v_cvt_pk_bf16_f32 v215, v198, v199
	v_mov_b32_dpp v216, v208 quad_perm:[1,0,3,2] row_mask:0xf bank_mask:0xf bound_ctrl:1
	v_mov_b32_dpp v217, v209 quad_perm:[1,0,3,2] row_mask:0xf bank_mask:0xf bound_ctrl:1
	v_mov_b32_dpp v218, v210 quad_perm:[1,0,3,2] row_mask:0xf bank_mask:0xf bound_ctrl:1
	v_mov_b32_dpp v219, v211 quad_perm:[1,0,3,2] row_mask:0xf bank_mask:0xf bound_ctrl:1
	v_mov_b32_dpp v220, v212 quad_perm:[1,0,3,2] row_mask:0xf bank_mask:0xf bound_ctrl:1
	v_mov_b32_dpp v221, v213 quad_perm:[1,0,3,2] row_mask:0xf bank_mask:0xf bound_ctrl:1
	v_mov_b32_dpp v222, v214 quad_perm:[1,0,3,2] row_mask:0xf bank_mask:0xf bound_ctrl:1
	v_mov_b32_dpp v223, v215 quad_perm:[1,0,3,2] row_mask:0xf bank_mask:0xf bound_ctrl:1
	v_perm_b32 v208, v216, v208, v164
	v_perm_b32 v209, v217, v209, v164
	v_perm_b32 v210, v218, v210, v164
	v_perm_b32 v211, v219, v211, v164
	v_perm_b32 v212, v220, v212, v164
	v_perm_b32 v213, v221, v213, v164
	v_perm_b32 v214, v222, v214, v164
	v_perm_b32 v215, v223, v215, v164
	global_store_dword v167, v208, s[8:9]
	global_store_dword v167, v209, s[8:9] offset:1024
	global_store_dword v167, v210, s[8:9] offset:32
	global_store_dword v167, v211, s[8:9] offset:1056
	global_store_dword v167, v212, s[8:9] offset:256
	global_store_dword v167, v213, s[8:9] offset:1280
	global_store_dword v167, v214, s[8:9] offset:288
	global_store_dword v167, v215, s[8:9] offset:1312
	ds_read_b64 v[180:181], v160 offset:52256
	v_add_u32_e32 v167, 0x6000, v163
	s_waitcnt lgkmcnt(0)
	v_mfma_f32_16x16x16_bf16 v[184:187], v[180:181], v[168:169], 0
	v_mfma_f32_16x16x16_bf16 v[188:191], v[180:181], v[170:171], 0
	v_mfma_f32_16x16x16_bf16 v[192:195], v[180:181], v[172:173], 0
	v_mfma_f32_16x16x16_bf16 v[196:199], v[180:181], v[174:175], 0
	s_nop 7
	s_nop 1
	v_pk_add_f32 v[184:185], v[184:185], v[176:177] op_sel_hi:[1,0]
	v_pk_add_f32 v[186:187], v[186:187], v[176:177] op_sel_hi:[1,0]
	v_pk_add_f32 v[188:189], v[188:189], v[176:177] op_sel:[0,1] op_sel_hi:[1,1]
	v_pk_add_f32 v[190:191], v[190:191], v[176:177] op_sel:[0,1] op_sel_hi:[1,1]
	v_min_f32_e32 v200, 0, v184
	v_min_f32_e32 v201, 0, v185
	v_min_f32_e32 v202, 0, v186
	v_min_f32_e32 v203, 0, v187
	v_min_f32_e32 v204, 0, v188
	v_min_f32_e32 v205, 0, v189
	v_min_f32_e32 v206, 0, v190
	v_min_f32_e32 v207, 0, v191
	v_mul_f32_e64 v208, |v184|, s93
	v_mul_f32_e64 v209, |v185|, s93
	v_mul_f32_e64 v210, |v186|, s93
	v_mul_f32_e64 v211, |v187|, s93
	v_mul_f32_e64 v212, |v188|, s93
	v_mul_f32_e64 v213, |v189|, s93
	v_mul_f32_e64 v214, |v190|, s93
	v_mul_f32_e64 v215, |v191|, s93
	v_exp_f32_e32 v208, v208
	v_exp_f32_e32 v209, v209
	v_exp_f32_e32 v210, v210
	v_exp_f32_e32 v211, v211
	v_exp_f32_e32 v212, v212
	v_exp_f32_e32 v213, v213
	v_exp_f32_e32 v214, v214
	v_exp_f32_e32 v215, v215
	v_pk_add_f32 v[208:209], v[208:209], 1.0 op_sel_hi:[1,0]
	v_pk_add_f32 v[210:211], v[210:211], 1.0 op_sel_hi:[1,0]
	v_pk_add_f32 v[212:213], v[212:213], 1.0 op_sel_hi:[1,0]
	v_pk_add_f32 v[214:215], v[214:215], 1.0 op_sel_hi:[1,0]
	v_log_f32_e32 v208, v208
	v_log_f32_e32 v209, v209
	v_log_f32_e32 v210, v210
	v_log_f32_e32 v211, v211
	v_log_f32_e32 v212, v212
	v_log_f32_e32 v213, v213
	v_log_f32_e32 v214, v214
	v_log_f32_e32 v215, v215
	v_pk_mul_f32 v[216:217], v[208:209], s[94:95] op_sel:[0,1] op_sel_hi:[1,1]
	v_pk_mul_f32 v[218:219], v[210:211], s[94:95] op_sel:[0,1] op_sel_hi:[1,1]
	v_pk_mul_f32 v[220:221], v[212:213], s[94:95] op_sel:[0,1] op_sel_hi:[1,1]
	v_pk_mul_f32 v[222:223], v[214:215], s[94:95] op_sel:[0,1] op_sel_hi:[1,1]
	v_pk_fma_f32 v[216:217], v[208:209], s[94:95], v[216:217] op_sel:[0,1,0] op_sel_hi:[1,1,1] neg_lo:[0,0,1] neg_hi:[0,0,1]
	v_pk_fma_f32 v[218:219], v[210:211], s[94:95], v[218:219] op_sel:[0,1,0] op_sel_hi:[1,1,1] neg_lo:[0,0,1] neg_hi:[0,0,1]
; __device__ __forceinline__ void store_rm4(u16* dst, size_t ld, int row0, int c, float v0, float v1, float v2, float v3, bool odd) {
;   {
;     float s = odd ? v0 : v1, r = dpp_swap1(s);
;     float lo = odd ? r : v0, hi = odd ? v1 : r;
;     *(unsigned*)(dst + (size_t)(row0 + (odd ? 1 : 0)) * ld + (c - (odd ? 1 : 0))) = pack2(lo, hi);
;   }
;   {
;     float s = odd ? v2 : v3, r = dpp_swap1(s);
;     float lo = odd ? r : v2, hi = odd ? v3 : r;
;     *(unsigned*)(dst + (size_t)(row0 + 2 + (odd ? 1 : 0)) * ld + (c - (odd ? 1 : 0))) = pack2(lo, hi);
;   }
;   __device__ __forceinline__ void operator()(f32x4 (&acc)[2][2][4][2], int brow, int bcol, int wr, int wc, int fr, int fq) const {
;     ...
;             for (int bj = 0; bj < 2; ++bj)
; #pragma unroll
;               for (int n = 0; n < 2; ++n) {
;                 f32x4 z4 = {0.f, 0.f, 0.f, 0.f};
;                 z4 = __builtin_amdgcn_mfma_f32_16x16x16bf16_1k(af, bfr[bj][n], z4, 0, 0, 0);
;                 int c = bj * 128 + wc * 32 + n * 16 + fr;
;                 float bb = bias[c];
;                 float ls[4];
; #pragma unroll
;                 for (int j = 0; j < 4; ++j) {
;                   float z = z4[j] + bb;
;                   ls[j] = (fminf(z, 0.f) - __logf(1.f + __expf(-fabsf(z)))) * (1.f / 16.f);
;                 }
;                 store_rm4(dst, 256, row0, c, ls[0], ls[1], ls[2], ls[3], fr & 1);
;               }
	v_pk_fma_f32 v[220:221], v[212:213], s[94:95], v[220:221] op_sel:[0,1,0] op_sel_hi:[1,1,1] neg_lo:[0,0,1] neg_hi:[0,0,1]
	v_pk_fma_f32 v[222:223], v[214:215], s[94:95], v[222:223] op_sel:[0,1,0] op_sel_hi:[1,1,1] neg_lo:[0,0,1] neg_hi:[0,0,1]
	v_pk_fma_f32 v[216:217], v[208:209], s[94:95], v[216:217] op_sel_hi:[1,0,1]
	v_pk_fma_f32 v[218:219], v[210:211], s[94:95], v[218:219] op_sel_hi:[1,0,1]
	v_pk_fma_f32 v[220:221], v[212:213], s[94:95], v[220:221] op_sel_hi:[1,0,1]
	v_pk_fma_f32 v[222:223], v[214:215], s[94:95], v[222:223] op_sel_hi:[1,0,1]
	v_pk_fma_f32 v[216:217], v[208:209], s[94:95], v[216:217] op_sel:[0,1,0] op_sel_hi:[1,1,1]
	v_pk_fma_f32 v[218:219], v[210:211], s[94:95], v[218:219] op_sel:[0,1,0] op_sel_hi:[1,1,1]
	v_pk_fma_f32 v[220:221], v[212:213], s[94:95], v[220:221] op_sel:[0,1,0] op_sel_hi:[1,1,1]
	v_pk_fma_f32 v[222:223], v[214:215], s[94:95], v[222:223] op_sel:[0,1,0] op_sel_hi:[1,1,1]
	v_pk_add_f32 v[200:201], v[200:201], v[216:217] neg_lo:[0,1] neg_hi:[0,1]
	v_pk_add_f32 v[202:203], v[202:203], v[218:219] neg_lo:[0,1] neg_hi:[0,1]
	v_pk_add_f32 v[204:205], v[204:205], v[220:221] neg_lo:[0,1] neg_hi:[0,1]
	v_pk_add_f32 v[206:207], v[206:207], v[222:223] neg_lo:[0,1] neg_hi:[0,1]
	v_pk_mul_f32 v[184:185], v[200:201], s[96:97] op_sel_hi:[1,0]
	v_pk_mul_f32 v[186:187], v[202:203], s[96:97] op_sel_hi:[1,0]
	v_pk_mul_f32 v[188:189], v[204:205], s[96:97] op_sel_hi:[1,0]
	v_pk_mul_f32 v[190:191], v[206:207], s[96:97] op_sel_hi:[1,0]
	v_pk_add_f32 v[192:193], v[192:193], v[178:179] op_sel_hi:[1,0]
	v_pk_add_f32 v[194:195], v[194:195], v[178:179] op_sel_hi:[1,0]
	v_pk_add_f32 v[196:197], v[196:197], v[178:179] op_sel:[0,1] op_sel_hi:[1,1]
	v_pk_add_f32 v[198:199], v[198:199], v[178:179] op_sel:[0,1] op_sel_hi:[1,1]
	v_min_f32_e32 v200, 0, v192
	v_min_f32_e32 v201, 0, v193
	v_min_f32_e32 v202, 0, v194
	v_min_f32_e32 v203, 0, v195
	v_min_f32_e32 v204, 0, v196
	v_min_f32_e32 v205, 0, v197
	v_min_f32_e32 v206, 0, v198
	v_min_f32_e32 v207, 0, v199
	v_mul_f32_e64 v208, |v192|, s93
	v_mul_f32_e64 v209, |v193|, s93
	v_mul_f32_e64 v210, |v194|, s93
	v_mul_f32_e64 v211, |v195|, s93
	v_mul_f32_e64 v212, |v196|, s93
	v_mul_f32_e64 v213, |v197|, s93
	v_mul_f32_e64 v214, |v198|, s93
	v_mul_f32_e64 v215, |v199|, s93
	v_exp_f32_e32 v208, v208
	v_exp_f32_e32 v209, v209
	v_exp_f32_e32 v210, v210
	v_exp_f32_e32 v211, v211
	v_exp_f32_e32 v212, v212
	v_exp_f32_e32 v213, v213
	v_exp_f32_e32 v214, v214
	v_exp_f32_e32 v215, v215
	v_pk_add_f32 v[208:209], v[208:209], 1.0 op_sel_hi:[1,0]
	v_pk_add_f32 v[210:211], v[210:211], 1.0 op_sel_hi:[1,0]
	v_pk_add_f32 v[212:213], v[212:213], 1.0 op_sel_hi:[1,0]
	v_pk_add_f32 v[214:215], v[214:215], 1.0 op_sel_hi:[1,0]
	v_log_f32_e32 v208, v208
	v_log_f32_e32 v209, v209
	v_log_f32_e32 v210, v210
	v_log_f32_e32 v211, v211
	v_log_f32_e32 v212, v212
	v_log_f32_e32 v213, v213
	v_log_f32_e32 v214, v214
	v_log_f32_e32 v215, v215
	v_pk_mul_f32 v[216:217], v[208:209], s[94:95] op_sel:[0,1] op_sel_hi:[1,1]
	v_pk_mul_f32 v[218:219], v[210:211], s[94:95] op_sel:[0,1] op_sel_hi:[1,1]
	v_pk_mul_f32 v[220:221], v[212:213], s[94:95] op_sel:[0,1] op_sel_hi:[1,1]
	v_pk_mul_f32 v[222:223], v[214:215], s[94:95] op_sel:[0,1] op_sel_hi:[1,1]
	v_pk_fma_f32 v[216:217], v[208:209], s[94:95], v[216:217] op_sel:[0,1,0] op_sel_hi:[1,1,1] neg_lo:[0,0,1] neg_hi:[0,0,1]
	v_pk_fma_f32 v[218:219], v[210:211], s[94:95], v[218:219] op_sel:[0,1,0] op_sel_hi:[1,1,1] neg_lo:[0,0,1] neg_hi:[0,0,1]
	v_pk_fma_f32 v[220:221], v[212:213], s[94:95], v[220:221] op_sel:[0,1,0] op_sel_hi:[1,1,1] neg_lo:[0,0,1] neg_hi:[0,0,1]
	v_pk_fma_f32 v[222:223], v[214:215], s[94:95], v[222:223] op_sel:[0,1,0] op_sel_hi:[1,1,1] neg_lo:[0,0,1] neg_hi:[0,0,1]
	v_pk_fma_f32 v[216:217], v[208:209], s[94:95], v[216:217] op_sel_hi:[1,0,1]
	v_pk_fma_f32 v[218:219], v[210:211], s[94:95], v[218:219] op_sel_hi:[1,0,1]
	v_pk_fma_f32 v[220:221], v[212:213], s[94:95], v[220:221] op_sel_hi:[1,0,1]
	v_pk_fma_f32 v[222:223], v[214:215], s[94:95], v[222:223] op_sel_hi:[1,0,1]
	v_pk_fma_f32 v[216:217], v[208:209], s[94:95], v[216:217] op_sel:[0,1,0] op_sel_hi:[1,1,1]
	v_pk_fma_f32 v[218:219], v[210:211], s[94:95], v[218:219] op_sel:[0,1,0] op_sel_hi:[1,1,1]
	v_pk_fma_f32 v[220:221], v[212:213], s[94:95], v[220:221] op_sel:[0,1,0] op_sel_hi:[1,1,1]
	v_pk_fma_f32 v[222:223], v[214:215], s[94:95], v[222:223] op_sel:[0,1,0] op_sel_hi:[1,1,1]
	v_pk_add_f32 v[200:201], v[200:201], v[216:217] neg_lo:[0,1] neg_hi:[0,1]
	v_pk_add_f32 v[202:203], v[202:203], v[218:219] neg_lo:[0,1] neg_hi:[0,1]
	v_pk_add_f32 v[204:205], v[204:205], v[220:221] neg_lo:[0,1] neg_hi:[0,1]
	v_pk_add_f32 v[206:207], v[206:207], v[222:223] neg_lo:[0,1] neg_hi:[0,1]
	v_pk_mul_f32 v[192:193], v[200:201], s[96:97] op_sel_hi:[1,0]
	v_pk_mul_f32 v[194:195], v[202:203], s[96:97] op_sel_hi:[1,0]
	v_pk_mul_f32 v[196:197], v[204:205], s[96:97] op_sel_hi:[1,0]
	v_pk_mul_f32 v[198:199], v[206:207], s[96:97] op_sel_hi:[1,0]
	v_cvt_pk_bf16_f32 v208, v184, v185
	v_cvt_pk_bf16_f32 v209, v186, v187
	v_cvt_pk_bf16_f32 v210, v188, v189
	v_cvt_pk_bf16_f32 v211, v190, v191
	v_cvt_pk_bf16_f32 v212, v192, v193
	v_cvt_pk_bf16_f32 v213, v194, v195
	v_cvt_pk_bf16_f32 v214, v196, v197
	v_cvt_pk_bf16_f32 v215, v198, v199
	v_mov_b32_dpp v216, v208 quad_perm:[1,0,3,2] row_mask:0xf bank_mask:0xf bound_ctrl:1
	v_mov_b32_dpp v217, v209 quad_perm:[1,0,3,2] row_mask:0xf bank_mask:0xf bound_ctrl:1
	v_mov_b32_dpp v218, v210 quad_perm:[1,0,3,2] row_mask:0xf bank_mask:0xf bound_ctrl:1
	v_mov_b32_dpp v219, v211 quad_perm:[1,0,3,2] row_mask:0xf bank_mask:0xf bound_ctrl:1
	v_mov_b32_dpp v220, v212 quad_perm:[1,0,3,2] row_mask:0xf bank_mask:0xf bound_ctrl:1
	v_mov_b32_dpp v221, v213 quad_perm:[1,0,3,2] row_mask:0xf bank_mask:0xf bound_ctrl:1
	v_mov_b32_dpp v222, v214 quad_perm:[1,0,3,2] row_mask:0xf bank_mask:0xf bound_ctrl:1
	v_mov_b32_dpp v223, v215 quad_perm:[1,0,3,2] row_mask:0xf bank_mask:0xf bound_ctrl:1
	v_perm_b32 v208, v216, v208, v164
	v_perm_b32 v209, v217, v209, v164
	v_perm_b32 v210, v218, v210, v164
	v_perm_b32 v211, v219, v211, v164
	v_perm_b32 v212, v220, v212, v164
	v_perm_b32 v213, v221, v213, v164
	v_perm_b32 v214, v222, v214, v164
	v_perm_b32 v215, v223, v215, v164
	global_store_dword v167, v208, s[8:9]
	global_store_dword v167, v209, s[8:9] offset:1024
	global_store_dword v167, v210, s[8:9] offset:32
	global_store_dword v167, v211, s[8:9] offset:1056
	global_store_dword v167, v212, s[8:9] offset:256
	global_store_dword v167, v213, s[8:9] offset:1280
	global_store_dword v167, v214, s[8:9] offset:288
	global_store_dword v167, v215, s[8:9] offset:1312
	ds_read_b64 v[180:181], v160 offset:57376
	v_add_u32_e32 v167, 0x10000, v163
	s_waitcnt lgkmcnt(0)
;   __device__ __forceinline__ void operator()(f32x4 (&acc)[2][2][4][2], int brow, int bcol, int wr, int wc, int fr, int fq) const {
;     ...
;             for (int bj = 0; bj < 2; ++bj)
; #pragma unroll
;               for (int n = 0; n < 2; ++n) {
;                 f32x4 z4 = {0.f, 0.f, 0.f, 0.f};
;                 z4 = __builtin_amdgcn_mfma_f32_16x16x16bf16_1k(af, bfr[bj][n], z4, 0, 0, 0);
;                 int c = bj * 128 + wc * 32 + n * 16 + fr;
;                 float bb = bias[c];
;                 float ls[4];
; #pragma unroll
;                 for (int j = 0; j < 4; ++j) {
;                   float z = z4[j] + bb;
;                   ls[j] = (fminf(z, 0.f) - __logf(1.f + __expf(-fabsf(z)))) * (1.f / 16.f);
;                 }
;                 store_rm4(dst, 256, row0, c, ls[0], ls[1], ls[2], ls[3], fr & 1);
;               }
	v_mfma_f32_16x16x16_bf16 v[184:187], v[180:181], v[168:169], 0
	v_mfma_f32_16x16x16_bf16 v[188:191], v[180:181], v[170:171], 0
	v_mfma_f32_16x16x16_bf16 v[192:195], v[180:181], v[172:173], 0
	v_mfma_f32_16x16x16_bf16 v[196:199], v[180:181], v[174:175], 0
	s_nop 7
	s_nop 1
	v_pk_add_f32 v[184:185], v[184:185], v[176:177] op_sel_hi:[1,0]
	v_pk_add_f32 v[186:187], v[186:187], v[176:177] op_sel_hi:[1,0]
	v_pk_add_f32 v[188:189], v[188:189], v[176:177] op_sel:[0,1] op_sel_hi:[1,1]
	v_pk_add_f32 v[190:191], v[190:191], v[176:177] op_sel:[0,1] op_sel_hi:[1,1]
	v_min_f32_e32 v200, 0, v184
	v_min_f32_e32 v201, 0, v185
	v_min_f32_e32 v202, 0, v186
	v_min_f32_e32 v203, 0, v187
	v_min_f32_e32 v204, 0, v188
	v_min_f32_e32 v205, 0, v189
	v_min_f32_e32 v206, 0, v190
	v_min_f32_e32 v207, 0, v191
	v_mul_f32_e64 v208, |v184|, s93
	v_mul_f32_e64 v209, |v185|, s93
	v_mul_f32_e64 v210, |v186|, s93
	v_mul_f32_e64 v211, |v187|, s93
	v_mul_f32_e64 v212, |v188|, s93
	v_mul_f32_e64 v213, |v189|, s93
	v_mul_f32_e64 v214, |v190|, s93
	v_mul_f32_e64 v215, |v191|, s93
	v_exp_f32_e32 v208, v208
	v_exp_f32_e32 v209, v209
	v_exp_f32_e32 v210, v210
	v_exp_f32_e32 v211, v211
	v_exp_f32_e32 v212, v212
	v_exp_f32_e32 v213, v213
	v_exp_f32_e32 v214, v214
	v_exp_f32_e32 v215, v215
	v_pk_add_f32 v[208:209], v[208:209], 1.0 op_sel_hi:[1,0]
	v_pk_add_f32 v[210:211], v[210:211], 1.0 op_sel_hi:[1,0]
	v_pk_add_f32 v[212:213], v[212:213], 1.0 op_sel_hi:[1,0]
	v_pk_add_f32 v[214:215], v[214:215], 1.0 op_sel_hi:[1,0]
	v_log_f32_e32 v208, v208
	v_log_f32_e32 v209, v209
	v_log_f32_e32 v210, v210
	v_log_f32_e32 v211, v211
	v_log_f32_e32 v212, v212
	v_log_f32_e32 v213, v213
	v_log_f32_e32 v214, v214
	v_log_f32_e32 v215, v215
	v_pk_mul_f32 v[216:217], v[208:209], s[94:95] op_sel:[0,1] op_sel_hi:[1,1]
	v_pk_mul_f32 v[218:219], v[210:211], s[94:95] op_sel:[0,1] op_sel_hi:[1,1]
	v_pk_mul_f32 v[220:221], v[212:213], s[94:95] op_sel:[0,1] op_sel_hi:[1,1]
	v_pk_mul_f32 v[222:223], v[214:215], s[94:95] op_sel:[0,1] op_sel_hi:[1,1]
	v_pk_fma_f32 v[216:217], v[208:209], s[94:95], v[216:217] op_sel:[0,1,0] op_sel_hi:[1,1,1] neg_lo:[0,0,1] neg_hi:[0,0,1]
	v_pk_fma_f32 v[218:219], v[210:211], s[94:95], v[218:219] op_sel:[0,1,0] op_sel_hi:[1,1,1] neg_lo:[0,0,1] neg_hi:[0,0,1]
	v_pk_fma_f32 v[220:221], v[212:213], s[94:95], v[220:221] op_sel:[0,1,0] op_sel_hi:[1,1,1] neg_lo:[0,0,1] neg_hi:[0,0,1]
	v_pk_fma_f32 v[222:223], v[214:215], s[94:95], v[222:223] op_sel:[0,1,0] op_sel_hi:[1,1,1] neg_lo:[0,0,1] neg_hi:[0,0,1]
	v_pk_fma_f32 v[216:217], v[208:209], s[94:95], v[216:217] op_sel_hi:[1,0,1]
	v_pk_fma_f32 v[218:219], v[210:211], s[94:95], v[218:219] op_sel_hi:[1,0,1]
	v_pk_fma_f32 v[220:221], v[212:213], s[94:95], v[220:221] op_sel_hi:[1,0,1]
	v_pk_fma_f32 v[222:223], v[214:215], s[94:95], v[222:223] op_sel_hi:[1,0,1]
	v_pk_fma_f32 v[216:217], v[208:209], s[94:95], v[216:217] op_sel:[0,1,0] op_sel_hi:[1,1,1]
	v_pk_fma_f32 v[218:219], v[210:211], s[94:95], v[218:219] op_sel:[0,1,0] op_sel_hi:[1,1,1]
	v_pk_fma_f32 v[220:221], v[212:213], s[94:95], v[220:221] op_sel:[0,1,0] op_sel_hi:[1,1,1]
	v_pk_fma_f32 v[222:223], v[214:215], s[94:95], v[222:223] op_sel:[0,1,0] op_sel_hi:[1,1,1]
	v_pk_add_f32 v[200:201], v[200:201], v[216:217] neg_lo:[0,1] neg_hi:[0,1]
	v_pk_add_f32 v[202:203], v[202:203], v[218:219] neg_lo:[0,1] neg_hi:[0,1]
	v_pk_add_f32 v[204:205], v[204:205], v[220:221] neg_lo:[0,1] neg_hi:[0,1]
	v_pk_add_f32 v[206:207], v[206:207], v[222:223] neg_lo:[0,1] neg_hi:[0,1]
	v_pk_mul_f32 v[184:185], v[200:201], s[96:97] op_sel_hi:[1,0]
	v_pk_mul_f32 v[186:187], v[202:203], s[96:97] op_sel_hi:[1,0]
	v_pk_mul_f32 v[188:189], v[204:205], s[96:97] op_sel_hi:[1,0]
	v_pk_mul_f32 v[190:191], v[206:207], s[96:97] op_sel_hi:[1,0]
	v_pk_add_f32 v[192:193], v[192:193], v[178:179] op_sel_hi:[1,0]
	v_pk_add_f32 v[194:195], v[194:195], v[178:179] op_sel_hi:[1,0]
	v_pk_add_f32 v[196:197], v[196:197], v[178:179] op_sel:[0,1] op_sel_hi:[1,1]
	v_pk_add_f32 v[198:199], v[198:199], v[178:179] op_sel:[0,1] op_sel_hi:[1,1]
	v_min_f32_e32 v200, 0, v192
	v_min_f32_e32 v201, 0, v193
	v_min_f32_e32 v202, 0, v194
	v_min_f32_e32 v203, 0, v195
	v_min_f32_e32 v204, 0, v196
	v_min_f32_e32 v205, 0, v197
	v_min_f32_e32 v206, 0, v198
	v_min_f32_e32 v207, 0, v199
	v_mul_f32_e64 v208, |v192|, s93
	v_mul_f32_e64 v209, |v193|, s93
	v_mul_f32_e64 v210, |v194|, s93
	v_mul_f32_e64 v211, |v195|, s93
	v_mul_f32_e64 v212, |v196|, s93
	v_mul_f32_e64 v213, |v197|, s93
	v_mul_f32_e64 v214, |v198|, s93
	v_mul_f32_e64 v215, |v199|, s93
	v_exp_f32_e32 v208, v208
	v_exp_f32_e32 v209, v209
	v_exp_f32_e32 v210, v210
	v_exp_f32_e32 v211, v211
	v_exp_f32_e32 v212, v212
	v_exp_f32_e32 v213, v213
	v_exp_f32_e32 v214, v214
	v_exp_f32_e32 v215, v215
	v_pk_add_f32 v[208:209], v[208:209], 1.0 op_sel_hi:[1,0]
	v_pk_add_f32 v[210:211], v[210:211], 1.0 op_sel_hi:[1,0]
	v_pk_add_f32 v[212:213], v[212:213], 1.0 op_sel_hi:[1,0]
	v_pk_add_f32 v[214:215], v[214:215], 1.0 op_sel_hi:[1,0]
	v_log_f32_e32 v208, v208
	v_log_f32_e32 v209, v209
	v_log_f32_e32 v210, v210
	v_log_f32_e32 v211, v211
	v_log_f32_e32 v212, v212
	v_log_f32_e32 v213, v213
	v_log_f32_e32 v214, v214
	v_log_f32_e32 v215, v215
	v_pk_mul_f32 v[216:217], v[208:209], s[94:95] op_sel:[0,1] op_sel_hi:[1,1]
	v_pk_mul_f32 v[218:219], v[210:211], s[94:95] op_sel:[0,1] op_sel_hi:[1,1]
	v_pk_mul_f32 v[220:221], v[212:213], s[94:95] op_sel:[0,1] op_sel_hi:[1,1]
	v_pk_mul_f32 v[222:223], v[214:215], s[94:95] op_sel:[0,1] op_sel_hi:[1,1]
	v_pk_fma_f32 v[216:217], v[208:209], s[94:95], v[216:217] op_sel:[0,1,0] op_sel_hi:[1,1,1] neg_lo:[0,0,1] neg_hi:[0,0,1]
; __device__ __forceinline__ void store_rm4(u16* dst, size_t ld, int row0, int c, float v0, float v1, float v2, float v3, bool odd) {
;   {
;     float s = odd ? v0 : v1, r = dpp_swap1(s);
;     float lo = odd ? r : v0, hi = odd ? v1 : r;
;     *(unsigned*)(dst + (size_t)(row0 + (odd ? 1 : 0)) * ld + (c - (odd ? 1 : 0))) = pack2(lo, hi);
;   }
;   {
;     float s = odd ? v2 : v3, r = dpp_swap1(s);
;     float lo = odd ? r : v2, hi = odd ? v3 : r;
;     *(unsigned*)(dst + (size_t)(row0 + 2 + (odd ? 1 : 0)) * ld + (c - (odd ? 1 : 0))) = pack2(lo, hi);
;   }
;   __device__ __forceinline__ void operator()(f32x4 (&acc)[2][2][4][2], int brow, int bcol, int wr, int wc, int fr, int fq) const {
;     ...
;             for (int bj = 0; bj < 2; ++bj)
; #pragma unroll
;               for (int n = 0; n < 2; ++n) {
;                 f32x4 z4 = {0.f, 0.f, 0.f, 0.f};
;                 z4 = __builtin_amdgcn_mfma_f32_16x16x16bf16_1k(af, bfr[bj][n], z4, 0, 0, 0);
;                 int c = bj * 128 + wc * 32 + n * 16 + fr;
;                 float bb = bias[c];
;                 float ls[4];
; #pragma unroll
;                 for (int j = 0; j < 4; ++j) {
;                   float z = z4[j] + bb;
;                   ls[j] = (fminf(z, 0.f) - __logf(1.f + __expf(-fabsf(z)))) * (1.f / 16.f);
;                 }
;                 store_rm4(dst, 256, row0, c, ls[0], ls[1], ls[2], ls[3], fr & 1);
;               }
	v_pk_fma_f32 v[218:219], v[210:211], s[94:95], v[218:219] op_sel:[0,1,0] op_sel_hi:[1,1,1] neg_lo:[0,0,1] neg_hi:[0,0,1]
	v_pk_fma_f32 v[220:221], v[212:213], s[94:95], v[220:221] op_sel:[0,1,0] op_sel_hi:[1,1,1] neg_lo:[0,0,1] neg_hi:[0,0,1]
	v_pk_fma_f32 v[222:223], v[214:215], s[94:95], v[222:223] op_sel:[0,1,0] op_sel_hi:[1,1,1] neg_lo:[0,0,1] neg_hi:[0,0,1]
	v_pk_fma_f32 v[216:217], v[208:209], s[94:95], v[216:217] op_sel_hi:[1,0,1]
	v_pk_fma_f32 v[218:219], v[210:211], s[94:95], v[218:219] op_sel_hi:[1,0,1]
	v_pk_fma_f32 v[220:221], v[212:213], s[94:95], v[220:221] op_sel_hi:[1,0,1]
	v_pk_fma_f32 v[222:223], v[214:215], s[94:95], v[222:223] op_sel_hi:[1,0,1]
	v_pk_fma_f32 v[216:217], v[208:209], s[94:95], v[216:217] op_sel:[0,1,0] op_sel_hi:[1,1,1]
	v_pk_fma_f32 v[218:219], v[210:211], s[94:95], v[218:219] op_sel:[0,1,0] op_sel_hi:[1,1,1]
	v_pk_fma_f32 v[220:221], v[212:213], s[94:95], v[220:221] op_sel:[0,1,0] op_sel_hi:[1,1,1]
	v_pk_fma_f32 v[222:223], v[214:215], s[94:95], v[222:223] op_sel:[0,1,0] op_sel_hi:[1,1,1]
	v_pk_add_f32 v[200:201], v[200:201], v[216:217] neg_lo:[0,1] neg_hi:[0,1]
	v_pk_add_f32 v[202:203], v[202:203], v[218:219] neg_lo:[0,1] neg_hi:[0,1]
	v_pk_add_f32 v[204:205], v[204:205], v[220:221] neg_lo:[0,1] neg_hi:[0,1]
	v_pk_add_f32 v[206:207], v[206:207], v[222:223] neg_lo:[0,1] neg_hi:[0,1]
	v_pk_mul_f32 v[192:193], v[200:201], s[96:97] op_sel_hi:[1,0]
	v_pk_mul_f32 v[194:195], v[202:203], s[96:97] op_sel_hi:[1,0]
	v_pk_mul_f32 v[196:197], v[204:205], s[96:97] op_sel_hi:[1,0]
	v_pk_mul_f32 v[198:199], v[206:207], s[96:97] op_sel_hi:[1,0]
	v_cvt_pk_bf16_f32 v208, v184, v185
	v_cvt_pk_bf16_f32 v209, v186, v187
	v_cvt_pk_bf16_f32 v210, v188, v189
	v_cvt_pk_bf16_f32 v211, v190, v191
	v_cvt_pk_bf16_f32 v212, v192, v193
	v_cvt_pk_bf16_f32 v213, v194, v195
	v_cvt_pk_bf16_f32 v214, v196, v197
	v_cvt_pk_bf16_f32 v215, v198, v199
	v_mov_b32_dpp v216, v208 quad_perm:[1,0,3,2] row_mask:0xf bank_mask:0xf bound_ctrl:1
	v_mov_b32_dpp v217, v209 quad_perm:[1,0,3,2] row_mask:0xf bank_mask:0xf bound_ctrl:1
	v_mov_b32_dpp v218, v210 quad_perm:[1,0,3,2] row_mask:0xf bank_mask:0xf bound_ctrl:1
	v_mov_b32_dpp v219, v211 quad_perm:[1,0,3,2] row_mask:0xf bank_mask:0xf bound_ctrl:1
	v_mov_b32_dpp v220, v212 quad_perm:[1,0,3,2] row_mask:0xf bank_mask:0xf bound_ctrl:1
	v_mov_b32_dpp v221, v213 quad_perm:[1,0,3,2] row_mask:0xf bank_mask:0xf bound_ctrl:1
	v_mov_b32_dpp v222, v214 quad_perm:[1,0,3,2] row_mask:0xf bank_mask:0xf bound_ctrl:1
	v_mov_b32_dpp v223, v215 quad_perm:[1,0,3,2] row_mask:0xf bank_mask:0xf bound_ctrl:1
	v_perm_b32 v208, v216, v208, v164
	v_perm_b32 v209, v217, v209, v164
	v_perm_b32 v210, v218, v210, v164
	v_perm_b32 v211, v219, v211, v164
	v_perm_b32 v212, v220, v212, v164
	v_perm_b32 v213, v221, v213, v164
	v_perm_b32 v214, v222, v214, v164
	v_perm_b32 v215, v223, v215, v164
	global_store_dword v167, v208, s[8:9]
	global_store_dword v167, v209, s[8:9] offset:1024
	global_store_dword v167, v210, s[8:9] offset:32
	global_store_dword v167, v211, s[8:9] offset:1056
	global_store_dword v167, v212, s[8:9] offset:256
	global_store_dword v167, v213, s[8:9] offset:1280
	global_store_dword v167, v214, s[8:9] offset:288
	global_store_dword v167, v215, s[8:9] offset:1312
	ds_read_b64 v[180:181], v160 offset:58400
	v_add_u32_e32 v167, 0x12000, v163
	s_waitcnt lgkmcnt(0)
	v_mfma_f32_16x16x16_bf16 v[184:187], v[180:181], v[168:169], 0
	v_mfma_f32_16x16x16_bf16 v[188:191], v[180:181], v[170:171], 0
	v_mfma_f32_16x16x16_bf16 v[192:195], v[180:181], v[172:173], 0
	v_mfma_f32_16x16x16_bf16 v[196:199], v[180:181], v[174:175], 0
	s_nop 7
	s_nop 1
	v_pk_add_f32 v[184:185], v[184:185], v[176:177] op_sel_hi:[1,0]
	v_pk_add_f32 v[186:187], v[186:187], v[176:177] op_sel_hi:[1,0]
	v_pk_add_f32 v[188:189], v[188:189], v[176:177] op_sel:[0,1] op_sel_hi:[1,1]
	v_pk_add_f32 v[190:191], v[190:191], v[176:177] op_sel:[0,1] op_sel_hi:[1,1]
	v_min_f32_e32 v200, 0, v184
	v_min_f32_e32 v201, 0, v185
	v_min_f32_e32 v202, 0, v186
	v_min_f32_e32 v203, 0, v187
	v_min_f32_e32 v204, 0, v188
	v_min_f32_e32 v205, 0, v189
	v_min_f32_e32 v206, 0, v190
	v_min_f32_e32 v207, 0, v191
	v_mul_f32_e64 v208, |v184|, s93
	v_mul_f32_e64 v209, |v185|, s93
	v_mul_f32_e64 v210, |v186|, s93
	v_mul_f32_e64 v211, |v187|, s93
	v_mul_f32_e64 v212, |v188|, s93
	v_mul_f32_e64 v213, |v189|, s93
	v_mul_f32_e64 v214, |v190|, s93
	v_mul_f32_e64 v215, |v191|, s93
	v_exp_f32_e32 v208, v208
	v_exp_f32_e32 v209, v209
	v_exp_f32_e32 v210, v210
	v_exp_f32_e32 v211, v211
	v_exp_f32_e32 v212, v212
	v_exp_f32_e32 v213, v213
	v_exp_f32_e32 v214, v214
	v_exp_f32_e32 v215, v215
	v_pk_add_f32 v[208:209], v[208:209], 1.0 op_sel_hi:[1,0]
	v_pk_add_f32 v[210:211], v[210:211], 1.0 op_sel_hi:[1,0]
	v_pk_add_f32 v[212:213], v[212:213], 1.0 op_sel_hi:[1,0]
	v_pk_add_f32 v[214:215], v[214:215], 1.0 op_sel_hi:[1,0]
	v_log_f32_e32 v208, v208
	v_log_f32_e32 v209, v209
	v_log_f32_e32 v210, v210
	v_log_f32_e32 v211, v211
	v_log_f32_e32 v212, v212
	v_log_f32_e32 v213, v213
	v_log_f32_e32 v214, v214
	v_log_f32_e32 v215, v215
	v_pk_mul_f32 v[216:217], v[208:209], s[94:95] op_sel:[0,1] op_sel_hi:[1,1]
	v_pk_mul_f32 v[218:219], v[210:211], s[94:95] op_sel:[0,1] op_sel_hi:[1,1]
	v_pk_mul_f32 v[220:221], v[212:213], s[94:95] op_sel:[0,1] op_sel_hi:[1,1]
	v_pk_mul_f32 v[222:223], v[214:215], s[94:95] op_sel:[0,1] op_sel_hi:[1,1]
	v_pk_fma_f32 v[216:217], v[208:209], s[94:95], v[216:217] op_sel:[0,1,0] op_sel_hi:[1,1,1] neg_lo:[0,0,1] neg_hi:[0,0,1]
	v_pk_fma_f32 v[218:219], v[210:211], s[94:95], v[218:219] op_sel:[0,1,0] op_sel_hi:[1,1,1] neg_lo:[0,0,1] neg_hi:[0,0,1]
; __device__ __forceinline__ void store_rm4(u16* dst, size_t ld, int row0, int c, float v0, float v1, float v2, float v3, bool odd) {
;   {
;     float s = odd ? v0 : v1, r = dpp_swap1(s);
;     float lo = odd ? r : v0, hi = odd ? v1 : r;
;     *(unsigned*)(dst + (size_t)(row0 + (odd ? 1 : 0)) * ld + (c - (odd ? 1 : 0))) = pack2(lo, hi);
;   }
;   {
;     float s = odd ? v2 : v3, r = dpp_swap1(s);
;     float lo = odd ? r : v2, hi = odd ? v3 : r;
;     *(unsigned*)(dst + (size_t)(row0 + 2 + (odd ? 1 : 0)) * ld + (c - (odd ? 1 : 0))) = pack2(lo, hi);
;   }
;   __device__ __forceinline__ void operator()(f32x4 (&acc)[2][2][4][2], int brow, int bcol, int wr, int wc, int fr, int fq) const {
;     ...
;             for (int bj = 0; bj < 2; ++bj)
; #pragma unroll
;               for (int n = 0; n < 2; ++n) {
;                 f32x4 z4 = {0.f, 0.f, 0.f, 0.f};
;                 z4 = __builtin_amdgcn_mfma_f32_16x16x16bf16_1k(af, bfr[bj][n], z4, 0, 0, 0);
;                 int c = bj * 128 + wc * 32 + n * 16 + fr;
;                 float bb = bias[c];
;                 float ls[4];
; #pragma unroll
;                 for (int j = 0; j < 4; ++j) {
;                   float z = z4[j] + bb;
;                   ls[j] = (fminf(z, 0.f) - __logf(1.f + __expf(-fabsf(z)))) * (1.f / 16.f);
;                 }
;                 store_rm4(dst, 256, row0, c, ls[0], ls[1], ls[2], ls[3], fr & 1);
;               }
	v_pk_fma_f32 v[220:221], v[212:213], s[94:95], v[220:221] op_sel:[0,1,0] op_sel_hi:[1,1,1] neg_lo:[0,0,1] neg_hi:[0,0,1]
	v_pk_fma_f32 v[222:223], v[214:215], s[94:95], v[222:223] op_sel:[0,1,0] op_sel_hi:[1,1,1] neg_lo:[0,0,1] neg_hi:[0,0,1]
	v_pk_fma_f32 v[216:217], v[208:209], s[94:95], v[216:217] op_sel_hi:[1,0,1]
	v_pk_fma_f32 v[218:219], v[210:211], s[94:95], v[218:219] op_sel_hi:[1,0,1]
	v_pk_fma_f32 v[220:221], v[212:213], s[94:95], v[220:221] op_sel_hi:[1,0,1]
	v_pk_fma_f32 v[222:223], v[214:215], s[94:95], v[222:223] op_sel_hi:[1,0,1]
	v_pk_fma_f32 v[216:217], v[208:209], s[94:95], v[216:217] op_sel:[0,1,0] op_sel_hi:[1,1,1]
	v_pk_fma_f32 v[218:219], v[210:211], s[94:95], v[218:219] op_sel:[0,1,0] op_sel_hi:[1,1,1]
	v_pk_fma_f32 v[220:221], v[212:213], s[94:95], v[220:221] op_sel:[0,1,0] op_sel_hi:[1,1,1]
	v_pk_fma_f32 v[222:223], v[214:215], s[94:95], v[222:223] op_sel:[0,1,0] op_sel_hi:[1,1,1]
	v_pk_add_f32 v[200:201], v[200:201], v[216:217] neg_lo:[0,1] neg_hi:[0,1]
	v_pk_add_f32 v[202:203], v[202:203], v[218:219] neg_lo:[0,1] neg_hi:[0,1]
	v_pk_add_f32 v[204:205], v[204:205], v[220:221] neg_lo:[0,1] neg_hi:[0,1]
	v_pk_add_f32 v[206:207], v[206:207], v[222:223] neg_lo:[0,1] neg_hi:[0,1]
	v_pk_mul_f32 v[184:185], v[200:201], s[96:97] op_sel_hi:[1,0]
	v_pk_mul_f32 v[186:187], v[202:203], s[96:97] op_sel_hi:[1,0]
	v_pk_mul_f32 v[188:189], v[204:205], s[96:97] op_sel_hi:[1,0]
	v_pk_mul_f32 v[190:191], v[206:207], s[96:97] op_sel_hi:[1,0]
	v_pk_add_f32 v[192:193], v[192:193], v[178:179] op_sel_hi:[1,0]
	v_pk_add_f32 v[194:195], v[194:195], v[178:179] op_sel_hi:[1,0]
	v_pk_add_f32 v[196:197], v[196:197], v[178:179] op_sel:[0,1] op_sel_hi:[1,1]
	v_pk_add_f32 v[198:199], v[198:199], v[178:179] op_sel:[0,1] op_sel_hi:[1,1]
	v_min_f32_e32 v200, 0, v192
	v_min_f32_e32 v201, 0, v193
	v_min_f32_e32 v202, 0, v194
	v_min_f32_e32 v203, 0, v195
	v_min_f32_e32 v204, 0, v196
	v_min_f32_e32 v205, 0, v197
	v_min_f32_e32 v206, 0, v198
	v_min_f32_e32 v207, 0, v199
	v_mul_f32_e64 v208, |v192|, s93
	v_mul_f32_e64 v209, |v193|, s93
	v_mul_f32_e64 v210, |v194|, s93
	v_mul_f32_e64 v211, |v195|, s93
	v_mul_f32_e64 v212, |v196|, s93
	v_mul_f32_e64 v213, |v197|, s93
	v_mul_f32_e64 v214, |v198|, s93
	v_mul_f32_e64 v215, |v199|, s93
	v_exp_f32_e32 v208, v208
	v_exp_f32_e32 v209, v209
	v_exp_f32_e32 v210, v210
	v_exp_f32_e32 v211, v211
	v_exp_f32_e32 v212, v212
	v_exp_f32_e32 v213, v213
	v_exp_f32_e32 v214, v214
	v_exp_f32_e32 v215, v215
	v_pk_add_f32 v[208:209], v[208:209], 1.0 op_sel_hi:[1,0]
	v_pk_add_f32 v[210:211], v[210:211], 1.0 op_sel_hi:[1,0]
	v_pk_add_f32 v[212:213], v[212:213], 1.0 op_sel_hi:[1,0]
	v_pk_add_f32 v[214:215], v[214:215], 1.0 op_sel_hi:[1,0]
	v_log_f32_e32 v208, v208
	v_log_f32_e32 v209, v209
	v_log_f32_e32 v210, v210
	v_log_f32_e32 v211, v211
	v_log_f32_e32 v212, v212
	v_log_f32_e32 v213, v213
	v_log_f32_e32 v214, v214
	v_log_f32_e32 v215, v215
	v_pk_mul_f32 v[216:217], v[208:209], s[94:95] op_sel:[0,1] op_sel_hi:[1,1]
	v_pk_mul_f32 v[218:219], v[210:211], s[94:95] op_sel:[0,1] op_sel_hi:[1,1]
	v_pk_mul_f32 v[220:221], v[212:213], s[94:95] op_sel:[0,1] op_sel_hi:[1,1]
	v_pk_mul_f32 v[222:223], v[214:215], s[94:95] op_sel:[0,1] op_sel_hi:[1,1]
	v_pk_fma_f32 v[216:217], v[208:209], s[94:95], v[216:217] op_sel:[0,1,0] op_sel_hi:[1,1,1] neg_lo:[0,0,1] neg_hi:[0,0,1]
	v_pk_fma_f32 v[218:219], v[210:211], s[94:95], v[218:219] op_sel:[0,1,0] op_sel_hi:[1,1,1] neg_lo:[0,0,1] neg_hi:[0,0,1]
	v_pk_fma_f32 v[220:221], v[212:213], s[94:95], v[220:221] op_sel:[0,1,0] op_sel_hi:[1,1,1] neg_lo:[0,0,1] neg_hi:[0,0,1]
	v_pk_fma_f32 v[222:223], v[214:215], s[94:95], v[222:223] op_sel:[0,1,0] op_sel_hi:[1,1,1] neg_lo:[0,0,1] neg_hi:[0,0,1]
	v_pk_fma_f32 v[216:217], v[208:209], s[94:95], v[216:217] op_sel_hi:[1,0,1]
	v_pk_fma_f32 v[218:219], v[210:211], s[94:95], v[218:219] op_sel_hi:[1,0,1]
	v_pk_fma_f32 v[220:221], v[212:213], s[94:95], v[220:221] op_sel_hi:[1,0,1]
	v_pk_fma_f32 v[222:223], v[214:215], s[94:95], v[222:223] op_sel_hi:[1,0,1]
	v_pk_fma_f32 v[216:217], v[208:209], s[94:95], v[216:217] op_sel:[0,1,0] op_sel_hi:[1,1,1]
	v_pk_fma_f32 v[218:219], v[210:211], s[94:95], v[218:219] op_sel:[0,1,0] op_sel_hi:[1,1,1]
	v_pk_fma_f32 v[220:221], v[212:213], s[94:95], v[220:221] op_sel:[0,1,0] op_sel_hi:[1,1,1]
	v_pk_fma_f32 v[222:223], v[214:215], s[94:95], v[222:223] op_sel:[0,1,0] op_sel_hi:[1,1,1]
	v_pk_add_f32 v[200:201], v[200:201], v[216:217] neg_lo:[0,1] neg_hi:[0,1]
	v_pk_add_f32 v[202:203], v[202:203], v[218:219] neg_lo:[0,1] neg_hi:[0,1]
	v_pk_add_f32 v[204:205], v[204:205], v[220:221] neg_lo:[0,1] neg_hi:[0,1]
	v_pk_add_f32 v[206:207], v[206:207], v[222:223] neg_lo:[0,1] neg_hi:[0,1]
	v_pk_mul_f32 v[192:193], v[200:201], s[96:97] op_sel_hi:[1,0]
	v_pk_mul_f32 v[194:195], v[202:203], s[96:97] op_sel_hi:[1,0]
	v_pk_mul_f32 v[196:197], v[204:205], s[96:97] op_sel_hi:[1,0]
	v_pk_mul_f32 v[198:199], v[206:207], s[96:97] op_sel_hi:[1,0]
	v_cvt_pk_bf16_f32 v208, v184, v185
	v_cvt_pk_bf16_f32 v209, v186, v187
	v_cvt_pk_bf16_f32 v210, v188, v189
	v_cvt_pk_bf16_f32 v211, v190, v191
	v_cvt_pk_bf16_f32 v212, v192, v193
	v_cvt_pk_bf16_f32 v213, v194, v195
	v_cvt_pk_bf16_f32 v214, v196, v197
	v_cvt_pk_bf16_f32 v215, v198, v199
	v_mov_b32_dpp v216, v208 quad_perm:[1,0,3,2] row_mask:0xf bank_mask:0xf bound_ctrl:1
	v_mov_b32_dpp v217, v209 quad_perm:[1,0,3,2] row_mask:0xf bank_mask:0xf bound_ctrl:1
	v_mov_b32_dpp v218, v210 quad_perm:[1,0,3,2] row_mask:0xf bank_mask:0xf bound_ctrl:1
	v_mov_b32_dpp v219, v211 quad_perm:[1,0,3,2] row_mask:0xf bank_mask:0xf bound_ctrl:1
	v_mov_b32_dpp v220, v212 quad_perm:[1,0,3,2] row_mask:0xf bank_mask:0xf bound_ctrl:1
	v_mov_b32_dpp v221, v213 quad_perm:[1,0,3,2] row_mask:0xf bank_mask:0xf bound_ctrl:1
	v_mov_b32_dpp v222, v214 quad_perm:[1,0,3,2] row_mask:0xf bank_mask:0xf bound_ctrl:1
	v_mov_b32_dpp v223, v215 quad_perm:[1,0,3,2] row_mask:0xf bank_mask:0xf bound_ctrl:1
	v_perm_b32 v208, v216, v208, v164
	v_perm_b32 v209, v217, v209, v164
	v_perm_b32 v210, v218, v210, v164
	v_perm_b32 v211, v219, v211, v164
	v_perm_b32 v212, v220, v212, v164
	v_perm_b32 v213, v221, v213, v164
	v_perm_b32 v214, v222, v214, v164
	v_perm_b32 v215, v223, v215, v164
	global_store_dword v167, v208, s[8:9]
	global_store_dword v167, v209, s[8:9] offset:1024
	global_store_dword v167, v210, s[8:9] offset:32
	global_store_dword v167, v211, s[8:9] offset:1056
	global_store_dword v167, v212, s[8:9] offset:256
	global_store_dword v167, v213, s[8:9] offset:1280
	global_store_dword v167, v214, s[8:9] offset:288
	global_store_dword v167, v215, s[8:9] offset:1312
	ds_read_b64 v[180:181], v160 offset:59424
	v_add_u32_e32 v167, 0x14000, v163
	s_waitcnt lgkmcnt(0)
;   __device__ __forceinline__ void operator()(f32x4 (&acc)[2][2][4][2], int brow, int bcol, int wr, int wc, int fr, int fq) const {
;     ...
;             s16x4 af = *(const s16x4*)(glr + (rl + fr) * 32 + dir * 16 + fq * 4);
;             int row0 = brow + rl + fq * 4;
; #pragma unroll
;             for (int bj = 0; bj < 2; ++bj)
; #pragma unroll
;               for (int n = 0; n < 2; ++n) {
;                 f32x4 z4 = {0.f, 0.f, 0.f, 0.f};
;                 z4 = __builtin_amdgcn_mfma_f32_16x16x16bf16_1k(af, bfr[bj][n], z4, 0, 0, 0);
;                 int c = bj * 128 + wc * 32 + n * 16 + fr;
;                 float bb = bias[c];
;                 float ls[4];
; #pragma unroll
;                 for (int j = 0; j < 4; ++j) {
;                   float z = z4[j] + bb;
;                   ls[j] = (fminf(z, 0.f) - __logf(1.f + __expf(-fabsf(z)))) * (1.f / 16.f);
;                 }
;                 store_rm4(dst, 256, row0, c, ls[0], ls[1], ls[2], ls[3], fr & 1);
	v_mfma_f32_16x16x16_bf16 v[184:187], v[180:181], v[168:169], 0
	v_mfma_f32_16x16x16_bf16 v[188:191], v[180:181], v[170:171], 0
	v_mfma_f32_16x16x16_bf16 v[192:195], v[180:181], v[172:173], 0
	v_mfma_f32_16x16x16_bf16 v[196:199], v[180:181], v[174:175], 0
	s_nop 7
	s_nop 1
	v_pk_add_f32 v[184:185], v[184:185], v[176:177] op_sel_hi:[1,0]
	v_pk_add_f32 v[186:187], v[186:187], v[176:177] op_sel_hi:[1,0]
	v_pk_add_f32 v[188:189], v[188:189], v[176:177] op_sel:[0,1] op_sel_hi:[1,1]
	v_pk_add_f32 v[190:191], v[190:191], v[176:177] op_sel:[0,1] op_sel_hi:[1,1]
	v_min_f32_e32 v200, 0, v184
	v_min_f32_e32 v201, 0, v185
	v_min_f32_e32 v202, 0, v186
	v_min_f32_e32 v203, 0, v187
	v_min_f32_e32 v204, 0, v188
	v_min_f32_e32 v205, 0, v189
	v_min_f32_e32 v206, 0, v190
	v_min_f32_e32 v207, 0, v191
	v_mul_f32_e64 v208, |v184|, s93
	v_mul_f32_e64 v209, |v185|, s93
	v_mul_f32_e64 v210, |v186|, s93
	v_mul_f32_e64 v211, |v187|, s93
	v_mul_f32_e64 v212, |v188|, s93
	v_mul_f32_e64 v213, |v189|, s93
	v_mul_f32_e64 v214, |v190|, s93
	v_mul_f32_e64 v215, |v191|, s93
	v_exp_f32_e32 v208, v208
	v_exp_f32_e32 v209, v209
	v_exp_f32_e32 v210, v210
	v_exp_f32_e32 v211, v211
	v_exp_f32_e32 v212, v212
	v_exp_f32_e32 v213, v213
	v_exp_f32_e32 v214, v214
	v_exp_f32_e32 v215, v215
	v_pk_add_f32 v[208:209], v[208:209], 1.0 op_sel_hi:[1,0]
	v_pk_add_f32 v[210:211], v[210:211], 1.0 op_sel_hi:[1,0]
	v_pk_add_f32 v[212:213], v[212:213], 1.0 op_sel_hi:[1,0]
	v_pk_add_f32 v[214:215], v[214:215], 1.0 op_sel_hi:[1,0]
	v_log_f32_e32 v208, v208
	v_log_f32_e32 v209, v209
	v_log_f32_e32 v210, v210
	v_log_f32_e32 v211, v211
	v_log_f32_e32 v212, v212
	v_log_f32_e32 v213, v213
	v_log_f32_e32 v214, v214
	v_log_f32_e32 v215, v215
	v_pk_mul_f32 v[216:217], v[208:209], s[94:95] op_sel:[0,1] op_sel_hi:[1,1]
	v_pk_mul_f32 v[218:219], v[210:211], s[94:95] op_sel:[0,1] op_sel_hi:[1,1]
	v_pk_mul_f32 v[220:221], v[212:213], s[94:95] op_sel:[0,1] op_sel_hi:[1,1]
	v_pk_mul_f32 v[222:223], v[214:215], s[94:95] op_sel:[0,1] op_sel_hi:[1,1]
	v_pk_fma_f32 v[216:217], v[208:209], s[94:95], v[216:217] op_sel:[0,1,0] op_sel_hi:[1,1,1] neg_lo:[0,0,1] neg_hi:[0,0,1]
	v_pk_fma_f32 v[218:219], v[210:211], s[94:95], v[218:219] op_sel:[0,1,0] op_sel_hi:[1,1,1] neg_lo:[0,0,1] neg_hi:[0,0,1]
	v_pk_fma_f32 v[220:221], v[212:213], s[94:95], v[220:221] op_sel:[0,1,0] op_sel_hi:[1,1,1] neg_lo:[0,0,1] neg_hi:[0,0,1]
	v_pk_fma_f32 v[222:223], v[214:215], s[94:95], v[222:223] op_sel:[0,1,0] op_sel_hi:[1,1,1] neg_lo:[0,0,1] neg_hi:[0,0,1]
	v_pk_fma_f32 v[216:217], v[208:209], s[94:95], v[216:217] op_sel_hi:[1,0,1]
	v_pk_fma_f32 v[218:219], v[210:211], s[94:95], v[218:219] op_sel_hi:[1,0,1]
	v_pk_fma_f32 v[220:221], v[212:213], s[94:95], v[220:221] op_sel_hi:[1,0,1]
	v_pk_fma_f32 v[222:223], v[214:215], s[94:95], v[222:223] op_sel_hi:[1,0,1]
	v_pk_fma_f32 v[216:217], v[208:209], s[94:95], v[216:217] op_sel:[0,1,0] op_sel_hi:[1,1,1]
	v_pk_fma_f32 v[218:219], v[210:211], s[94:95], v[218:219] op_sel:[0,1,0] op_sel_hi:[1,1,1]
	v_pk_fma_f32 v[220:221], v[212:213], s[94:95], v[220:221] op_sel:[0,1,0] op_sel_hi:[1,1,1]
	v_pk_fma_f32 v[222:223], v[214:215], s[94:95], v[222:223] op_sel:[0,1,0] op_sel_hi:[1,1,1]
	v_pk_add_f32 v[200:201], v[200:201], v[216:217] neg_lo:[0,1] neg_hi:[0,1]
	v_pk_add_f32 v[202:203], v[202:203], v[218:219] neg_lo:[0,1] neg_hi:[0,1]
	v_pk_add_f32 v[204:205], v[204:205], v[220:221] neg_lo:[0,1] neg_hi:[0,1]
	v_pk_add_f32 v[206:207], v[206:207], v[222:223] neg_lo:[0,1] neg_hi:[0,1]
	v_pk_mul_f32 v[184:185], v[200:201], s[96:97] op_sel_hi:[1,0]
	v_pk_mul_f32 v[186:187], v[202:203], s[96:97] op_sel_hi:[1,0]
	v_pk_mul_f32 v[188:189], v[204:205], s[96:97] op_sel_hi:[1,0]
	v_pk_mul_f32 v[190:191], v[206:207], s[96:97] op_sel_hi:[1,0]
	v_pk_add_f32 v[192:193], v[192:193], v[178:179] op_sel_hi:[1,0]
	v_pk_add_f32 v[194:195], v[194:195], v[178:179] op_sel_hi:[1,0]
	v_pk_add_f32 v[196:197], v[196:197], v[178:179] op_sel:[0,1] op_sel_hi:[1,1]
	v_pk_add_f32 v[198:199], v[198:199], v[178:179] op_sel:[0,1] op_sel_hi:[1,1]
	v_min_f32_e32 v200, 0, v192
	v_min_f32_e32 v201, 0, v193
	v_min_f32_e32 v202, 0, v194
	v_min_f32_e32 v203, 0, v195
	v_min_f32_e32 v204, 0, v196
	v_min_f32_e32 v205, 0, v197
	v_min_f32_e32 v206, 0, v198
	v_min_f32_e32 v207, 0, v199
	v_mul_f32_e64 v208, |v192|, s93
	v_mul_f32_e64 v209, |v193|, s93
	v_mul_f32_e64 v210, |v194|, s93
	v_mul_f32_e64 v211, |v195|, s93
	v_mul_f32_e64 v212, |v196|, s93
	v_mul_f32_e64 v213, |v197|, s93
	v_mul_f32_e64 v214, |v198|, s93
	v_mul_f32_e64 v215, |v199|, s93
	v_exp_f32_e32 v208, v208
	v_exp_f32_e32 v209, v209
	v_exp_f32_e32 v210, v210
	v_exp_f32_e32 v211, v211
	v_exp_f32_e32 v212, v212
	v_exp_f32_e32 v213, v213
	v_exp_f32_e32 v214, v214
	v_exp_f32_e32 v215, v215
	v_pk_add_f32 v[208:209], v[208:209], 1.0 op_sel_hi:[1,0]
	v_pk_add_f32 v[210:211], v[210:211], 1.0 op_sel_hi:[1,0]
	v_pk_add_f32 v[212:213], v[212:213], 1.0 op_sel_hi:[1,0]
	v_pk_add_f32 v[214:215], v[214:215], 1.0 op_sel_hi:[1,0]
	v_log_f32_e32 v208, v208
	v_log_f32_e32 v209, v209
	v_log_f32_e32 v210, v210
	v_log_f32_e32 v211, v211
	v_log_f32_e32 v212, v212
	v_log_f32_e32 v213, v213
	v_log_f32_e32 v214, v214
	v_log_f32_e32 v215, v215
	v_pk_mul_f32 v[216:217], v[208:209], s[94:95] op_sel:[0,1] op_sel_hi:[1,1]
	v_pk_mul_f32 v[218:219], v[210:211], s[94:95] op_sel:[0,1] op_sel_hi:[1,1]
	v_pk_mul_f32 v[220:221], v[212:213], s[94:95] op_sel:[0,1] op_sel_hi:[1,1]
	v_pk_mul_f32 v[222:223], v[214:215], s[94:95] op_sel:[0,1] op_sel_hi:[1,1]
	v_pk_fma_f32 v[216:217], v[208:209], s[94:95], v[216:217] op_sel:[0,1,0] op_sel_hi:[1,1,1] neg_lo:[0,0,1] neg_hi:[0,0,1]
;   __device__ __forceinline__ void operator()(f32x4 (&acc)[2][2][4][2], int brow, int bcol, int wr, int wc, int fr, int fq) const {
;     ...
;             s16x4 af = *(const s16x4*)(glr + (rl + fr) * 32 + dir * 16 + fq * 4);
;             int row0 = brow + rl + fq * 4;
; #pragma unroll
;             for (int bj = 0; bj < 2; ++bj)
; #pragma unroll
;               for (int n = 0; n < 2; ++n) {
;                 f32x4 z4 = {0.f, 0.f, 0.f, 0.f};
;                 z4 = __builtin_amdgcn_mfma_f32_16x16x16bf16_1k(af, bfr[bj][n], z4, 0, 0, 0);
;                 int c = bj * 128 + wc * 32 + n * 16 + fr;
;                 float bb = bias[c];
;                 float ls[4];
; #pragma unroll
;                 for (int j = 0; j < 4; ++j) {
;                   float z = z4[j] + bb;
;                   ls[j] = (fminf(z, 0.f) - __logf(1.f + __expf(-fabsf(z)))) * (1.f / 16.f);
;                 }
;                 store_rm4(dst, 256, row0, c, ls[0], ls[1], ls[2], ls[3], fr & 1);
	v_pk_fma_f32 v[218:219], v[210:211], s[94:95], v[218:219] op_sel:[0,1,0] op_sel_hi:[1,1,1] neg_lo:[0,0,1] neg_hi:[0,0,1]
	v_pk_fma_f32 v[220:221], v[212:213], s[94:95], v[220:221] op_sel:[0,1,0] op_sel_hi:[1,1,1] neg_lo:[0,0,1] neg_hi:[0,0,1]
	v_pk_fma_f32 v[222:223], v[214:215], s[94:95], v[222:223] op_sel:[0,1,0] op_sel_hi:[1,1,1] neg_lo:[0,0,1] neg_hi:[0,0,1]
	v_pk_fma_f32 v[216:217], v[208:209], s[94:95], v[216:217] op_sel_hi:[1,0,1]
	v_pk_fma_f32 v[218:219], v[210:211], s[94:95], v[218:219] op_sel_hi:[1,0,1]
	v_pk_fma_f32 v[220:221], v[212:213], s[94:95], v[220:221] op_sel_hi:[1,0,1]
	v_pk_fma_f32 v[222:223], v[214:215], s[94:95], v[222:223] op_sel_hi:[1,0,1]
	v_pk_fma_f32 v[216:217], v[208:209], s[94:95], v[216:217] op_sel:[0,1,0] op_sel_hi:[1,1,1]
	v_pk_fma_f32 v[218:219], v[210:211], s[94:95], v[218:219] op_sel:[0,1,0] op_sel_hi:[1,1,1]
	v_pk_fma_f32 v[220:221], v[212:213], s[94:95], v[220:221] op_sel:[0,1,0] op_sel_hi:[1,1,1]
	v_pk_fma_f32 v[222:223], v[214:215], s[94:95], v[222:223] op_sel:[0,1,0] op_sel_hi:[1,1,1]
	v_pk_add_f32 v[200:201], v[200:201], v[216:217] neg_lo:[0,1] neg_hi:[0,1]
	v_pk_add_f32 v[202:203], v[202:203], v[218:219] neg_lo:[0,1] neg_hi:[0,1]
	v_pk_add_f32 v[204:205], v[204:205], v[220:221] neg_lo:[0,1] neg_hi:[0,1]
	v_pk_add_f32 v[206:207], v[206:207], v[222:223] neg_lo:[0,1] neg_hi:[0,1]
	v_pk_mul_f32 v[192:193], v[200:201], s[96:97] op_sel_hi:[1,0]
	v_pk_mul_f32 v[194:195], v[202:203], s[96:97] op_sel_hi:[1,0]
	v_pk_mul_f32 v[196:197], v[204:205], s[96:97] op_sel_hi:[1,0]
	v_pk_mul_f32 v[198:199], v[206:207], s[96:97] op_sel_hi:[1,0]
	v_cvt_pk_bf16_f32 v208, v184, v185
	v_cvt_pk_bf16_f32 v209, v186, v187
	v_cvt_pk_bf16_f32 v210, v188, v189
	v_cvt_pk_bf16_f32 v211, v190, v191
	v_cvt_pk_bf16_f32 v212, v192, v193
	v_cvt_pk_bf16_f32 v213, v194, v195
	v_cvt_pk_bf16_f32 v214, v196, v197
	v_cvt_pk_bf16_f32 v215, v198, v199
	v_mov_b32_dpp v216, v208 quad_perm:[1,0,3,2] row_mask:0xf bank_mask:0xf bound_ctrl:1
	v_mov_b32_dpp v217, v209 quad_perm:[1,0,3,2] row_mask:0xf bank_mask:0xf bound_ctrl:1
	v_mov_b32_dpp v218, v210 quad_perm:[1,0,3,2] row_mask:0xf bank_mask:0xf bound_ctrl:1
	v_mov_b32_dpp v219, v211 quad_perm:[1,0,3,2] row_mask:0xf bank_mask:0xf bound_ctrl:1
	v_mov_b32_dpp v220, v212 quad_perm:[1,0,3,2] row_mask:0xf bank_mask:0xf bound_ctrl:1
	v_mov_b32_dpp v221, v213 quad_perm:[1,0,3,2] row_mask:0xf bank_mask:0xf bound_ctrl:1
	v_mov_b32_dpp v222, v214 quad_perm:[1,0,3,2] row_mask:0xf bank_mask:0xf bound_ctrl:1
	v_mov_b32_dpp v223, v215 quad_perm:[1,0,3,2] row_mask:0xf bank_mask:0xf bound_ctrl:1
	v_perm_b32 v208, v216, v208, v164
	v_perm_b32 v209, v217, v209, v164
	v_perm_b32 v210, v218, v210, v164
	v_perm_b32 v211, v219, v211, v164
	v_perm_b32 v212, v220, v212, v164
	v_perm_b32 v213, v221, v213, v164
	v_perm_b32 v214, v222, v214, v164
	v_perm_b32 v215, v223, v215, v164
	global_store_dword v167, v208, s[8:9]
	global_store_dword v167, v209, s[8:9] offset:1024
	global_store_dword v167, v210, s[8:9] offset:32
	global_store_dword v167, v211, s[8:9] offset:1056
	global_store_dword v167, v212, s[8:9] offset:256
	global_store_dword v167, v213, s[8:9] offset:1280
	global_store_dword v167, v214, s[8:9] offset:288
	global_store_dword v167, v215, s[8:9] offset:1312
	ds_read_b64 v[180:181], v160 offset:60448
	v_add_u32_e32 v167, 0x16000, v163
	s_waitcnt lgkmcnt(0)
	v_mfma_f32_16x16x16_bf16 v[184:187], v[180:181], v[168:169], 0
	v_mfma_f32_16x16x16_bf16 v[188:191], v[180:181], v[170:171], 0
	v_mfma_f32_16x16x16_bf16 v[192:195], v[180:181], v[172:173], 0
	v_mfma_f32_16x16x16_bf16 v[196:199], v[180:181], v[174:175], 0
	s_nop 7
	s_nop 1
	v_pk_add_f32 v[184:185], v[184:185], v[176:177] op_sel_hi:[1,0]
	v_pk_add_f32 v[186:187], v[186:187], v[176:177] op_sel_hi:[1,0]
	v_pk_add_f32 v[188:189], v[188:189], v[176:177] op_sel:[0,1] op_sel_hi:[1,1]
	v_pk_add_f32 v[190:191], v[190:191], v[176:177] op_sel:[0,1] op_sel_hi:[1,1]
	v_min_f32_e32 v200, 0, v184
	v_min_f32_e32 v201, 0, v185
	v_min_f32_e32 v202, 0, v186
	v_min_f32_e32 v203, 0, v187
	v_min_f32_e32 v204, 0, v188
	v_min_f32_e32 v205, 0, v189
	v_min_f32_e32 v206, 0, v190
	v_min_f32_e32 v207, 0, v191
	v_mul_f32_e64 v208, |v184|, s93
	v_mul_f32_e64 v209, |v185|, s93
	v_mul_f32_e64 v210, |v186|, s93
	v_mul_f32_e64 v211, |v187|, s93
	v_mul_f32_e64 v212, |v188|, s93
	v_mul_f32_e64 v213, |v189|, s93
	v_mul_f32_e64 v214, |v190|, s93
	v_mul_f32_e64 v215, |v191|, s93
	v_exp_f32_e32 v208, v208
	v_exp_f32_e32 v209, v209
	v_exp_f32_e32 v210, v210
	v_exp_f32_e32 v211, v211
	v_exp_f32_e32 v212, v212
	v_exp_f32_e32 v213, v213
	v_exp_f32_e32 v214, v214
	v_exp_f32_e32 v215, v215
	v_pk_add_f32 v[208:209], v[208:209], 1.0 op_sel_hi:[1,0]
	v_pk_add_f32 v[210:211], v[210:211], 1.0 op_sel_hi:[1,0]
	v_pk_add_f32 v[212:213], v[212:213], 1.0 op_sel_hi:[1,0]
	v_pk_add_f32 v[214:215], v[214:215], 1.0 op_sel_hi:[1,0]
	v_log_f32_e32 v208, v208
	v_log_f32_e32 v209, v209
	v_log_f32_e32 v210, v210
	v_log_f32_e32 v211, v211
	v_log_f32_e32 v212, v212
	v_log_f32_e32 v213, v213
	v_log_f32_e32 v214, v214
	v_log_f32_e32 v215, v215
	v_pk_mul_f32 v[216:217], v[208:209], s[94:95] op_sel:[0,1] op_sel_hi:[1,1]
	v_pk_mul_f32 v[218:219], v[210:211], s[94:95] op_sel:[0,1] op_sel_hi:[1,1]
	v_pk_mul_f32 v[220:221], v[212:213], s[94:95] op_sel:[0,1] op_sel_hi:[1,1]
	v_pk_mul_f32 v[222:223], v[214:215], s[94:95] op_sel:[0,1] op_sel_hi:[1,1]
	v_pk_fma_f32 v[216:217], v[208:209], s[94:95], v[216:217] op_sel:[0,1,0] op_sel_hi:[1,1,1] neg_lo:[0,0,1] neg_hi:[0,0,1]
	v_pk_fma_f32 v[218:219], v[210:211], s[94:95], v[218:219] op_sel:[0,1,0] op_sel_hi:[1,1,1] neg_lo:[0,0,1] neg_hi:[0,0,1]
;   __device__ __forceinline__ void operator()(f32x4 (&acc)[2][2][4][2], int brow, int bcol, int wr, int wc, int fr, int fq) const {
;     ...
;             s16x4 af = *(const s16x4*)(glr + (rl + fr) * 32 + dir * 16 + fq * 4);
;             int row0 = brow + rl + fq * 4;
; #pragma unroll
;             for (int bj = 0; bj < 2; ++bj)
; #pragma unroll
;               for (int n = 0; n < 2; ++n) {
;                 f32x4 z4 = {0.f, 0.f, 0.f, 0.f};
;                 z4 = __builtin_amdgcn_mfma_f32_16x16x16bf16_1k(af, bfr[bj][n], z4, 0, 0, 0);
;                 int c = bj * 128 + wc * 32 + n * 16 + fr;
;                 float bb = bias[c];
;                 float ls[4];
; #pragma unroll
;                 for (int j = 0; j < 4; ++j) {
;                   float z = z4[j] + bb;
;                   ls[j] = (fminf(z, 0.f) - __logf(1.f + __expf(-fabsf(z)))) * (1.f / 16.f);
;                 }
;                 store_rm4(dst, 256, row0, c, ls[0], ls[1], ls[2], ls[3], fr & 1);
	v_pk_fma_f32 v[220:221], v[212:213], s[94:95], v[220:221] op_sel:[0,1,0] op_sel_hi:[1,1,1] neg_lo:[0,0,1] neg_hi:[0,0,1]
	v_pk_fma_f32 v[222:223], v[214:215], s[94:95], v[222:223] op_sel:[0,1,0] op_sel_hi:[1,1,1] neg_lo:[0,0,1] neg_hi:[0,0,1]
	v_pk_fma_f32 v[216:217], v[208:209], s[94:95], v[216:217] op_sel_hi:[1,0,1]
	v_pk_fma_f32 v[218:219], v[210:211], s[94:95], v[218:219] op_sel_hi:[1,0,1]
	v_pk_fma_f32 v[220:221], v[212:213], s[94:95], v[220:221] op_sel_hi:[1,0,1]
	v_pk_fma_f32 v[222:223], v[214:215], s[94:95], v[222:223] op_sel_hi:[1,0,1]
	v_pk_fma_f32 v[216:217], v[208:209], s[94:95], v[216:217] op_sel:[0,1,0] op_sel_hi:[1,1,1]
	v_pk_fma_f32 v[218:219], v[210:211], s[94:95], v[218:219] op_sel:[0,1,0] op_sel_hi:[1,1,1]
	v_pk_fma_f32 v[220:221], v[212:213], s[94:95], v[220:221] op_sel:[0,1,0] op_sel_hi:[1,1,1]
	v_pk_fma_f32 v[222:223], v[214:215], s[94:95], v[222:223] op_sel:[0,1,0] op_sel_hi:[1,1,1]
	v_pk_add_f32 v[200:201], v[200:201], v[216:217] neg_lo:[0,1] neg_hi:[0,1]
	v_pk_add_f32 v[202:203], v[202:203], v[218:219] neg_lo:[0,1] neg_hi:[0,1]
	v_pk_add_f32 v[204:205], v[204:205], v[220:221] neg_lo:[0,1] neg_hi:[0,1]
	v_pk_add_f32 v[206:207], v[206:207], v[222:223] neg_lo:[0,1] neg_hi:[0,1]
	v_pk_mul_f32 v[184:185], v[200:201], s[96:97] op_sel_hi:[1,0]
	v_pk_mul_f32 v[186:187], v[202:203], s[96:97] op_sel_hi:[1,0]
	v_pk_mul_f32 v[188:189], v[204:205], s[96:97] op_sel_hi:[1,0]
	v_pk_mul_f32 v[190:191], v[206:207], s[96:97] op_sel_hi:[1,0]
	v_pk_add_f32 v[192:193], v[192:193], v[178:179] op_sel_hi:[1,0]
	v_pk_add_f32 v[194:195], v[194:195], v[178:179] op_sel_hi:[1,0]
	v_pk_add_f32 v[196:197], v[196:197], v[178:179] op_sel:[0,1] op_sel_hi:[1,1]
	v_pk_add_f32 v[198:199], v[198:199], v[178:179] op_sel:[0,1] op_sel_hi:[1,1]
	v_min_f32_e32 v200, 0, v192
	v_min_f32_e32 v201, 0, v193
	v_min_f32_e32 v202, 0, v194
	v_min_f32_e32 v203, 0, v195
	v_min_f32_e32 v204, 0, v196
	v_min_f32_e32 v205, 0, v197
	v_min_f32_e32 v206, 0, v198
	v_min_f32_e32 v207, 0, v199
	v_mul_f32_e64 v208, |v192|, s93
	v_mul_f32_e64 v209, |v193|, s93
	v_mul_f32_e64 v210, |v194|, s93
	v_mul_f32_e64 v211, |v195|, s93
	v_mul_f32_e64 v212, |v196|, s93
	v_mul_f32_e64 v213, |v197|, s93
	v_mul_f32_e64 v214, |v198|, s93
	v_mul_f32_e64 v215, |v199|, s93
	v_exp_f32_e32 v208, v208
	v_exp_f32_e32 v209, v209
	v_exp_f32_e32 v210, v210
	v_exp_f32_e32 v211, v211
	v_exp_f32_e32 v212, v212
	v_exp_f32_e32 v213, v213
	v_exp_f32_e32 v214, v214
	v_exp_f32_e32 v215, v215
	v_pk_add_f32 v[208:209], v[208:209], 1.0 op_sel_hi:[1,0]
	v_pk_add_f32 v[210:211], v[210:211], 1.0 op_sel_hi:[1,0]
	v_pk_add_f32 v[212:213], v[212:213], 1.0 op_sel_hi:[1,0]
	v_pk_add_f32 v[214:215], v[214:215], 1.0 op_sel_hi:[1,0]
	v_log_f32_e32 v208, v208
	v_log_f32_e32 v209, v209
	v_log_f32_e32 v210, v210
	v_log_f32_e32 v211, v211
	v_log_f32_e32 v212, v212
	v_log_f32_e32 v213, v213
	v_log_f32_e32 v214, v214
	v_log_f32_e32 v215, v215
	v_pk_mul_f32 v[216:217], v[208:209], s[94:95] op_sel:[0,1] op_sel_hi:[1,1]
	v_pk_mul_f32 v[218:219], v[210:211], s[94:95] op_sel:[0,1] op_sel_hi:[1,1]
	v_pk_mul_f32 v[220:221], v[212:213], s[94:95] op_sel:[0,1] op_sel_hi:[1,1]
	v_pk_mul_f32 v[222:223], v[214:215], s[94:95] op_sel:[0,1] op_sel_hi:[1,1]
	v_pk_fma_f32 v[216:217], v[208:209], s[94:95], v[216:217] op_sel:[0,1,0] op_sel_hi:[1,1,1] neg_lo:[0,0,1] neg_hi:[0,0,1]
	v_pk_fma_f32 v[218:219], v[210:211], s[94:95], v[218:219] op_sel:[0,1,0] op_sel_hi:[1,1,1] neg_lo:[0,0,1] neg_hi:[0,0,1]
	v_pk_fma_f32 v[220:221], v[212:213], s[94:95], v[220:221] op_sel:[0,1,0] op_sel_hi:[1,1,1] neg_lo:[0,0,1] neg_hi:[0,0,1]
	v_pk_fma_f32 v[222:223], v[214:215], s[94:95], v[222:223] op_sel:[0,1,0] op_sel_hi:[1,1,1] neg_lo:[0,0,1] neg_hi:[0,0,1]
	v_pk_fma_f32 v[216:217], v[208:209], s[94:95], v[216:217] op_sel_hi:[1,0,1]
	v_pk_fma_f32 v[218:219], v[210:211], s[94:95], v[218:219] op_sel_hi:[1,0,1]
	v_pk_fma_f32 v[220:221], v[212:213], s[94:95], v[220:221] op_sel_hi:[1,0,1]
	v_pk_fma_f32 v[222:223], v[214:215], s[94:95], v[222:223] op_sel_hi:[1,0,1]
	v_pk_fma_f32 v[216:217], v[208:209], s[94:95], v[216:217] op_sel:[0,1,0] op_sel_hi:[1,1,1]
	v_pk_fma_f32 v[218:219], v[210:211], s[94:95], v[218:219] op_sel:[0,1,0] op_sel_hi:[1,1,1]
	v_pk_fma_f32 v[220:221], v[212:213], s[94:95], v[220:221] op_sel:[0,1,0] op_sel_hi:[1,1,1]
	v_pk_fma_f32 v[222:223], v[214:215], s[94:95], v[222:223] op_sel:[0,1,0] op_sel_hi:[1,1,1]
	v_pk_add_f32 v[200:201], v[200:201], v[216:217] neg_lo:[0,1] neg_hi:[0,1]
	v_pk_add_f32 v[202:203], v[202:203], v[218:219] neg_lo:[0,1] neg_hi:[0,1]
	v_pk_add_f32 v[204:205], v[204:205], v[220:221] neg_lo:[0,1] neg_hi:[0,1]
	v_pk_add_f32 v[206:207], v[206:207], v[222:223] neg_lo:[0,1] neg_hi:[0,1]
	v_pk_mul_f32 v[192:193], v[200:201], s[96:97] op_sel_hi:[1,0]
	v_pk_mul_f32 v[194:195], v[202:203], s[96:97] op_sel_hi:[1,0]
	v_pk_mul_f32 v[196:197], v[204:205], s[96:97] op_sel_hi:[1,0]
	v_pk_mul_f32 v[198:199], v[206:207], s[96:97] op_sel_hi:[1,0]
	v_cvt_pk_bf16_f32 v208, v184, v185
	v_cvt_pk_bf16_f32 v209, v186, v187
	v_cvt_pk_bf16_f32 v210, v188, v189
	v_cvt_pk_bf16_f32 v211, v190, v191
	v_cvt_pk_bf16_f32 v212, v192, v193
	v_cvt_pk_bf16_f32 v213, v194, v195
	v_cvt_pk_bf16_f32 v214, v196, v197
	v_cvt_pk_bf16_f32 v215, v198, v199
	v_mov_b32_dpp v216, v208 quad_perm:[1,0,3,2] row_mask:0xf bank_mask:0xf bound_ctrl:1
	v_mov_b32_dpp v217, v209 quad_perm:[1,0,3,2] row_mask:0xf bank_mask:0xf bound_ctrl:1
	v_mov_b32_dpp v218, v210 quad_perm:[1,0,3,2] row_mask:0xf bank_mask:0xf bound_ctrl:1
	v_mov_b32_dpp v219, v211 quad_perm:[1,0,3,2] row_mask:0xf bank_mask:0xf bound_ctrl:1
	v_mov_b32_dpp v220, v212 quad_perm:[1,0,3,2] row_mask:0xf bank_mask:0xf bound_ctrl:1
	v_mov_b32_dpp v221, v213 quad_perm:[1,0,3,2] row_mask:0xf bank_mask:0xf bound_ctrl:1
	v_mov_b32_dpp v222, v214 quad_perm:[1,0,3,2] row_mask:0xf bank_mask:0xf bound_ctrl:1
	v_mov_b32_dpp v223, v215 quad_perm:[1,0,3,2] row_mask:0xf bank_mask:0xf bound_ctrl:1
	v_perm_b32 v208, v216, v208, v164
	v_perm_b32 v209, v217, v209, v164
	v_perm_b32 v210, v218, v210, v164
	v_perm_b32 v211, v219, v211, v164
	v_perm_b32 v212, v220, v212, v164
	v_perm_b32 v213, v221, v213, v164
	v_perm_b32 v214, v222, v214, v164
	v_perm_b32 v215, v223, v215, v164
	global_store_dword v167, v208, s[8:9]
	global_store_dword v167, v209, s[8:9] offset:1024
	global_store_dword v167, v210, s[8:9] offset:32
	global_store_dword v167, v211, s[8:9] offset:1056
	global_store_dword v167, v212, s[8:9] offset:256
	global_store_dword v167, v213, s[8:9] offset:1280
	global_store_dword v167, v214, s[8:9] offset:288
	global_store_dword v167, v215, s[8:9] offset:1312
	s_mov_b32 s94, 0x800000
	s_mov_b32 s96, 0x7f800000
	s_mov_b64 s[0:1], 0
